# MFMA order inside every 32-MFMA K-loop segment: diagonal (m,n) order so that both source fragments change at every MFMA; per-accumulator order unchanged
# speedup vs baseline: 1.0086x; 1.0086x over previous
; #define PG8_STAGE(bufoff, gbase, voff) do { _Pragma("unroll") for (int _i = 0; _i < 2; ++_i) \
;         __builtin_amdgcn_global_load_lds((const unsigned*)((const char*)(gbase) + (voff)[_i]), (PG8_LAS unsigned*)(lds + (bufoff) + ldsw + _i * 8192), 16, 0, 0); } while (0)
; #define PG8_LDA(dst, b, h) do { _Pragma("unroll") for (int m = 0; m < 4; ++m) _Pragma("unroll") for (int k = 0; k < 2; ++k) dst[m][k] = *(const PG8_LAS bf16x8*)(lds + PG8_SA(b, h) + aoff + m * 2048 + k * 1024); } while (0)
; #define PG8_LDB(dst, b, h) do { _Pragma("unroll") for (int n = 0; n < 2; ++n) _Pragma("unroll") for (int k = 0; k < 2; ++k) dst[n][k] = *(const PG8_LAS bf16x8*)(lds + PG8_SB(b, h) + boff + n * 2048 + k * 1024); } while (0)
; #define PG8_MMA(ai, bj, At, Bt) do { __builtin_amdgcn_s_setprio(1); _Pragma("unroll") for (int m = 0; m < 4; ++m) _Pragma("unroll") for (int n = 0; n < 2; ++n) _Pragma("unroll") for (int k = 0; k < 2; ++k) \
;         acc[ai][bj][m][n] = __builtin_amdgcn_mfma_f32_16x16x32_bf16(Bt[n][k], At[m][k], acc[ai][bj][m][n], 0, 0, 0); __builtin_amdgcn_s_setprio(0); } while (0)
; #define PG8_WAIT_V(n) asm volatile("s_waitcnt vmcnt(" #n ")" ::: "memory")
; #define PG8_WAIT_L(n) asm volatile("s_waitcnt lgkmcnt(" #n ")" ::: "memory")
; template <class Epi, class Sched, bool ALIGN_EPI = false, bool SP2 = false>
; __device__ __forceinline__ void gemm_phase(PG8_LAS unsigned char* lds, const Gemm g, const Sched& S, const Epi& E) {
;     ...
;             const bool last = (t == nt - 2);
;             const char* a1 = cA + (size_t)(t + 1) * kstep;
;             const char* a2 = last ? nA : cA + (size_t)(t + 2) * kstep; const char* b2 = last ? nB : cB + (size_t)(t + 2) * kstep;
;             const char* a3 = a2 + kstep; const char* b3 = b2 + kstep;
;             if (last && has_next) S.a_ready(nxt);
;             if constexpr (SP2) {
;             PG8_LDB(B0, 0, 0); PG8_LDB(B1, 0, 1); PG8_SCHED; PG8_LDA(At, 0, 0); PG8_STAGE(PG8_SA(1, 1), a1 + hstep, voffA);
;             PG8_WAIT_V(8); PG8_WAIT_L(0); PG8_BAR; PG8_MMA(0, 0, At, B0); PG8_MMA(0, 1, At, B1); PG8_BAR; PG8_SCHED;
;             PG8_LDA(At, 0, 1); PG8_STAGE(PG8_SB(0, 0), b2, voffB); PG8_STAGE(PG8_SB(0, 1), b2 + hstep, voffB); PG8_STAGE(PG8_SA(0, 0), a2, voffA);
;             PG8_WAIT_V(8); PG8_WAIT_L(0); PG8_BAR; PG8_MMA(1, 0, At, B0); PG8_MMA(1, 1, At, B1); PG8_BAR; PG8_SCHED;
.Labo_peel:
	ds_read_b128 v[68:71], v254
	ds_read_b128 v[72:75], v254 offset:1024
	ds_read_b128 v[76:79], v254 offset:2048
	ds_read_b128 v[80:83], v254 offset:3072
	ds_read_b128 v[174:177], v254 offset:16384
	ds_read_b128 v[182:185], v254 offset:17408
	ds_read_b128 v[186:189], v254 offset:18432
	ds_read_b128 v[210:213], v254 offset:19456
	s_add_u32 s2, s0, 0xfffc0080
	s_addc_u32 s3, s1, -1
	s_cmp_eq_u32 s56, 12
	s_cselect_b32 s5, s27, s3
	s_cselect_b32 s4, s52, s2
	s_cselect_b32 s3, s25, s55
	s_cselect_b32 s2, s53, s54
	s_add_i32 m0, s29, 0xc000
	ds_read_b128 v[214:217], v179
	ds_read_b128 v[218:221], v179 offset:1024
	ds_read_b128 v[222:225], v179 offset:2048
	ds_read_b128 v[226:229], v179 offset:3072
	ds_read_b128 v[230:233], v179 offset:4096
	ds_read_b128 v[234:237], v179 offset:5120
	ds_read_b128 v[238:241], v179 offset:6144
	ds_read_b128 v[242:245], v179 offset:7168
	global_load_lds_dwordx4 v170, s[0:1]
	s_add_i32 m0, s29, 0xe000
	s_nop 0
	global_load_lds_dwordx4 v172, s[0:1]
	s_waitcnt vmcnt(8)
	s_waitcnt lgkmcnt(0)
	s_barrier
	s_setprio 1
	v_mfma_f32_16x16x32_bf16 v[140:143], v[68:71], v[214:217], 0
	v_mfma_f32_16x16x32_bf16 v[120:123], v[76:79], v[222:225], 0
	v_mfma_f32_16x16x32_bf16 v[108:111], v[68:71], v[230:233], 0
	v_mfma_f32_16x16x32_bf16 v[88:91], v[76:79], v[238:241], 0
	v_mfma_f32_16x16x32_bf16 v[136:139], v[76:79], v[214:217], 0
	v_mfma_f32_16x16x32_bf16 v[124:127], v[68:71], v[222:225], 0
	v_mfma_f32_16x16x32_bf16 v[104:107], v[76:79], v[230:233], 0
	v_mfma_f32_16x16x32_bf16 v[92:95], v[68:71], v[238:241], 0
	v_mfma_f32_16x16x32_bf16 v[140:143], v[72:75], v[218:221], v[140:143]
	v_mfma_f32_16x16x32_bf16 v[120:123], v[80:83], v[226:229], v[120:123]
	v_mfma_f32_16x16x32_bf16 v[108:111], v[72:75], v[234:237], v[108:111]
	v_mfma_f32_16x16x32_bf16 v[88:91], v[80:83], v[242:245], v[88:91]
	v_mfma_f32_16x16x32_bf16 v[136:139], v[80:83], v[218:221], v[136:139]
	v_mfma_f32_16x16x32_bf16 v[124:127], v[72:75], v[226:229], v[124:127]
	v_mfma_f32_16x16x32_bf16 v[104:107], v[80:83], v[234:237], v[104:107]
	v_mfma_f32_16x16x32_bf16 v[92:95], v[72:75], v[242:245], v[92:95]
	v_mfma_f32_16x16x32_bf16 v[132:135], v[174:177], v[214:217], 0
	v_mfma_f32_16x16x32_bf16 v[112:115], v[186:189], v[222:225], 0
	v_mfma_f32_16x16x32_bf16 v[100:103], v[174:177], v[230:233], 0
	v_mfma_f32_16x16x32_bf16 v[64:67], v[186:189], v[238:241], 0
	v_mfma_f32_16x16x32_bf16 v[128:131], v[186:189], v[214:217], 0
	v_mfma_f32_16x16x32_bf16 v[116:119], v[174:177], v[222:225], 0
	v_mfma_f32_16x16x32_bf16 v[96:99], v[186:189], v[230:233], 0
	v_mfma_f32_16x16x32_bf16 v[84:87], v[174:177], v[238:241], 0
	v_mfma_f32_16x16x32_bf16 v[132:135], v[182:185], v[218:221], v[132:135]
	v_mfma_f32_16x16x32_bf16 v[112:115], v[210:213], v[226:229], v[112:115]
	v_mfma_f32_16x16x32_bf16 v[100:103], v[182:185], v[234:237], v[100:103]
	v_mfma_f32_16x16x32_bf16 v[64:67], v[210:213], v[242:245], v[64:67]
	v_mfma_f32_16x16x32_bf16 v[128:131], v[210:213], v[218:221], v[128:131]
	v_mfma_f32_16x16x32_bf16 v[116:119], v[182:185], v[226:229], v[116:119]
	v_mfma_f32_16x16x32_bf16 v[96:99], v[210:213], v[234:237], v[96:99]
	v_mfma_f32_16x16x32_bf16 v[84:87], v[182:185], v[242:245], v[84:87]
	s_setprio 0
	s_barrier
	s_mov_b32 m0, s30
	s_add_u32 s58, s2, 0x40000
	s_addc_u32 s59, s3, 0
	ds_read_b128 v[214:217], v179 offset:16384
	ds_read_b128 v[218:221], v179 offset:17408
	ds_read_b128 v[222:225], v179 offset:18432
	ds_read_b128 v[226:229], v179 offset:19456
	ds_read_b128 v[230:233], v179 offset:20480
	ds_read_b128 v[234:237], v179 offset:21504
	ds_read_b128 v[238:241], v179 offset:22528
	ds_read_b128 v[242:245], v179 offset:23552
	global_load_lds_dwordx4 v166, s[2:3]
	s_mov_b32 m0, s31
	s_nop 0
	global_load_lds_dwordx4 v162, s[2:3]
	s_mov_b32 m0, s33
	s_nop 0
	global_load_lds_dwordx4 v166, s[58:59]
	s_mov_b32 m0, s34
	s_nop 0
	global_load_lds_dwordx4 v162, s[58:59]
	s_mov_b32 m0, s29
	s_nop 0
	global_load_lds_dwordx4 v168, s[4:5]
	s_mov_b32 m0, s35
	s_nop 0
	global_load_lds_dwordx4 v164, s[4:5]
	s_waitcnt vmcnt(8)
	s_waitcnt lgkmcnt(0)
	s_barrier
	s_setprio 1
	v_mfma_f32_16x16x32_bf16 v[60:63], v[68:71], v[214:217], 0
	v_mfma_f32_16x16x32_bf16 v[40:43], v[76:79], v[222:225], 0
	v_mfma_f32_16x16x32_bf16 v[28:31], v[68:71], v[230:233], 0
	v_mfma_f32_16x16x32_bf16 v[8:11], v[76:79], v[238:241], 0
	v_mfma_f32_16x16x32_bf16 v[56:59], v[76:79], v[214:217], 0
	v_mfma_f32_16x16x32_bf16 v[44:47], v[68:71], v[222:225], 0
	v_mfma_f32_16x16x32_bf16 v[24:27], v[76:79], v[230:233], 0
	v_mfma_f32_16x16x32_bf16 v[12:15], v[68:71], v[238:241], 0
	v_mfma_f32_16x16x32_bf16 v[60:63], v[72:75], v[218:221], v[60:63]
	v_mfma_f32_16x16x32_bf16 v[40:43], v[80:83], v[226:229], v[40:43]
	v_mfma_f32_16x16x32_bf16 v[28:31], v[72:75], v[234:237], v[28:31]
	v_mfma_f32_16x16x32_bf16 v[8:11], v[80:83], v[242:245], v[8:11]
	v_mfma_f32_16x16x32_bf16 v[56:59], v[80:83], v[218:221], v[56:59]
	v_mfma_f32_16x16x32_bf16 v[44:47], v[72:75], v[226:229], v[44:47]
	v_mfma_f32_16x16x32_bf16 v[24:27], v[80:83], v[234:237], v[24:27]
	v_mfma_f32_16x16x32_bf16 v[12:15], v[72:75], v[242:245], v[12:15]
	v_mfma_f32_16x16x32_bf16 v[52:55], v[174:177], v[214:217], 0
	v_mfma_f32_16x16x32_bf16 v[32:35], v[186:189], v[222:225], 0
	v_mfma_f32_16x16x32_bf16 v[20:23], v[174:177], v[230:233], 0
	v_mfma_f32_16x16x32_bf16 v[0:3], v[186:189], v[238:241], 0
	v_mfma_f32_16x16x32_bf16 v[48:51], v[186:189], v[214:217], 0
	v_mfma_f32_16x16x32_bf16 v[36:39], v[174:177], v[222:225], 0
	v_mfma_f32_16x16x32_bf16 v[16:19], v[186:189], v[230:233], 0
	v_mfma_f32_16x16x32_bf16 v[4:7], v[174:177], v[238:241], 0
	v_mfma_f32_16x16x32_bf16 v[52:55], v[182:185], v[218:221], v[52:55]
	v_mfma_f32_16x16x32_bf16 v[32:35], v[210:213], v[226:229], v[32:35]
	v_mfma_f32_16x16x32_bf16 v[20:23], v[182:185], v[234:237], v[20:23]
	v_mfma_f32_16x16x32_bf16 v[0:3], v[210:213], v[242:245], v[0:3]
	v_mfma_f32_16x16x32_bf16 v[48:51], v[210:213], v[218:221], v[48:51]
	v_mfma_f32_16x16x32_bf16 v[36:39], v[182:185], v[226:229], v[36:39]
	v_mfma_f32_16x16x32_bf16 v[16:19], v[210:213], v[234:237], v[16:19]
	v_mfma_f32_16x16x32_bf16 v[4:7], v[182:185], v[242:245], v[4:7]
	s_setprio 0
	s_barrier
; #define PG8_STAGE(bufoff, gbase, voff) do { _Pragma("unroll") for (int _i = 0; _i < 2; ++_i) \
;         __builtin_amdgcn_global_load_lds((const unsigned*)((const char*)(gbase) + (voff)[_i]), (PG8_LAS unsigned*)(lds + (bufoff) + ldsw + _i * 8192), 16, 0, 0); } while (0)
; #define PG8_LDA(dst, b, h) do { _Pragma("unroll") for (int m = 0; m < 4; ++m) _Pragma("unroll") for (int k = 0; k < 2; ++k) dst[m][k] = *(const PG8_LAS bf16x8*)(lds + PG8_SA(b, h) + aoff + m * 2048 + k * 1024); } while (0)
; #define PG8_LDB(dst, b, h) do { _Pragma("unroll") for (int n = 0; n < 2; ++n) _Pragma("unroll") for (int k = 0; k < 2; ++k) dst[n][k] = *(const PG8_LAS bf16x8*)(lds + PG8_SB(b, h) + boff + n * 2048 + k * 1024); } while (0)
; #define PG8_MMA(ai, bj, At, Bt) do { __builtin_amdgcn_s_setprio(1); _Pragma("unroll") for (int m = 0; m < 4; ++m) _Pragma("unroll") for (int n = 0; n < 2; ++n) _Pragma("unroll") for (int k = 0; k < 2; ++k) \
;         acc[ai][bj][m][n] = __builtin_amdgcn_mfma_f32_16x16x32_bf16(Bt[n][k], At[m][k], acc[ai][bj][m][n], 0, 0, 0); __builtin_amdgcn_s_setprio(0); } while (0)
; #define PG8_WAIT_V(n) asm volatile("s_waitcnt vmcnt(" #n ")" ::: "memory")
; #define PG8_WAIT_L(n) asm volatile("s_waitcnt lgkmcnt(" #n ")" ::: "memory")
; #define PG8_BAR __builtin_amdgcn_s_barrier()
; #define PG8_SCHED __builtin_amdgcn_sched_barrier(0)
; template <class Epi, class Sched, bool ALIGN_EPI = false, bool SP2 = false>
; __device__ __forceinline__ void gemm_phase(PG8_LAS unsigned char* lds, const Gemm g, const Sched& S, const Epi& E) {
;     ...
;             PG8_LDB(B0, 1, 0); PG8_LDB(B1, 1, 1); PG8_SCHED; PG8_LDA(At, 1, 0); PG8_STAGE(PG8_SA(0, 1), a2 + hstep, voffA);
;             PG8_WAIT_V(8); PG8_WAIT_L(0); PG8_BAR; PG8_MMA(0, 0, At, B0); PG8_MMA(0, 1, At, B1); PG8_BAR; PG8_SCHED;
;             PG8_LDA(At, 1, 1); PG8_STAGE(PG8_SB(1, 0), b3, voffB); PG8_STAGE(PG8_SB(1, 1), b3 + hstep, voffB); PG8_STAGE(PG8_SA(1, 0), a3, voffA);
;             PG8_WAIT_V(8); PG8_WAIT_L(0); PG8_BAR; PG8_MMA(1, 0, At, B0); PG8_MMA(1, 1, At, B1); PG8_BAR; PG8_SCHED;
	ds_read_b128 v[68:71], v254 offset:32768
	ds_read_b128 v[72:75], v254 offset:33792
	ds_read_b128 v[76:79], v254 offset:34816
	ds_read_b128 v[80:83], v254 offset:35840
	ds_read_b128 v[174:177], v254 offset:49152
	ds_read_b128 v[182:185], v254 offset:50176
	ds_read_b128 v[186:189], v254 offset:51200
	ds_read_b128 v[210:213], v254 offset:52224
	s_add_u32 s4, s4, 0x40000
	s_addc_u32 s5, s5, 0
	s_mov_b32 m0, s40
	ds_read_b128 v[214:217], v179 offset:32768
	ds_read_b128 v[218:221], v179 offset:33792
	ds_read_b128 v[222:225], v179 offset:34816
	ds_read_b128 v[226:229], v179 offset:35840
	ds_read_b128 v[230:233], v179 offset:36864
	ds_read_b128 v[234:237], v179 offset:37888
	ds_read_b128 v[238:241], v179 offset:38912
	ds_read_b128 v[242:245], v179 offset:39936
	global_load_lds_dwordx4 v168, s[4:5]
	s_mov_b32 m0, s41
	s_nop 0
	global_load_lds_dwordx4 v164, s[4:5]
	s_waitcnt vmcnt(8)
	s_waitcnt lgkmcnt(0)
	s_barrier
	s_setprio 1
	v_mfma_f32_16x16x32_bf16 v[140:143], v[68:71], v[214:217], v[140:143]
	v_mfma_f32_16x16x32_bf16 v[120:123], v[76:79], v[222:225], v[120:123]
	v_mfma_f32_16x16x32_bf16 v[108:111], v[68:71], v[230:233], v[108:111]
	v_mfma_f32_16x16x32_bf16 v[88:91], v[76:79], v[238:241], v[88:91]
	v_mfma_f32_16x16x32_bf16 v[136:139], v[76:79], v[214:217], v[136:139]
	v_mfma_f32_16x16x32_bf16 v[124:127], v[68:71], v[222:225], v[124:127]
	v_mfma_f32_16x16x32_bf16 v[104:107], v[76:79], v[230:233], v[104:107]
	v_mfma_f32_16x16x32_bf16 v[92:95], v[68:71], v[238:241], v[92:95]
	v_mfma_f32_16x16x32_bf16 v[140:143], v[72:75], v[218:221], v[140:143]
	v_mfma_f32_16x16x32_bf16 v[120:123], v[80:83], v[226:229], v[120:123]
	v_mfma_f32_16x16x32_bf16 v[108:111], v[72:75], v[234:237], v[108:111]
	v_mfma_f32_16x16x32_bf16 v[88:91], v[80:83], v[242:245], v[88:91]
	v_mfma_f32_16x16x32_bf16 v[136:139], v[80:83], v[218:221], v[136:139]
	v_mfma_f32_16x16x32_bf16 v[124:127], v[72:75], v[226:229], v[124:127]
	v_mfma_f32_16x16x32_bf16 v[104:107], v[80:83], v[234:237], v[104:107]
	v_mfma_f32_16x16x32_bf16 v[92:95], v[72:75], v[242:245], v[92:95]
	v_mfma_f32_16x16x32_bf16 v[132:135], v[174:177], v[214:217], v[132:135]
	v_mfma_f32_16x16x32_bf16 v[112:115], v[186:189], v[222:225], v[112:115]
	v_mfma_f32_16x16x32_bf16 v[100:103], v[174:177], v[230:233], v[100:103]
	v_mfma_f32_16x16x32_bf16 v[64:67], v[186:189], v[238:241], v[64:67]
	v_mfma_f32_16x16x32_bf16 v[128:131], v[186:189], v[214:217], v[128:131]
	v_mfma_f32_16x16x32_bf16 v[116:119], v[174:177], v[222:225], v[116:119]
	v_mfma_f32_16x16x32_bf16 v[96:99], v[186:189], v[230:233], v[96:99]
	v_mfma_f32_16x16x32_bf16 v[84:87], v[174:177], v[238:241], v[84:87]
	v_mfma_f32_16x16x32_bf16 v[132:135], v[182:185], v[218:221], v[132:135]
	v_mfma_f32_16x16x32_bf16 v[112:115], v[210:213], v[226:229], v[112:115]
	v_mfma_f32_16x16x32_bf16 v[100:103], v[182:185], v[234:237], v[100:103]
	v_mfma_f32_16x16x32_bf16 v[64:67], v[210:213], v[242:245], v[64:67]
	v_mfma_f32_16x16x32_bf16 v[128:131], v[210:213], v[218:221], v[128:131]
	v_mfma_f32_16x16x32_bf16 v[116:119], v[182:185], v[226:229], v[116:119]
	v_mfma_f32_16x16x32_bf16 v[96:99], v[210:213], v[234:237], v[96:99]
	v_mfma_f32_16x16x32_bf16 v[84:87], v[182:185], v[242:245], v[84:87]
	s_setprio 0
	s_barrier
	s_mov_b32 m0, s45
	s_add_u32 s2, s2, 0x40080
	s_addc_u32 s3, s3, 0
	ds_read_b128 v[214:217], v179 offset:49152
	ds_read_b128 v[218:221], v179 offset:50176
	ds_read_b128 v[222:225], v179 offset:51200
	ds_read_b128 v[226:229], v179 offset:52224
	ds_read_b128 v[230:233], v179 offset:53248
	ds_read_b128 v[234:237], v179 offset:54272
	ds_read_b128 v[238:241], v179 offset:55296
	ds_read_b128 v[242:245], v179 offset:56320
	s_add_u32 s98, s2, 0xfffc0000
	s_addc_u32 s99, s3, -1
	global_load_lds_dwordx4 v166, s[98:99]
	s_mov_b32 m0, s46
	s_nop 0
	global_load_lds_dwordx4 v162, s[98:99]
	s_mov_b32 m0, s49
	s_nop 0
	global_load_lds_dwordx4 v166, s[2:3]
	s_mov_b32 m0, s50
	s_nop 0
	global_load_lds_dwordx4 v162, s[2:3]
	s_mov_b32 m0, s47
	s_nop 0
	s_add_u32 s100, s4, 0xfffc0080
	s_addc_u32 s101, s5, -1
	global_load_lds_dwordx4 v168, s[100:101]
	s_mov_b32 m0, s48
	s_nop 0
	global_load_lds_dwordx4 v164, s[100:101]
	s_waitcnt vmcnt(8)
	s_waitcnt lgkmcnt(0)
	s_barrier
	s_setprio 1
	v_mfma_f32_16x16x32_bf16 v[60:63], v[68:71], v[214:217], v[60:63]
	v_mfma_f32_16x16x32_bf16 v[40:43], v[76:79], v[222:225], v[40:43]
	v_mfma_f32_16x16x32_bf16 v[28:31], v[68:71], v[230:233], v[28:31]
	v_mfma_f32_16x16x32_bf16 v[8:11], v[76:79], v[238:241], v[8:11]
	v_mfma_f32_16x16x32_bf16 v[56:59], v[76:79], v[214:217], v[56:59]
	v_mfma_f32_16x16x32_bf16 v[44:47], v[68:71], v[222:225], v[44:47]
	v_mfma_f32_16x16x32_bf16 v[24:27], v[76:79], v[230:233], v[24:27]
	v_mfma_f32_16x16x32_bf16 v[12:15], v[68:71], v[238:241], v[12:15]
	v_mfma_f32_16x16x32_bf16 v[60:63], v[72:75], v[218:221], v[60:63]
	v_mfma_f32_16x16x32_bf16 v[40:43], v[80:83], v[226:229], v[40:43]
	v_mfma_f32_16x16x32_bf16 v[28:31], v[72:75], v[234:237], v[28:31]
	v_mfma_f32_16x16x32_bf16 v[8:11], v[80:83], v[242:245], v[8:11]
	v_mfma_f32_16x16x32_bf16 v[56:59], v[80:83], v[218:221], v[56:59]
	v_mfma_f32_16x16x32_bf16 v[44:47], v[72:75], v[226:229], v[44:47]
	v_mfma_f32_16x16x32_bf16 v[24:27], v[80:83], v[234:237], v[24:27]
	v_mfma_f32_16x16x32_bf16 v[12:15], v[72:75], v[242:245], v[12:15]
	v_mfma_f32_16x16x32_bf16 v[52:55], v[174:177], v[214:217], v[52:55]
	v_mfma_f32_16x16x32_bf16 v[32:35], v[186:189], v[222:225], v[32:35]
	v_mfma_f32_16x16x32_bf16 v[20:23], v[174:177], v[230:233], v[20:23]
	v_mfma_f32_16x16x32_bf16 v[0:3], v[186:189], v[238:241], v[0:3]
	v_mfma_f32_16x16x32_bf16 v[48:51], v[186:189], v[214:217], v[48:51]
	v_mfma_f32_16x16x32_bf16 v[36:39], v[174:177], v[222:225], v[36:39]
	v_mfma_f32_16x16x32_bf16 v[16:19], v[186:189], v[230:233], v[16:19]
	v_mfma_f32_16x16x32_bf16 v[4:7], v[174:177], v[238:241], v[4:7]
	v_mfma_f32_16x16x32_bf16 v[52:55], v[182:185], v[218:221], v[52:55]
	v_mfma_f32_16x16x32_bf16 v[32:35], v[210:213], v[226:229], v[32:35]
	v_mfma_f32_16x16x32_bf16 v[20:23], v[182:185], v[234:237], v[20:23]
	v_mfma_f32_16x16x32_bf16 v[0:3], v[210:213], v[242:245], v[0:3]
	v_mfma_f32_16x16x32_bf16 v[48:51], v[210:213], v[218:221], v[48:51]
	v_mfma_f32_16x16x32_bf16 v[36:39], v[182:185], v[226:229], v[36:39]
	v_mfma_f32_16x16x32_bf16 v[16:19], v[210:213], v[234:237], v[16:19]
	v_mfma_f32_16x16x32_bf16 v[4:7], v[182:185], v[242:245], v[4:7]
	s_setprio 0
	s_barrier
	s_add_i32 s56, s56, 2
	s_add_u32 s0, s0, 0x100
	s_addc_u32 s1, s1, 0
	s_add_u32 s54, s54, 0x100
	s_addc_u32 s55, s55, 0
	s_cmp_gt_u32 s56, 13
; #define PG8_STAGE(bufoff, gbase, voff) do { _Pragma("unroll") for (int _i = 0; _i < 2; ++_i) \
;         __builtin_amdgcn_global_load_lds((const unsigned*)((const char*)(gbase) + (voff)[_i]), (PG8_LAS unsigned*)(lds + (bufoff) + ldsw + _i * 8192), 16, 0, 0); } while (0)
; #define PG8_LDA(dst, b, h) do { _Pragma("unroll") for (int m = 0; m < 4; ++m) _Pragma("unroll") for (int k = 0; k < 2; ++k) dst[m][k] = *(const PG8_LAS bf16x8*)(lds + PG8_SA(b, h) + aoff + m * 2048 + k * 1024); } while (0)
; #define PG8_LDB(dst, b, h) do { _Pragma("unroll") for (int n = 0; n < 2; ++n) _Pragma("unroll") for (int k = 0; k < 2; ++k) dst[n][k] = *(const PG8_LAS bf16x8*)(lds + PG8_SB(b, h) + boff + n * 2048 + k * 1024); } while (0)
; #define PG8_MMA(ai, bj, At, Bt) do { __builtin_amdgcn_s_setprio(1); _Pragma("unroll") for (int m = 0; m < 4; ++m) _Pragma("unroll") for (int n = 0; n < 2; ++n) _Pragma("unroll") for (int k = 0; k < 2; ++k) \
;         acc[ai][bj][m][n] = __builtin_amdgcn_mfma_f32_16x16x32_bf16(Bt[n][k], At[m][k], acc[ai][bj][m][n], 0, 0, 0); __builtin_amdgcn_s_setprio(0); } while (0)
; #define PG8_WAIT_V(n) asm volatile("s_waitcnt vmcnt(" #n ")" ::: "memory")
; #define PG8_WAIT_L(n) asm volatile("s_waitcnt lgkmcnt(" #n ")" ::: "memory")
; template <class Epi, class Sched, bool ALIGN_EPI = false, bool SP2 = false>
; __device__ __forceinline__ void gemm_phase(PG8_LAS unsigned char* lds, const Gemm g, const Sched& S, const Epi& E) {
;     ...
;             const bool last = (t == nt - 2);
;             const char* a1 = cA + (size_t)(t + 1) * kstep;
;             const char* a2 = last ? nA : cA + (size_t)(t + 2) * kstep; const char* b2 = last ? nB : cB + (size_t)(t + 2) * kstep;
;             const char* a3 = a2 + kstep; const char* b3 = b2 + kstep;
;             if (last && has_next) S.a_ready(nxt);
;             if constexpr (SP2) {
;             PG8_LDB(B0, 0, 0); PG8_LDB(B1, 0, 1); PG8_SCHED; PG8_LDA(At, 0, 0); PG8_STAGE(PG8_SA(1, 1), a1 + hstep, voffA);
;             PG8_WAIT_V(8); PG8_WAIT_L(0); PG8_BAR; PG8_MMA(0, 0, At, B0); PG8_MMA(0, 1, At, B1); PG8_BAR; PG8_SCHED;
;             PG8_LDA(At, 0, 1); PG8_STAGE(PG8_SB(0, 0), b2, voffB); PG8_STAGE(PG8_SB(0, 1), b2 + hstep, voffB); PG8_STAGE(PG8_SA(0, 0), a2, voffA);
;             PG8_WAIT_V(8); PG8_WAIT_L(0); PG8_BAR; PG8_MMA(1, 0, At, B0); PG8_MMA(1, 1, At, B1); PG8_BAR; PG8_SCHED;
.LBB0_327:
	ds_read_b128 v[68:71], v254
	ds_read_b128 v[72:75], v254 offset:1024
	ds_read_b128 v[76:79], v254 offset:2048
	ds_read_b128 v[80:83], v254 offset:3072
	ds_read_b128 v[174:177], v254 offset:16384
	ds_read_b128 v[182:185], v254 offset:17408
	ds_read_b128 v[186:189], v254 offset:18432
	ds_read_b128 v[210:213], v254 offset:19456
	s_add_u32 s2, s0, 0xfffc0080
	s_addc_u32 s3, s1, -1
	s_cmp_eq_u32 s56, 12
	s_cselect_b32 s5, s27, s3
	s_cselect_b32 s4, s52, s2
	s_cselect_b32 s3, s25, s55
	s_cselect_b32 s2, s53, s54
	s_add_i32 m0, s29, 0xc000
	ds_read_b128 v[214:217], v179
	ds_read_b128 v[218:221], v179 offset:1024
	ds_read_b128 v[222:225], v179 offset:2048
	ds_read_b128 v[226:229], v179 offset:3072
	ds_read_b128 v[230:233], v179 offset:4096
	ds_read_b128 v[234:237], v179 offset:5120
	ds_read_b128 v[238:241], v179 offset:6144
	ds_read_b128 v[242:245], v179 offset:7168
	global_load_lds_dwordx4 v170, s[0:1]
	s_add_i32 m0, s29, 0xe000
	s_nop 0
	global_load_lds_dwordx4 v172, s[0:1]
	s_waitcnt vmcnt(8)
	s_waitcnt lgkmcnt(0)
	s_barrier
	s_setprio 1
	v_mfma_f32_16x16x32_bf16 v[140:143], v[68:71], v[214:217], v[140:143]
	v_mfma_f32_16x16x32_bf16 v[120:123], v[76:79], v[222:225], v[120:123]
	v_mfma_f32_16x16x32_bf16 v[108:111], v[68:71], v[230:233], v[108:111]
	v_mfma_f32_16x16x32_bf16 v[88:91], v[76:79], v[238:241], v[88:91]
	v_mfma_f32_16x16x32_bf16 v[136:139], v[76:79], v[214:217], v[136:139]
	v_mfma_f32_16x16x32_bf16 v[124:127], v[68:71], v[222:225], v[124:127]
	v_mfma_f32_16x16x32_bf16 v[104:107], v[76:79], v[230:233], v[104:107]
	v_mfma_f32_16x16x32_bf16 v[92:95], v[68:71], v[238:241], v[92:95]
	v_mfma_f32_16x16x32_bf16 v[140:143], v[72:75], v[218:221], v[140:143]
	v_mfma_f32_16x16x32_bf16 v[120:123], v[80:83], v[226:229], v[120:123]
	v_mfma_f32_16x16x32_bf16 v[108:111], v[72:75], v[234:237], v[108:111]
	v_mfma_f32_16x16x32_bf16 v[88:91], v[80:83], v[242:245], v[88:91]
	v_mfma_f32_16x16x32_bf16 v[136:139], v[80:83], v[218:221], v[136:139]
	v_mfma_f32_16x16x32_bf16 v[124:127], v[72:75], v[226:229], v[124:127]
	v_mfma_f32_16x16x32_bf16 v[104:107], v[80:83], v[234:237], v[104:107]
	v_mfma_f32_16x16x32_bf16 v[92:95], v[72:75], v[242:245], v[92:95]
	v_mfma_f32_16x16x32_bf16 v[132:135], v[174:177], v[214:217], v[132:135]
	v_mfma_f32_16x16x32_bf16 v[112:115], v[186:189], v[222:225], v[112:115]
	v_mfma_f32_16x16x32_bf16 v[100:103], v[174:177], v[230:233], v[100:103]
	v_mfma_f32_16x16x32_bf16 v[64:67], v[186:189], v[238:241], v[64:67]
	v_mfma_f32_16x16x32_bf16 v[128:131], v[186:189], v[214:217], v[128:131]
	v_mfma_f32_16x16x32_bf16 v[116:119], v[174:177], v[222:225], v[116:119]
	v_mfma_f32_16x16x32_bf16 v[96:99], v[186:189], v[230:233], v[96:99]
	v_mfma_f32_16x16x32_bf16 v[84:87], v[174:177], v[238:241], v[84:87]
	v_mfma_f32_16x16x32_bf16 v[132:135], v[182:185], v[218:221], v[132:135]
	v_mfma_f32_16x16x32_bf16 v[112:115], v[210:213], v[226:229], v[112:115]
	v_mfma_f32_16x16x32_bf16 v[100:103], v[182:185], v[234:237], v[100:103]
	v_mfma_f32_16x16x32_bf16 v[64:67], v[210:213], v[242:245], v[64:67]
	v_mfma_f32_16x16x32_bf16 v[128:131], v[210:213], v[218:221], v[128:131]
	v_mfma_f32_16x16x32_bf16 v[116:119], v[182:185], v[226:229], v[116:119]
	v_mfma_f32_16x16x32_bf16 v[96:99], v[210:213], v[234:237], v[96:99]
	v_mfma_f32_16x16x32_bf16 v[84:87], v[182:185], v[242:245], v[84:87]
	s_setprio 0
	s_barrier
	s_mov_b32 m0, s30
	s_add_u32 s58, s2, 0x40000
	s_addc_u32 s59, s3, 0
	ds_read_b128 v[214:217], v179 offset:16384
	ds_read_b128 v[218:221], v179 offset:17408
	ds_read_b128 v[222:225], v179 offset:18432
	ds_read_b128 v[226:229], v179 offset:19456
	ds_read_b128 v[230:233], v179 offset:20480
	ds_read_b128 v[234:237], v179 offset:21504
	ds_read_b128 v[238:241], v179 offset:22528
	ds_read_b128 v[242:245], v179 offset:23552
	global_load_lds_dwordx4 v166, s[2:3]
	s_mov_b32 m0, s31
	s_nop 0
	global_load_lds_dwordx4 v162, s[2:3]
	s_mov_b32 m0, s33
	s_nop 0
	global_load_lds_dwordx4 v166, s[58:59]
	s_mov_b32 m0, s34
	s_nop 0
	global_load_lds_dwordx4 v162, s[58:59]
	s_mov_b32 m0, s29
	s_nop 0
	global_load_lds_dwordx4 v168, s[4:5]
	s_mov_b32 m0, s35
	s_nop 0
	global_load_lds_dwordx4 v164, s[4:5]
	s_waitcnt vmcnt(8)
	s_waitcnt lgkmcnt(0)
	s_barrier
	s_setprio 1
	v_mfma_f32_16x16x32_bf16 v[60:63], v[68:71], v[214:217], v[60:63]
	v_mfma_f32_16x16x32_bf16 v[40:43], v[76:79], v[222:225], v[40:43]
	v_mfma_f32_16x16x32_bf16 v[28:31], v[68:71], v[230:233], v[28:31]
	v_mfma_f32_16x16x32_bf16 v[8:11], v[76:79], v[238:241], v[8:11]
	v_mfma_f32_16x16x32_bf16 v[56:59], v[76:79], v[214:217], v[56:59]
	v_mfma_f32_16x16x32_bf16 v[44:47], v[68:71], v[222:225], v[44:47]
	v_mfma_f32_16x16x32_bf16 v[24:27], v[76:79], v[230:233], v[24:27]
	v_mfma_f32_16x16x32_bf16 v[12:15], v[68:71], v[238:241], v[12:15]
	v_mfma_f32_16x16x32_bf16 v[60:63], v[72:75], v[218:221], v[60:63]
	v_mfma_f32_16x16x32_bf16 v[40:43], v[80:83], v[226:229], v[40:43]
	v_mfma_f32_16x16x32_bf16 v[28:31], v[72:75], v[234:237], v[28:31]
	v_mfma_f32_16x16x32_bf16 v[8:11], v[80:83], v[242:245], v[8:11]
	v_mfma_f32_16x16x32_bf16 v[56:59], v[80:83], v[218:221], v[56:59]
	v_mfma_f32_16x16x32_bf16 v[44:47], v[72:75], v[226:229], v[44:47]
	v_mfma_f32_16x16x32_bf16 v[24:27], v[80:83], v[234:237], v[24:27]
	v_mfma_f32_16x16x32_bf16 v[12:15], v[72:75], v[242:245], v[12:15]
	v_mfma_f32_16x16x32_bf16 v[52:55], v[174:177], v[214:217], v[52:55]
	v_mfma_f32_16x16x32_bf16 v[32:35], v[186:189], v[222:225], v[32:35]
	v_mfma_f32_16x16x32_bf16 v[20:23], v[174:177], v[230:233], v[20:23]
	v_mfma_f32_16x16x32_bf16 v[0:3], v[186:189], v[238:241], v[0:3]
	v_mfma_f32_16x16x32_bf16 v[48:51], v[186:189], v[214:217], v[48:51]
	v_mfma_f32_16x16x32_bf16 v[36:39], v[174:177], v[222:225], v[36:39]
	v_mfma_f32_16x16x32_bf16 v[16:19], v[186:189], v[230:233], v[16:19]
	v_mfma_f32_16x16x32_bf16 v[4:7], v[174:177], v[238:241], v[4:7]
	v_mfma_f32_16x16x32_bf16 v[52:55], v[182:185], v[218:221], v[52:55]
	v_mfma_f32_16x16x32_bf16 v[32:35], v[210:213], v[226:229], v[32:35]
	v_mfma_f32_16x16x32_bf16 v[20:23], v[182:185], v[234:237], v[20:23]
	v_mfma_f32_16x16x32_bf16 v[0:3], v[210:213], v[242:245], v[0:3]
	v_mfma_f32_16x16x32_bf16 v[48:51], v[210:213], v[218:221], v[48:51]
	v_mfma_f32_16x16x32_bf16 v[36:39], v[182:185], v[226:229], v[36:39]
	v_mfma_f32_16x16x32_bf16 v[16:19], v[210:213], v[234:237], v[16:19]
	v_mfma_f32_16x16x32_bf16 v[4:7], v[182:185], v[242:245], v[4:7]
	s_setprio 0
	s_barrier
; #define PG8_STAGE(bufoff, gbase, voff) do { _Pragma("unroll") for (int _i = 0; _i < 2; ++_i) \
;         __builtin_amdgcn_global_load_lds((const unsigned*)((const char*)(gbase) + (voff)[_i]), (PG8_LAS unsigned*)(lds + (bufoff) + ldsw + _i * 8192), 16, 0, 0); } while (0)
; #define PG8_LDA(dst, b, h) do { _Pragma("unroll") for (int m = 0; m < 4; ++m) _Pragma("unroll") for (int k = 0; k < 2; ++k) dst[m][k] = *(const PG8_LAS bf16x8*)(lds + PG8_SA(b, h) + aoff + m * 2048 + k * 1024); } while (0)
; #define PG8_LDB(dst, b, h) do { _Pragma("unroll") for (int n = 0; n < 2; ++n) _Pragma("unroll") for (int k = 0; k < 2; ++k) dst[n][k] = *(const PG8_LAS bf16x8*)(lds + PG8_SB(b, h) + boff + n * 2048 + k * 1024); } while (0)
; #define PG8_MMA(ai, bj, At, Bt) do { __builtin_amdgcn_s_setprio(1); _Pragma("unroll") for (int m = 0; m < 4; ++m) _Pragma("unroll") for (int n = 0; n < 2; ++n) _Pragma("unroll") for (int k = 0; k < 2; ++k) \
;         acc[ai][bj][m][n] = __builtin_amdgcn_mfma_f32_16x16x32_bf16(Bt[n][k], At[m][k], acc[ai][bj][m][n], 0, 0, 0); __builtin_amdgcn_s_setprio(0); } while (0)
; #define PG8_WAIT_V(n) asm volatile("s_waitcnt vmcnt(" #n ")" ::: "memory")
; #define PG8_WAIT_L(n) asm volatile("s_waitcnt lgkmcnt(" #n ")" ::: "memory")
; #define PG8_BAR __builtin_amdgcn_s_barrier()
; #define PG8_SCHED __builtin_amdgcn_sched_barrier(0)
; template <class Epi, class Sched, bool ALIGN_EPI = false, bool SP2 = false>
; __device__ __forceinline__ void gemm_phase(PG8_LAS unsigned char* lds, const Gemm g, const Sched& S, const Epi& E) {
;     ...
;             PG8_LDB(B0, 1, 0); PG8_LDB(B1, 1, 1); PG8_SCHED; PG8_LDA(At, 1, 0); PG8_STAGE(PG8_SA(0, 1), a2 + hstep, voffA);
;             PG8_WAIT_V(8); PG8_WAIT_L(0); PG8_BAR; PG8_MMA(0, 0, At, B0); PG8_MMA(0, 1, At, B1); PG8_BAR; PG8_SCHED;
;             PG8_LDA(At, 1, 1); PG8_STAGE(PG8_SB(1, 0), b3, voffB); PG8_STAGE(PG8_SB(1, 1), b3 + hstep, voffB); PG8_STAGE(PG8_SA(1, 0), a3, voffA);
;             PG8_WAIT_V(8); PG8_WAIT_L(0); PG8_BAR; PG8_MMA(1, 0, At, B0); PG8_MMA(1, 1, At, B1); PG8_BAR; PG8_SCHED;
;     ...
;         if constexpr (ALIGN_EPI) { if (wr == 0) PG8_BAR; }
	ds_read_b128 v[68:71], v254 offset:32768
	ds_read_b128 v[72:75], v254 offset:33792
	ds_read_b128 v[76:79], v254 offset:34816
	ds_read_b128 v[80:83], v254 offset:35840
	ds_read_b128 v[174:177], v254 offset:49152
	ds_read_b128 v[182:185], v254 offset:50176
	ds_read_b128 v[186:189], v254 offset:51200
	ds_read_b128 v[210:213], v254 offset:52224
	s_add_u32 s4, s4, 0x40000
	s_addc_u32 s5, s5, 0
	s_mov_b32 m0, s40
	ds_read_b128 v[214:217], v179 offset:32768
	ds_read_b128 v[218:221], v179 offset:33792
	ds_read_b128 v[222:225], v179 offset:34816
	ds_read_b128 v[226:229], v179 offset:35840
	ds_read_b128 v[230:233], v179 offset:36864
	ds_read_b128 v[234:237], v179 offset:37888
	ds_read_b128 v[238:241], v179 offset:38912
	ds_read_b128 v[242:245], v179 offset:39936
	global_load_lds_dwordx4 v168, s[4:5]
	s_mov_b32 m0, s41
	s_nop 0
	global_load_lds_dwordx4 v164, s[4:5]
	s_waitcnt vmcnt(8)
	s_waitcnt lgkmcnt(0)
	s_barrier
	s_setprio 1
	v_mfma_f32_16x16x32_bf16 v[140:143], v[68:71], v[214:217], v[140:143]
	v_mfma_f32_16x16x32_bf16 v[120:123], v[76:79], v[222:225], v[120:123]
	v_mfma_f32_16x16x32_bf16 v[108:111], v[68:71], v[230:233], v[108:111]
	v_mfma_f32_16x16x32_bf16 v[88:91], v[76:79], v[238:241], v[88:91]
	v_mfma_f32_16x16x32_bf16 v[136:139], v[76:79], v[214:217], v[136:139]
	v_mfma_f32_16x16x32_bf16 v[124:127], v[68:71], v[222:225], v[124:127]
	v_mfma_f32_16x16x32_bf16 v[104:107], v[76:79], v[230:233], v[104:107]
	v_mfma_f32_16x16x32_bf16 v[92:95], v[68:71], v[238:241], v[92:95]
	v_mfma_f32_16x16x32_bf16 v[140:143], v[72:75], v[218:221], v[140:143]
	v_mfma_f32_16x16x32_bf16 v[120:123], v[80:83], v[226:229], v[120:123]
	v_mfma_f32_16x16x32_bf16 v[108:111], v[72:75], v[234:237], v[108:111]
	v_mfma_f32_16x16x32_bf16 v[88:91], v[80:83], v[242:245], v[88:91]
	v_mfma_f32_16x16x32_bf16 v[136:139], v[80:83], v[218:221], v[136:139]
	v_mfma_f32_16x16x32_bf16 v[124:127], v[72:75], v[226:229], v[124:127]
	v_mfma_f32_16x16x32_bf16 v[104:107], v[80:83], v[234:237], v[104:107]
	v_mfma_f32_16x16x32_bf16 v[92:95], v[72:75], v[242:245], v[92:95]
	v_mfma_f32_16x16x32_bf16 v[132:135], v[174:177], v[214:217], v[132:135]
	v_mfma_f32_16x16x32_bf16 v[112:115], v[186:189], v[222:225], v[112:115]
	v_mfma_f32_16x16x32_bf16 v[100:103], v[174:177], v[230:233], v[100:103]
	v_mfma_f32_16x16x32_bf16 v[64:67], v[186:189], v[238:241], v[64:67]
	v_mfma_f32_16x16x32_bf16 v[128:131], v[186:189], v[214:217], v[128:131]
	v_mfma_f32_16x16x32_bf16 v[116:119], v[174:177], v[222:225], v[116:119]
	v_mfma_f32_16x16x32_bf16 v[96:99], v[186:189], v[230:233], v[96:99]
	v_mfma_f32_16x16x32_bf16 v[84:87], v[174:177], v[238:241], v[84:87]
	v_mfma_f32_16x16x32_bf16 v[132:135], v[182:185], v[218:221], v[132:135]
	v_mfma_f32_16x16x32_bf16 v[112:115], v[210:213], v[226:229], v[112:115]
	v_mfma_f32_16x16x32_bf16 v[100:103], v[182:185], v[234:237], v[100:103]
	v_mfma_f32_16x16x32_bf16 v[64:67], v[210:213], v[242:245], v[64:67]
	v_mfma_f32_16x16x32_bf16 v[128:131], v[210:213], v[218:221], v[128:131]
	v_mfma_f32_16x16x32_bf16 v[116:119], v[182:185], v[226:229], v[116:119]
	v_mfma_f32_16x16x32_bf16 v[96:99], v[210:213], v[234:237], v[96:99]
	v_mfma_f32_16x16x32_bf16 v[84:87], v[182:185], v[242:245], v[84:87]
	s_setprio 0
	s_barrier
	s_mov_b32 m0, s45
	s_add_u32 s2, s2, 0x40080
	s_addc_u32 s3, s3, 0
	ds_read_b128 v[214:217], v179 offset:49152
	ds_read_b128 v[218:221], v179 offset:50176
	ds_read_b128 v[222:225], v179 offset:51200
	ds_read_b128 v[226:229], v179 offset:52224
	ds_read_b128 v[230:233], v179 offset:53248
	ds_read_b128 v[234:237], v179 offset:54272
	ds_read_b128 v[238:241], v179 offset:55296
	ds_read_b128 v[242:245], v179 offset:56320
	s_add_u32 s98, s2, 0xfffc0000
	s_addc_u32 s99, s3, -1
	global_load_lds_dwordx4 v166, s[98:99]
	s_mov_b32 m0, s46
	s_nop 0
	global_load_lds_dwordx4 v162, s[98:99]
	s_mov_b32 m0, s49
	s_nop 0
	global_load_lds_dwordx4 v166, s[2:3]
	s_mov_b32 m0, s50
	s_nop 0
	global_load_lds_dwordx4 v162, s[2:3]
	s_mov_b32 m0, s47
	s_nop 0
	s_add_u32 s100, s4, 0xfffc0080
	s_addc_u32 s101, s5, -1
	global_load_lds_dwordx4 v168, s[100:101]
	s_mov_b32 m0, s48
	s_nop 0
	global_load_lds_dwordx4 v164, s[100:101]
	s_waitcnt vmcnt(8)
	s_waitcnt lgkmcnt(0)
	s_barrier
	s_setprio 1
	v_mfma_f32_16x16x32_bf16 v[60:63], v[68:71], v[214:217], v[60:63]
	v_mfma_f32_16x16x32_bf16 v[40:43], v[76:79], v[222:225], v[40:43]
	v_mfma_f32_16x16x32_bf16 v[28:31], v[68:71], v[230:233], v[28:31]
	v_mfma_f32_16x16x32_bf16 v[8:11], v[76:79], v[238:241], v[8:11]
	v_mfma_f32_16x16x32_bf16 v[56:59], v[76:79], v[214:217], v[56:59]
	v_mfma_f32_16x16x32_bf16 v[44:47], v[68:71], v[222:225], v[44:47]
	v_mfma_f32_16x16x32_bf16 v[24:27], v[76:79], v[230:233], v[24:27]
	v_mfma_f32_16x16x32_bf16 v[12:15], v[68:71], v[238:241], v[12:15]
	v_mfma_f32_16x16x32_bf16 v[60:63], v[72:75], v[218:221], v[60:63]
	v_mfma_f32_16x16x32_bf16 v[40:43], v[80:83], v[226:229], v[40:43]
	v_mfma_f32_16x16x32_bf16 v[28:31], v[72:75], v[234:237], v[28:31]
	v_mfma_f32_16x16x32_bf16 v[8:11], v[80:83], v[242:245], v[8:11]
	v_mfma_f32_16x16x32_bf16 v[56:59], v[80:83], v[218:221], v[56:59]
	v_mfma_f32_16x16x32_bf16 v[44:47], v[72:75], v[226:229], v[44:47]
	v_mfma_f32_16x16x32_bf16 v[24:27], v[80:83], v[234:237], v[24:27]
	v_mfma_f32_16x16x32_bf16 v[12:15], v[72:75], v[242:245], v[12:15]
	v_mfma_f32_16x16x32_bf16 v[52:55], v[174:177], v[214:217], v[52:55]
	v_mfma_f32_16x16x32_bf16 v[32:35], v[186:189], v[222:225], v[32:35]
	v_mfma_f32_16x16x32_bf16 v[20:23], v[174:177], v[230:233], v[20:23]
	v_mfma_f32_16x16x32_bf16 v[0:3], v[186:189], v[238:241], v[0:3]
	v_mfma_f32_16x16x32_bf16 v[48:51], v[186:189], v[214:217], v[48:51]
	v_mfma_f32_16x16x32_bf16 v[36:39], v[174:177], v[222:225], v[36:39]
	v_mfma_f32_16x16x32_bf16 v[16:19], v[186:189], v[230:233], v[16:19]
	v_mfma_f32_16x16x32_bf16 v[4:7], v[174:177], v[238:241], v[4:7]
	v_mfma_f32_16x16x32_bf16 v[52:55], v[182:185], v[218:221], v[52:55]
	v_mfma_f32_16x16x32_bf16 v[32:35], v[210:213], v[226:229], v[32:35]
	v_mfma_f32_16x16x32_bf16 v[20:23], v[182:185], v[234:237], v[20:23]
	v_mfma_f32_16x16x32_bf16 v[0:3], v[210:213], v[242:245], v[0:3]
	v_mfma_f32_16x16x32_bf16 v[48:51], v[210:213], v[218:221], v[48:51]
	v_mfma_f32_16x16x32_bf16 v[36:39], v[182:185], v[226:229], v[36:39]
	v_mfma_f32_16x16x32_bf16 v[16:19], v[210:213], v[234:237], v[16:19]
	v_mfma_f32_16x16x32_bf16 v[4:7], v[182:185], v[242:245], v[4:7]
	s_setprio 0
	s_barrier
	s_add_i32 s56, s56, 2
	s_add_u32 s0, s0, 0x100
	s_addc_u32 s1, s1, 0
	s_add_u32 s54, s54, 0x100
	s_addc_u32 s55, s55, 0
	s_cmp_gt_u32 s56, 13
	s_cbranch_scc0 .LBB0_327
	s_and_b64 vcc, exec, s[22:23]
	s_cbranch_vccz .LBB0_330
	s_barrier

; #define PG8_STAGE(bufoff, gbase, voff) do { _Pragma("unroll") for (int _i = 0; _i < 2; ++_i) \
;         __builtin_amdgcn_global_load_lds((const unsigned*)((const char*)(gbase) + (voff)[_i]), (PG8_LAS unsigned*)(lds + (bufoff) + ldsw + _i * 8192), 16, 0, 0); } while (0)
; #define PG8_LDA(dst, b, h) do { _Pragma("unroll") for (int m = 0; m < 4; ++m) _Pragma("unroll") for (int k = 0; k < 2; ++k) dst[m][k] = *(const PG8_LAS bf16x8*)(lds + PG8_SA(b, h) + aoff + m * 2048 + k * 1024); } while (0)
; #define PG8_LDB(dst, b, h) do { _Pragma("unroll") for (int n = 0; n < 2; ++n) _Pragma("unroll") for (int k = 0; k < 2; ++k) dst[n][k] = *(const PG8_LAS bf16x8*)(lds + PG8_SB(b, h) + boff + n * 2048 + k * 1024); } while (0)
; #define PG8_MMA(ai, bj, At, Bt) do { __builtin_amdgcn_s_setprio(1); _Pragma("unroll") for (int m = 0; m < 4; ++m) _Pragma("unroll") for (int n = 0; n < 2; ++n) _Pragma("unroll") for (int k = 0; k < 2; ++k) \
;         acc[ai][bj][m][n] = __builtin_amdgcn_mfma_f32_16x16x32_bf16(Bt[n][k], At[m][k], acc[ai][bj][m][n], 0, 0, 0); __builtin_amdgcn_s_setprio(0); } while (0)
; #define PG8_WAIT_V(n) asm volatile("s_waitcnt vmcnt(" #n ")" ::: "memory")
; #define PG8_WAIT_L(n) asm volatile("s_waitcnt lgkmcnt(" #n ")" ::: "memory")
; #define PG8_BAR __builtin_amdgcn_s_barrier()
; #define PG8_SCHED __builtin_amdgcn_sched_barrier(0)
; template <class Epi, class Sched, bool ALIGN_EPI = false, bool SP2 = false>
; __device__ __forceinline__ void gemm_phase(PG8_LAS unsigned char* lds, const Gemm g, const Sched& S, const Epi& E) {
;     ...
;             PG8_LDB(B0, 0, 0); PG8_LDB(B1, 0, 1); PG8_SCHED; PG8_LDA(At, 0, 0); PG8_STAGE(PG8_SA(1, 1), a1 + hstep, voffA);
;             PG8_WAIT_V(8); PG8_WAIT_L(0); PG8_BAR; PG8_MMA(0, 0, At, B0); PG8_MMA(0, 1, At, B1); PG8_BAR; PG8_SCHED;
;             PG8_LDA(At, 0, 1); PG8_STAGE(PG8_SB(0, 0), b2, voffB); PG8_STAGE(PG8_SB(0, 1), b2 + hstep, voffB); PG8_STAGE(PG8_SA(0, 0), a2, voffA);
;             PG8_WAIT_V(8); PG8_WAIT_L(0); PG8_BAR; PG8_MMA(1, 0, At, B0); PG8_MMA(1, 1, At, B1); PG8_BAR; PG8_SCHED;
.Lup_peel:
	ds_read_b128 v[140:143], v254
	ds_read_b128 v[168:171], v254 offset:1024
	ds_read_b128 v[172:175], v254 offset:2048
	ds_read_b128 v[176:179], v254 offset:3072
	ds_read_b128 v[180:183], v254 offset:16384
	ds_read_b128 v[184:187], v254 offset:17408
	ds_read_b128 v[188:191], v254 offset:18432
	ds_read_b128 v[210:213], v254 offset:19456
	s_add_u32 s16, s14, 0xfffc0080
	s_addc_u32 s17, s15, -1
	s_cmp_eq_u32 s53, 12
	s_cselect_b32 s19, s7, s17
	s_cselect_b32 s18, s49, s16
	s_cselect_b32 s17, s5, s52
	s_cselect_b32 s16, s50, s51
	s_mov_b32 m0, s43
	ds_read_b128 v[214:217], v165
	ds_read_b128 v[218:221], v165 offset:1024
	ds_read_b128 v[222:225], v165 offset:2048
	ds_read_b128 v[226:229], v165 offset:3072
	ds_read_b128 v[230:233], v165 offset:4096
	ds_read_b128 v[234:237], v165 offset:5120
	ds_read_b128 v[238:241], v165 offset:6144
	ds_read_b128 v[242:245], v165 offset:7168
	global_load_lds_dwordx4 v136, s[14:15]
	s_mov_b32 m0, s44
	s_nop 0
	global_load_lds_dwordx4 v138, s[14:15]
	s_waitcnt vmcnt(8)
	s_waitcnt lgkmcnt(0)
	s_barrier
	s_setprio 1
	v_mfma_f32_16x16x32_bf16 v[124:127], v[140:143], v[214:217], 0
	v_mfma_f32_16x16x32_bf16 v[100:103], v[172:175], v[222:225], 0
	v_mfma_f32_16x16x32_bf16 v[92:95], v[140:143], v[230:233], 0
	v_mfma_f32_16x16x32_bf16 v[68:71], v[172:175], v[238:241], 0
	v_mfma_f32_16x16x32_bf16 v[116:119], v[172:175], v[214:217], 0
	v_mfma_f32_16x16x32_bf16 v[108:111], v[140:143], v[222:225], 0
	v_mfma_f32_16x16x32_bf16 v[84:87], v[172:175], v[230:233], 0
	v_mfma_f32_16x16x32_bf16 v[76:79], v[140:143], v[238:241], 0
	v_mfma_f32_16x16x32_bf16 v[124:127], v[168:171], v[218:221], v[124:127]
	v_mfma_f32_16x16x32_bf16 v[100:103], v[176:179], v[226:229], v[100:103]
	v_mfma_f32_16x16x32_bf16 v[92:95], v[168:171], v[234:237], v[92:95]
	v_mfma_f32_16x16x32_bf16 v[68:71], v[176:179], v[242:245], v[68:71]
	v_mfma_f32_16x16x32_bf16 v[116:119], v[176:179], v[218:221], v[116:119]
	v_mfma_f32_16x16x32_bf16 v[108:111], v[168:171], v[226:229], v[108:111]
	v_mfma_f32_16x16x32_bf16 v[84:87], v[176:179], v[234:237], v[84:87]
	v_mfma_f32_16x16x32_bf16 v[76:79], v[168:171], v[242:245], v[76:79]
	v_mfma_f32_16x16x32_bf16 v[120:123], v[180:183], v[214:217], 0
	v_mfma_f32_16x16x32_bf16 v[96:99], v[188:191], v[222:225], 0
	v_mfma_f32_16x16x32_bf16 v[88:91], v[180:183], v[230:233], 0
	v_mfma_f32_16x16x32_bf16 v[64:67], v[188:191], v[238:241], 0
	v_mfma_f32_16x16x32_bf16 v[112:115], v[188:191], v[214:217], 0
	v_mfma_f32_16x16x32_bf16 v[104:107], v[180:183], v[222:225], 0
	v_mfma_f32_16x16x32_bf16 v[80:83], v[188:191], v[230:233], 0
	v_mfma_f32_16x16x32_bf16 v[72:75], v[180:183], v[238:241], 0
	v_mfma_f32_16x16x32_bf16 v[120:123], v[184:187], v[218:221], v[120:123]
	v_mfma_f32_16x16x32_bf16 v[96:99], v[210:213], v[226:229], v[96:99]
	v_mfma_f32_16x16x32_bf16 v[88:91], v[184:187], v[234:237], v[88:91]
	v_mfma_f32_16x16x32_bf16 v[64:67], v[210:213], v[242:245], v[64:67]
	v_mfma_f32_16x16x32_bf16 v[112:115], v[210:213], v[218:221], v[112:115]
	v_mfma_f32_16x16x32_bf16 v[104:107], v[184:187], v[226:229], v[104:107]
	v_mfma_f32_16x16x32_bf16 v[80:83], v[210:213], v[234:237], v[80:83]
	v_mfma_f32_16x16x32_bf16 v[72:75], v[184:187], v[242:245], v[72:75]
	s_setprio 0
	s_barrier
	s_mov_b32 m0, s27
	s_add_u32 s54, s16, 0x40000
	s_addc_u32 s55, s17, 0
	ds_read_b128 v[214:217], v165 offset:16384
	ds_read_b128 v[218:221], v165 offset:17408
	ds_read_b128 v[222:225], v165 offset:18432
	ds_read_b128 v[226:229], v165 offset:19456
	ds_read_b128 v[230:233], v165 offset:20480
	ds_read_b128 v[234:237], v165 offset:21504
	ds_read_b128 v[238:241], v165 offset:22528
	ds_read_b128 v[242:245], v165 offset:23552
	global_load_lds_dwordx4 v132, s[16:17]
	s_mov_b32 m0, s28
	s_nop 0
	global_load_lds_dwordx4 v128, s[16:17]
	s_mov_b32 m0, s29
	s_nop 0
	global_load_lds_dwordx4 v132, s[54:55]
	s_mov_b32 m0, s30
	s_nop 0
	global_load_lds_dwordx4 v128, s[54:55]
	s_mov_b32 m0, s22
	s_nop 0
	global_load_lds_dwordx4 v134, s[18:19]
	s_mov_b32 m0, s31
	s_nop 0
	global_load_lds_dwordx4 v130, s[18:19]
	s_waitcnt vmcnt(8)
	s_waitcnt lgkmcnt(0)
	s_barrier
	s_setprio 1
	v_mfma_f32_16x16x32_bf16 v[60:63], v[140:143], v[214:217], 0
	v_mfma_f32_16x16x32_bf16 v[36:39], v[172:175], v[222:225], 0
	v_mfma_f32_16x16x32_bf16 v[28:31], v[140:143], v[230:233], 0
	v_mfma_f32_16x16x32_bf16 v[4:7], v[172:175], v[238:241], 0
	v_mfma_f32_16x16x32_bf16 v[52:55], v[172:175], v[214:217], 0
	v_mfma_f32_16x16x32_bf16 v[44:47], v[140:143], v[222:225], 0
	v_mfma_f32_16x16x32_bf16 v[20:23], v[172:175], v[230:233], 0
	v_mfma_f32_16x16x32_bf16 v[12:15], v[140:143], v[238:241], 0
	v_mfma_f32_16x16x32_bf16 v[60:63], v[168:171], v[218:221], v[60:63]
	v_mfma_f32_16x16x32_bf16 v[36:39], v[176:179], v[226:229], v[36:39]
	v_mfma_f32_16x16x32_bf16 v[28:31], v[168:171], v[234:237], v[28:31]
	v_mfma_f32_16x16x32_bf16 v[4:7], v[176:179], v[242:245], v[4:7]
	v_mfma_f32_16x16x32_bf16 v[52:55], v[176:179], v[218:221], v[52:55]
	v_mfma_f32_16x16x32_bf16 v[44:47], v[168:171], v[226:229], v[44:47]
	v_mfma_f32_16x16x32_bf16 v[20:23], v[176:179], v[234:237], v[20:23]
	v_mfma_f32_16x16x32_bf16 v[12:15], v[168:171], v[242:245], v[12:15]
	v_mfma_f32_16x16x32_bf16 v[56:59], v[180:183], v[214:217], 0
	v_mfma_f32_16x16x32_bf16 v[32:35], v[188:191], v[222:225], 0
	v_mfma_f32_16x16x32_bf16 v[24:27], v[180:183], v[230:233], 0
	v_mfma_f32_16x16x32_bf16 v[0:3], v[188:191], v[238:241], 0
	v_mfma_f32_16x16x32_bf16 v[48:51], v[188:191], v[214:217], 0
	v_mfma_f32_16x16x32_bf16 v[40:43], v[180:183], v[222:225], 0
	v_mfma_f32_16x16x32_bf16 v[16:19], v[188:191], v[230:233], 0
	v_mfma_f32_16x16x32_bf16 v[8:11], v[180:183], v[238:241], 0
	v_mfma_f32_16x16x32_bf16 v[56:59], v[184:187], v[218:221], v[56:59]
	v_mfma_f32_16x16x32_bf16 v[32:35], v[210:213], v[226:229], v[32:35]
	v_mfma_f32_16x16x32_bf16 v[24:27], v[184:187], v[234:237], v[24:27]
	v_mfma_f32_16x16x32_bf16 v[0:3], v[210:213], v[242:245], v[0:3]
	v_mfma_f32_16x16x32_bf16 v[48:51], v[210:213], v[218:221], v[48:51]
	v_mfma_f32_16x16x32_bf16 v[40:43], v[184:187], v[226:229], v[40:43]
	v_mfma_f32_16x16x32_bf16 v[16:19], v[210:213], v[234:237], v[16:19]
	v_mfma_f32_16x16x32_bf16 v[8:11], v[184:187], v[242:245], v[8:11]
	s_setprio 0
	s_barrier
; #define PG8_STAGE(bufoff, gbase, voff) do { _Pragma("unroll") for (int _i = 0; _i < 2; ++_i) \
;         __builtin_amdgcn_global_load_lds((const unsigned*)((const char*)(gbase) + (voff)[_i]), (PG8_LAS unsigned*)(lds + (bufoff) + ldsw + _i * 8192), 16, 0, 0); } while (0)
; #define PG8_LDA(dst, b, h) do { _Pragma("unroll") for (int m = 0; m < 4; ++m) _Pragma("unroll") for (int k = 0; k < 2; ++k) dst[m][k] = *(const PG8_LAS bf16x8*)(lds + PG8_SA(b, h) + aoff + m * 2048 + k * 1024); } while (0)
; #define PG8_LDB(dst, b, h) do { _Pragma("unroll") for (int n = 0; n < 2; ++n) _Pragma("unroll") for (int k = 0; k < 2; ++k) dst[n][k] = *(const PG8_LAS bf16x8*)(lds + PG8_SB(b, h) + boff + n * 2048 + k * 1024); } while (0)
; #define PG8_MMA(ai, bj, At, Bt) do { __builtin_amdgcn_s_setprio(1); _Pragma("unroll") for (int m = 0; m < 4; ++m) _Pragma("unroll") for (int n = 0; n < 2; ++n) _Pragma("unroll") for (int k = 0; k < 2; ++k) \
;         acc[ai][bj][m][n] = __builtin_amdgcn_mfma_f32_16x16x32_bf16(Bt[n][k], At[m][k], acc[ai][bj][m][n], 0, 0, 0); __builtin_amdgcn_s_setprio(0); } while (0)
; #define PG8_WAIT_V(n) asm volatile("s_waitcnt vmcnt(" #n ")" ::: "memory")
; #define PG8_WAIT_L(n) asm volatile("s_waitcnt lgkmcnt(" #n ")" ::: "memory")
; #define PG8_BAR __builtin_amdgcn_s_barrier()
; #define PG8_SCHED __builtin_amdgcn_sched_barrier(0)
; template <class Epi, class Sched, bool ALIGN_EPI = false, bool SP2 = false>
; __device__ __forceinline__ void gemm_phase(PG8_LAS unsigned char* lds, const Gemm g, const Sched& S, const Epi& E) {
;     ...
;         for (int t = 0; t < nt; t += 2) {
;     ...
;             PG8_LDB(B0, 1, 0); PG8_LDB(B1, 1, 1); PG8_SCHED; PG8_LDA(At, 1, 0); PG8_STAGE(PG8_SA(0, 1), a2 + hstep, voffA);
;             PG8_WAIT_V(8); PG8_WAIT_L(0); PG8_BAR; PG8_MMA(0, 0, At, B0); PG8_MMA(0, 1, At, B1); PG8_BAR; PG8_SCHED;
;             PG8_LDA(At, 1, 1); PG8_STAGE(PG8_SB(1, 0), b3, voffB); PG8_STAGE(PG8_SB(1, 1), b3 + hstep, voffB); PG8_STAGE(PG8_SA(1, 0), a3, voffA);
;             PG8_WAIT_V(8); PG8_WAIT_L(0); PG8_BAR; PG8_MMA(1, 0, At, B0); PG8_MMA(1, 1, At, B1); PG8_BAR; PG8_SCHED;
	ds_read_b128 v[140:143], v254 offset:32768
	ds_read_b128 v[168:171], v254 offset:33792
	ds_read_b128 v[172:175], v254 offset:34816
	ds_read_b128 v[176:179], v254 offset:35840
	ds_read_b128 v[180:183], v254 offset:49152
	ds_read_b128 v[184:187], v254 offset:50176
	ds_read_b128 v[188:191], v254 offset:51200
	ds_read_b128 v[210:213], v254 offset:52224
	s_add_u32 s18, s18, 0x40000
	s_addc_u32 s19, s19, 0
	s_mov_b32 m0, s33
	ds_read_b128 v[214:217], v165 offset:32768
	ds_read_b128 v[218:221], v165 offset:33792
	ds_read_b128 v[222:225], v165 offset:34816
	ds_read_b128 v[226:229], v165 offset:35840
	ds_read_b128 v[230:233], v165 offset:36864
	ds_read_b128 v[234:237], v165 offset:37888
	ds_read_b128 v[238:241], v165 offset:38912
	ds_read_b128 v[242:245], v165 offset:39936
	global_load_lds_dwordx4 v134, s[18:19]
	s_mov_b32 m0, s34
	s_nop 0
	global_load_lds_dwordx4 v130, s[18:19]
	s_waitcnt vmcnt(8)
	s_waitcnt lgkmcnt(0)
	s_barrier
	s_setprio 1
	v_mfma_f32_16x16x32_bf16 v[124:127], v[140:143], v[214:217], v[124:127]
	v_mfma_f32_16x16x32_bf16 v[100:103], v[172:175], v[222:225], v[100:103]
	v_mfma_f32_16x16x32_bf16 v[92:95], v[140:143], v[230:233], v[92:95]
	v_mfma_f32_16x16x32_bf16 v[68:71], v[172:175], v[238:241], v[68:71]
	v_mfma_f32_16x16x32_bf16 v[116:119], v[172:175], v[214:217], v[116:119]
	v_mfma_f32_16x16x32_bf16 v[108:111], v[140:143], v[222:225], v[108:111]
	v_mfma_f32_16x16x32_bf16 v[84:87], v[172:175], v[230:233], v[84:87]
	v_mfma_f32_16x16x32_bf16 v[76:79], v[140:143], v[238:241], v[76:79]
	v_mfma_f32_16x16x32_bf16 v[124:127], v[168:171], v[218:221], v[124:127]
	v_mfma_f32_16x16x32_bf16 v[100:103], v[176:179], v[226:229], v[100:103]
	v_mfma_f32_16x16x32_bf16 v[92:95], v[168:171], v[234:237], v[92:95]
	v_mfma_f32_16x16x32_bf16 v[68:71], v[176:179], v[242:245], v[68:71]
	v_mfma_f32_16x16x32_bf16 v[116:119], v[176:179], v[218:221], v[116:119]
	v_mfma_f32_16x16x32_bf16 v[108:111], v[168:171], v[226:229], v[108:111]
	v_mfma_f32_16x16x32_bf16 v[84:87], v[176:179], v[234:237], v[84:87]
	v_mfma_f32_16x16x32_bf16 v[76:79], v[168:171], v[242:245], v[76:79]
	v_mfma_f32_16x16x32_bf16 v[120:123], v[180:183], v[214:217], v[120:123]
	v_mfma_f32_16x16x32_bf16 v[96:99], v[188:191], v[222:225], v[96:99]
	v_mfma_f32_16x16x32_bf16 v[88:91], v[180:183], v[230:233], v[88:91]
	v_mfma_f32_16x16x32_bf16 v[64:67], v[188:191], v[238:241], v[64:67]
	v_mfma_f32_16x16x32_bf16 v[112:115], v[188:191], v[214:217], v[112:115]
	v_mfma_f32_16x16x32_bf16 v[104:107], v[180:183], v[222:225], v[104:107]
	v_mfma_f32_16x16x32_bf16 v[80:83], v[188:191], v[230:233], v[80:83]
	v_mfma_f32_16x16x32_bf16 v[72:75], v[180:183], v[238:241], v[72:75]
	v_mfma_f32_16x16x32_bf16 v[120:123], v[184:187], v[218:221], v[120:123]
	v_mfma_f32_16x16x32_bf16 v[96:99], v[210:213], v[226:229], v[96:99]
	v_mfma_f32_16x16x32_bf16 v[88:91], v[184:187], v[234:237], v[88:91]
	v_mfma_f32_16x16x32_bf16 v[64:67], v[210:213], v[242:245], v[64:67]
	v_mfma_f32_16x16x32_bf16 v[112:115], v[210:213], v[218:221], v[112:115]
	v_mfma_f32_16x16x32_bf16 v[104:107], v[184:187], v[226:229], v[104:107]
	v_mfma_f32_16x16x32_bf16 v[80:83], v[210:213], v[234:237], v[80:83]
	v_mfma_f32_16x16x32_bf16 v[72:75], v[184:187], v[242:245], v[72:75]
	s_setprio 0
	s_barrier
	s_mov_b32 m0, s37
	s_add_u32 s16, s16, 0x40080
	s_addc_u32 s17, s17, 0
	ds_read_b128 v[214:217], v165 offset:49152
	ds_read_b128 v[218:221], v165 offset:50176
	ds_read_b128 v[222:225], v165 offset:51200
	ds_read_b128 v[226:229], v165 offset:52224
	ds_read_b128 v[230:233], v165 offset:53248
	ds_read_b128 v[234:237], v165 offset:54272
	ds_read_b128 v[238:241], v165 offset:55296
	ds_read_b128 v[242:245], v165 offset:56320
	s_add_u32 s98, s16, 0xfffc0000
	s_addc_u32 s99, s17, -1
	global_load_lds_dwordx4 v132, s[98:99]
	s_mov_b32 m0, s38
	s_nop 0
	global_load_lds_dwordx4 v128, s[98:99]
	s_mov_b32 m0, s41
	s_nop 0
	global_load_lds_dwordx4 v132, s[16:17]
	s_mov_b32 m0, s42
	s_nop 0
	global_load_lds_dwordx4 v128, s[16:17]
	s_mov_b32 m0, s39
	s_nop 0
	s_add_u32 s100, s18, 0xfffc0080
	s_addc_u32 s101, s19, -1
	global_load_lds_dwordx4 v134, s[100:101]
	s_mov_b32 m0, s40
	s_nop 0
	global_load_lds_dwordx4 v130, s[100:101]
	s_waitcnt vmcnt(8)
	s_waitcnt lgkmcnt(0)
	s_barrier
	s_setprio 1
	v_mfma_f32_16x16x32_bf16 v[60:63], v[140:143], v[214:217], v[60:63]
	v_mfma_f32_16x16x32_bf16 v[36:39], v[172:175], v[222:225], v[36:39]
	v_mfma_f32_16x16x32_bf16 v[28:31], v[140:143], v[230:233], v[28:31]
	v_mfma_f32_16x16x32_bf16 v[4:7], v[172:175], v[238:241], v[4:7]
	v_mfma_f32_16x16x32_bf16 v[52:55], v[172:175], v[214:217], v[52:55]
	v_mfma_f32_16x16x32_bf16 v[44:47], v[140:143], v[222:225], v[44:47]
	v_mfma_f32_16x16x32_bf16 v[20:23], v[172:175], v[230:233], v[20:23]
	v_mfma_f32_16x16x32_bf16 v[12:15], v[140:143], v[238:241], v[12:15]
	v_mfma_f32_16x16x32_bf16 v[60:63], v[168:171], v[218:221], v[60:63]
	v_mfma_f32_16x16x32_bf16 v[36:39], v[176:179], v[226:229], v[36:39]
	v_mfma_f32_16x16x32_bf16 v[28:31], v[168:171], v[234:237], v[28:31]
	v_mfma_f32_16x16x32_bf16 v[4:7], v[176:179], v[242:245], v[4:7]
	v_mfma_f32_16x16x32_bf16 v[52:55], v[176:179], v[218:221], v[52:55]
	v_mfma_f32_16x16x32_bf16 v[44:47], v[168:171], v[226:229], v[44:47]
	v_mfma_f32_16x16x32_bf16 v[20:23], v[176:179], v[234:237], v[20:23]
	v_mfma_f32_16x16x32_bf16 v[12:15], v[168:171], v[242:245], v[12:15]
	v_mfma_f32_16x16x32_bf16 v[56:59], v[180:183], v[214:217], v[56:59]
	v_mfma_f32_16x16x32_bf16 v[32:35], v[188:191], v[222:225], v[32:35]
	v_mfma_f32_16x16x32_bf16 v[24:27], v[180:183], v[230:233], v[24:27]
	v_mfma_f32_16x16x32_bf16 v[0:3], v[188:191], v[238:241], v[0:3]
	v_mfma_f32_16x16x32_bf16 v[48:51], v[188:191], v[214:217], v[48:51]
	v_mfma_f32_16x16x32_bf16 v[40:43], v[180:183], v[222:225], v[40:43]
	v_mfma_f32_16x16x32_bf16 v[16:19], v[188:191], v[230:233], v[16:19]
	v_mfma_f32_16x16x32_bf16 v[8:11], v[180:183], v[238:241], v[8:11]
	v_mfma_f32_16x16x32_bf16 v[56:59], v[184:187], v[218:221], v[56:59]
	v_mfma_f32_16x16x32_bf16 v[32:35], v[210:213], v[226:229], v[32:35]
	v_mfma_f32_16x16x32_bf16 v[24:27], v[184:187], v[234:237], v[24:27]
	v_mfma_f32_16x16x32_bf16 v[0:3], v[210:213], v[242:245], v[0:3]
	v_mfma_f32_16x16x32_bf16 v[48:51], v[210:213], v[218:221], v[48:51]
	v_mfma_f32_16x16x32_bf16 v[40:43], v[184:187], v[226:229], v[40:43]
	v_mfma_f32_16x16x32_bf16 v[16:19], v[210:213], v[234:237], v[16:19]
	v_mfma_f32_16x16x32_bf16 v[8:11], v[184:187], v[242:245], v[8:11]
	s_setprio 0
	s_barrier
	s_add_i32 s53, s53, 2
	s_add_u32 s14, s14, 0x100
	s_addc_u32 s15, s15, 0
	s_add_u32 s51, s51, 0x100
	s_addc_u32 s52, s52, 0
	s_cmp_gt_u32 s53, 13
; #define PG8_STAGE(bufoff, gbase, voff) do { _Pragma("unroll") for (int _i = 0; _i < 2; ++_i) \
;         __builtin_amdgcn_global_load_lds((const unsigned*)((const char*)(gbase) + (voff)[_i]), (PG8_LAS unsigned*)(lds + (bufoff) + ldsw + _i * 8192), 16, 0, 0); } while (0)
; #define PG8_LDA(dst, b, h) do { _Pragma("unroll") for (int m = 0; m < 4; ++m) _Pragma("unroll") for (int k = 0; k < 2; ++k) dst[m][k] = *(const PG8_LAS bf16x8*)(lds + PG8_SA(b, h) + aoff + m * 2048 + k * 1024); } while (0)
; #define PG8_LDB(dst, b, h) do { _Pragma("unroll") for (int n = 0; n < 2; ++n) _Pragma("unroll") for (int k = 0; k < 2; ++k) dst[n][k] = *(const PG8_LAS bf16x8*)(lds + PG8_SB(b, h) + boff + n * 2048 + k * 1024); } while (0)
; #define PG8_MMA(ai, bj, At, Bt) do { __builtin_amdgcn_s_setprio(1); _Pragma("unroll") for (int m = 0; m < 4; ++m) _Pragma("unroll") for (int n = 0; n < 2; ++n) _Pragma("unroll") for (int k = 0; k < 2; ++k) \
;         acc[ai][bj][m][n] = __builtin_amdgcn_mfma_f32_16x16x32_bf16(Bt[n][k], At[m][k], acc[ai][bj][m][n], 0, 0, 0); __builtin_amdgcn_s_setprio(0); } while (0)
; #define PG8_WAIT_V(n) asm volatile("s_waitcnt vmcnt(" #n ")" ::: "memory")
; #define PG8_WAIT_L(n) asm volatile("s_waitcnt lgkmcnt(" #n ")" ::: "memory")
; #define PG8_BAR __builtin_amdgcn_s_barrier()
; #define PG8_SCHED __builtin_amdgcn_sched_barrier(0)
; template <class Epi, class Sched, bool ALIGN_EPI = false, bool SP2 = false>
; __device__ __forceinline__ void gemm_phase(PG8_LAS unsigned char* lds, const Gemm g, const Sched& S, const Epi& E) {
;     ...
;             PG8_LDB(B0, 0, 0); PG8_LDB(B1, 0, 1); PG8_SCHED; PG8_LDA(At, 0, 0); PG8_STAGE(PG8_SA(1, 1), a1 + hstep, voffA);
;             PG8_WAIT_V(8); PG8_WAIT_L(0); PG8_BAR; PG8_MMA(0, 0, At, B0); PG8_MMA(0, 1, At, B1); PG8_BAR; PG8_SCHED;
;             PG8_LDA(At, 0, 1); PG8_STAGE(PG8_SB(0, 0), b2, voffB); PG8_STAGE(PG8_SB(0, 1), b2 + hstep, voffB); PG8_STAGE(PG8_SA(0, 0), a2, voffA);
;             PG8_WAIT_V(8); PG8_WAIT_L(0); PG8_BAR; PG8_MMA(1, 0, At, B0); PG8_MMA(1, 1, At, B1); PG8_BAR; PG8_SCHED;
.LBB0_446:
	ds_read_b128 v[140:143], v254
	ds_read_b128 v[168:171], v254 offset:1024
	ds_read_b128 v[172:175], v254 offset:2048
	ds_read_b128 v[176:179], v254 offset:3072
	ds_read_b128 v[180:183], v254 offset:16384
	ds_read_b128 v[184:187], v254 offset:17408
	ds_read_b128 v[188:191], v254 offset:18432
	ds_read_b128 v[210:213], v254 offset:19456
	s_add_u32 s16, s14, 0xfffc0080
	s_addc_u32 s17, s15, -1
	s_cmp_eq_u32 s53, 12
	s_cselect_b32 s19, s7, s17
	s_cselect_b32 s18, s49, s16
	s_cselect_b32 s17, s5, s52
	s_cselect_b32 s16, s50, s51
	s_mov_b32 m0, s43
	ds_read_b128 v[214:217], v165
	ds_read_b128 v[218:221], v165 offset:1024
	ds_read_b128 v[222:225], v165 offset:2048
	ds_read_b128 v[226:229], v165 offset:3072
	ds_read_b128 v[230:233], v165 offset:4096
	ds_read_b128 v[234:237], v165 offset:5120
	ds_read_b128 v[238:241], v165 offset:6144
	ds_read_b128 v[242:245], v165 offset:7168
	global_load_lds_dwordx4 v136, s[14:15]
	s_mov_b32 m0, s44
	s_nop 0
	global_load_lds_dwordx4 v138, s[14:15]
	s_waitcnt vmcnt(8)
	s_waitcnt lgkmcnt(0)
	s_barrier
	s_setprio 1
	v_mfma_f32_16x16x32_bf16 v[124:127], v[140:143], v[214:217], v[124:127]
	v_mfma_f32_16x16x32_bf16 v[100:103], v[172:175], v[222:225], v[100:103]
	v_mfma_f32_16x16x32_bf16 v[92:95], v[140:143], v[230:233], v[92:95]
	v_mfma_f32_16x16x32_bf16 v[68:71], v[172:175], v[238:241], v[68:71]
	v_mfma_f32_16x16x32_bf16 v[116:119], v[172:175], v[214:217], v[116:119]
	v_mfma_f32_16x16x32_bf16 v[108:111], v[140:143], v[222:225], v[108:111]
	v_mfma_f32_16x16x32_bf16 v[84:87], v[172:175], v[230:233], v[84:87]
	v_mfma_f32_16x16x32_bf16 v[76:79], v[140:143], v[238:241], v[76:79]
	v_mfma_f32_16x16x32_bf16 v[124:127], v[168:171], v[218:221], v[124:127]
	v_mfma_f32_16x16x32_bf16 v[100:103], v[176:179], v[226:229], v[100:103]
	v_mfma_f32_16x16x32_bf16 v[92:95], v[168:171], v[234:237], v[92:95]
	v_mfma_f32_16x16x32_bf16 v[68:71], v[176:179], v[242:245], v[68:71]
	v_mfma_f32_16x16x32_bf16 v[116:119], v[176:179], v[218:221], v[116:119]
	v_mfma_f32_16x16x32_bf16 v[108:111], v[168:171], v[226:229], v[108:111]
	v_mfma_f32_16x16x32_bf16 v[84:87], v[176:179], v[234:237], v[84:87]
	v_mfma_f32_16x16x32_bf16 v[76:79], v[168:171], v[242:245], v[76:79]
	v_mfma_f32_16x16x32_bf16 v[120:123], v[180:183], v[214:217], v[120:123]
	v_mfma_f32_16x16x32_bf16 v[96:99], v[188:191], v[222:225], v[96:99]
	v_mfma_f32_16x16x32_bf16 v[88:91], v[180:183], v[230:233], v[88:91]
	v_mfma_f32_16x16x32_bf16 v[64:67], v[188:191], v[238:241], v[64:67]
	v_mfma_f32_16x16x32_bf16 v[112:115], v[188:191], v[214:217], v[112:115]
	v_mfma_f32_16x16x32_bf16 v[104:107], v[180:183], v[222:225], v[104:107]
	v_mfma_f32_16x16x32_bf16 v[80:83], v[188:191], v[230:233], v[80:83]
	v_mfma_f32_16x16x32_bf16 v[72:75], v[180:183], v[238:241], v[72:75]
	v_mfma_f32_16x16x32_bf16 v[120:123], v[184:187], v[218:221], v[120:123]
	v_mfma_f32_16x16x32_bf16 v[96:99], v[210:213], v[226:229], v[96:99]
	v_mfma_f32_16x16x32_bf16 v[88:91], v[184:187], v[234:237], v[88:91]
	v_mfma_f32_16x16x32_bf16 v[64:67], v[210:213], v[242:245], v[64:67]
	v_mfma_f32_16x16x32_bf16 v[112:115], v[210:213], v[218:221], v[112:115]
	v_mfma_f32_16x16x32_bf16 v[104:107], v[184:187], v[226:229], v[104:107]
	v_mfma_f32_16x16x32_bf16 v[80:83], v[210:213], v[234:237], v[80:83]
	v_mfma_f32_16x16x32_bf16 v[72:75], v[184:187], v[242:245], v[72:75]
	s_setprio 0
	s_barrier
	s_mov_b32 m0, s27
	s_add_u32 s54, s16, 0x40000
	s_addc_u32 s55, s17, 0
	ds_read_b128 v[214:217], v165 offset:16384
	ds_read_b128 v[218:221], v165 offset:17408
	ds_read_b128 v[222:225], v165 offset:18432
	ds_read_b128 v[226:229], v165 offset:19456
	ds_read_b128 v[230:233], v165 offset:20480
	ds_read_b128 v[234:237], v165 offset:21504
	ds_read_b128 v[238:241], v165 offset:22528
	ds_read_b128 v[242:245], v165 offset:23552
	global_load_lds_dwordx4 v132, s[16:17]
	s_mov_b32 m0, s28
	s_nop 0
	global_load_lds_dwordx4 v128, s[16:17]
	s_mov_b32 m0, s29
	s_nop 0
	global_load_lds_dwordx4 v132, s[54:55]
	s_mov_b32 m0, s30
	s_nop 0
	global_load_lds_dwordx4 v128, s[54:55]
	s_mov_b32 m0, s22
	s_nop 0
	global_load_lds_dwordx4 v134, s[18:19]
	s_mov_b32 m0, s31
	s_nop 0
	global_load_lds_dwordx4 v130, s[18:19]
	s_waitcnt vmcnt(8)
	s_waitcnt lgkmcnt(0)
	s_barrier
	s_setprio 1
	v_mfma_f32_16x16x32_bf16 v[60:63], v[140:143], v[214:217], v[60:63]
	v_mfma_f32_16x16x32_bf16 v[36:39], v[172:175], v[222:225], v[36:39]
	v_mfma_f32_16x16x32_bf16 v[28:31], v[140:143], v[230:233], v[28:31]
	v_mfma_f32_16x16x32_bf16 v[4:7], v[172:175], v[238:241], v[4:7]
	v_mfma_f32_16x16x32_bf16 v[52:55], v[172:175], v[214:217], v[52:55]
	v_mfma_f32_16x16x32_bf16 v[44:47], v[140:143], v[222:225], v[44:47]
	v_mfma_f32_16x16x32_bf16 v[20:23], v[172:175], v[230:233], v[20:23]
	v_mfma_f32_16x16x32_bf16 v[12:15], v[140:143], v[238:241], v[12:15]
	v_mfma_f32_16x16x32_bf16 v[60:63], v[168:171], v[218:221], v[60:63]
	v_mfma_f32_16x16x32_bf16 v[36:39], v[176:179], v[226:229], v[36:39]
	v_mfma_f32_16x16x32_bf16 v[28:31], v[168:171], v[234:237], v[28:31]
	v_mfma_f32_16x16x32_bf16 v[4:7], v[176:179], v[242:245], v[4:7]
	v_mfma_f32_16x16x32_bf16 v[52:55], v[176:179], v[218:221], v[52:55]
	v_mfma_f32_16x16x32_bf16 v[44:47], v[168:171], v[226:229], v[44:47]
	v_mfma_f32_16x16x32_bf16 v[20:23], v[176:179], v[234:237], v[20:23]
	v_mfma_f32_16x16x32_bf16 v[12:15], v[168:171], v[242:245], v[12:15]
	v_mfma_f32_16x16x32_bf16 v[56:59], v[180:183], v[214:217], v[56:59]
	v_mfma_f32_16x16x32_bf16 v[32:35], v[188:191], v[222:225], v[32:35]
	v_mfma_f32_16x16x32_bf16 v[24:27], v[180:183], v[230:233], v[24:27]
	v_mfma_f32_16x16x32_bf16 v[0:3], v[188:191], v[238:241], v[0:3]
	v_mfma_f32_16x16x32_bf16 v[48:51], v[188:191], v[214:217], v[48:51]
	v_mfma_f32_16x16x32_bf16 v[40:43], v[180:183], v[222:225], v[40:43]
	v_mfma_f32_16x16x32_bf16 v[16:19], v[188:191], v[230:233], v[16:19]
	v_mfma_f32_16x16x32_bf16 v[8:11], v[180:183], v[238:241], v[8:11]
	v_mfma_f32_16x16x32_bf16 v[56:59], v[184:187], v[218:221], v[56:59]
	v_mfma_f32_16x16x32_bf16 v[32:35], v[210:213], v[226:229], v[32:35]
	v_mfma_f32_16x16x32_bf16 v[24:27], v[184:187], v[234:237], v[24:27]
	v_mfma_f32_16x16x32_bf16 v[0:3], v[210:213], v[242:245], v[0:3]
	v_mfma_f32_16x16x32_bf16 v[48:51], v[210:213], v[218:221], v[48:51]
	v_mfma_f32_16x16x32_bf16 v[40:43], v[184:187], v[226:229], v[40:43]
	v_mfma_f32_16x16x32_bf16 v[16:19], v[210:213], v[234:237], v[16:19]
	v_mfma_f32_16x16x32_bf16 v[8:11], v[184:187], v[242:245], v[8:11]
	s_setprio 0
	s_barrier
; #define PG8_STAGE(bufoff, gbase, voff) do { _Pragma("unroll") for (int _i = 0; _i < 2; ++_i) \
;         __builtin_amdgcn_global_load_lds((const unsigned*)((const char*)(gbase) + (voff)[_i]), (PG8_LAS unsigned*)(lds + (bufoff) + ldsw + _i * 8192), 16, 0, 0); } while (0)
; #define PG8_LDA(dst, b, h) do { _Pragma("unroll") for (int m = 0; m < 4; ++m) _Pragma("unroll") for (int k = 0; k < 2; ++k) dst[m][k] = *(const PG8_LAS bf16x8*)(lds + PG8_SA(b, h) + aoff + m * 2048 + k * 1024); } while (0)
; #define PG8_LDB(dst, b, h) do { _Pragma("unroll") for (int n = 0; n < 2; ++n) _Pragma("unroll") for (int k = 0; k < 2; ++k) dst[n][k] = *(const PG8_LAS bf16x8*)(lds + PG8_SB(b, h) + boff + n * 2048 + k * 1024); } while (0)
; #define PG8_MMA(ai, bj, At, Bt) do { __builtin_amdgcn_s_setprio(1); _Pragma("unroll") for (int m = 0; m < 4; ++m) _Pragma("unroll") for (int n = 0; n < 2; ++n) _Pragma("unroll") for (int k = 0; k < 2; ++k) \
;         acc[ai][bj][m][n] = __builtin_amdgcn_mfma_f32_16x16x32_bf16(Bt[n][k], At[m][k], acc[ai][bj][m][n], 0, 0, 0); __builtin_amdgcn_s_setprio(0); } while (0)
; #define PG8_WAIT_V(n) asm volatile("s_waitcnt vmcnt(" #n ")" ::: "memory")
; #define PG8_WAIT_L(n) asm volatile("s_waitcnt lgkmcnt(" #n ")" ::: "memory")
; #define PG8_BAR __builtin_amdgcn_s_barrier()
; #define PG8_SCHED __builtin_amdgcn_sched_barrier(0)
; template <class Epi, class Sched, bool ALIGN_EPI = false, bool SP2 = false>
; __device__ __forceinline__ void gemm_phase(PG8_LAS unsigned char* lds, const Gemm g, const Sched& S, const Epi& E) {
;     ...
;         for (int t = 0; t < nt; t += 2) {
;     ...
;             PG8_LDB(B0, 1, 0); PG8_LDB(B1, 1, 1); PG8_SCHED; PG8_LDA(At, 1, 0); PG8_STAGE(PG8_SA(0, 1), a2 + hstep, voffA);
;             PG8_WAIT_V(8); PG8_WAIT_L(0); PG8_BAR; PG8_MMA(0, 0, At, B0); PG8_MMA(0, 1, At, B1); PG8_BAR; PG8_SCHED;
;             PG8_LDA(At, 1, 1); PG8_STAGE(PG8_SB(1, 0), b3, voffB); PG8_STAGE(PG8_SB(1, 1), b3 + hstep, voffB); PG8_STAGE(PG8_SA(1, 0), a3, voffA);
;             PG8_WAIT_V(8); PG8_WAIT_L(0); PG8_BAR; PG8_MMA(1, 0, At, B0); PG8_MMA(1, 1, At, B1); PG8_BAR; PG8_SCHED;
;     ...
;         if constexpr (ALIGN_EPI) { if (wr == 0) PG8_BAR; }
	ds_read_b128 v[140:143], v254 offset:32768
	ds_read_b128 v[168:171], v254 offset:33792
	ds_read_b128 v[172:175], v254 offset:34816
	ds_read_b128 v[176:179], v254 offset:35840
	ds_read_b128 v[180:183], v254 offset:49152
	ds_read_b128 v[184:187], v254 offset:50176
	ds_read_b128 v[188:191], v254 offset:51200
	ds_read_b128 v[210:213], v254 offset:52224
	s_add_u32 s18, s18, 0x40000
	s_addc_u32 s19, s19, 0
	s_mov_b32 m0, s33
	ds_read_b128 v[214:217], v165 offset:32768
	ds_read_b128 v[218:221], v165 offset:33792
	ds_read_b128 v[222:225], v165 offset:34816
	ds_read_b128 v[226:229], v165 offset:35840
	ds_read_b128 v[230:233], v165 offset:36864
	ds_read_b128 v[234:237], v165 offset:37888
	ds_read_b128 v[238:241], v165 offset:38912
	ds_read_b128 v[242:245], v165 offset:39936
	global_load_lds_dwordx4 v134, s[18:19]
	s_mov_b32 m0, s34
	s_nop 0
	global_load_lds_dwordx4 v130, s[18:19]
	s_waitcnt vmcnt(8)
	s_waitcnt lgkmcnt(0)
	s_barrier
	s_setprio 1
	v_mfma_f32_16x16x32_bf16 v[124:127], v[140:143], v[214:217], v[124:127]
	v_mfma_f32_16x16x32_bf16 v[100:103], v[172:175], v[222:225], v[100:103]
	v_mfma_f32_16x16x32_bf16 v[92:95], v[140:143], v[230:233], v[92:95]
	v_mfma_f32_16x16x32_bf16 v[68:71], v[172:175], v[238:241], v[68:71]
	v_mfma_f32_16x16x32_bf16 v[116:119], v[172:175], v[214:217], v[116:119]
	v_mfma_f32_16x16x32_bf16 v[108:111], v[140:143], v[222:225], v[108:111]
	v_mfma_f32_16x16x32_bf16 v[84:87], v[172:175], v[230:233], v[84:87]
	v_mfma_f32_16x16x32_bf16 v[76:79], v[140:143], v[238:241], v[76:79]
	v_mfma_f32_16x16x32_bf16 v[124:127], v[168:171], v[218:221], v[124:127]
	v_mfma_f32_16x16x32_bf16 v[100:103], v[176:179], v[226:229], v[100:103]
	v_mfma_f32_16x16x32_bf16 v[92:95], v[168:171], v[234:237], v[92:95]
	v_mfma_f32_16x16x32_bf16 v[68:71], v[176:179], v[242:245], v[68:71]
	v_mfma_f32_16x16x32_bf16 v[116:119], v[176:179], v[218:221], v[116:119]
	v_mfma_f32_16x16x32_bf16 v[108:111], v[168:171], v[226:229], v[108:111]
	v_mfma_f32_16x16x32_bf16 v[84:87], v[176:179], v[234:237], v[84:87]
	v_mfma_f32_16x16x32_bf16 v[76:79], v[168:171], v[242:245], v[76:79]
	v_mfma_f32_16x16x32_bf16 v[120:123], v[180:183], v[214:217], v[120:123]
	v_mfma_f32_16x16x32_bf16 v[96:99], v[188:191], v[222:225], v[96:99]
	v_mfma_f32_16x16x32_bf16 v[88:91], v[180:183], v[230:233], v[88:91]
	v_mfma_f32_16x16x32_bf16 v[64:67], v[188:191], v[238:241], v[64:67]
	v_mfma_f32_16x16x32_bf16 v[112:115], v[188:191], v[214:217], v[112:115]
	v_mfma_f32_16x16x32_bf16 v[104:107], v[180:183], v[222:225], v[104:107]
	v_mfma_f32_16x16x32_bf16 v[80:83], v[188:191], v[230:233], v[80:83]
	v_mfma_f32_16x16x32_bf16 v[72:75], v[180:183], v[238:241], v[72:75]
	v_mfma_f32_16x16x32_bf16 v[120:123], v[184:187], v[218:221], v[120:123]
	v_mfma_f32_16x16x32_bf16 v[96:99], v[210:213], v[226:229], v[96:99]
	v_mfma_f32_16x16x32_bf16 v[88:91], v[184:187], v[234:237], v[88:91]
	v_mfma_f32_16x16x32_bf16 v[64:67], v[210:213], v[242:245], v[64:67]
	v_mfma_f32_16x16x32_bf16 v[112:115], v[210:213], v[218:221], v[112:115]
	v_mfma_f32_16x16x32_bf16 v[104:107], v[184:187], v[226:229], v[104:107]
	v_mfma_f32_16x16x32_bf16 v[80:83], v[210:213], v[234:237], v[80:83]
	v_mfma_f32_16x16x32_bf16 v[72:75], v[184:187], v[242:245], v[72:75]
	s_setprio 0
	s_barrier
	s_mov_b32 m0, s37
	s_add_u32 s16, s16, 0x40080
	s_addc_u32 s17, s17, 0
	ds_read_b128 v[214:217], v165 offset:49152
	ds_read_b128 v[218:221], v165 offset:50176
	ds_read_b128 v[222:225], v165 offset:51200
	ds_read_b128 v[226:229], v165 offset:52224
	ds_read_b128 v[230:233], v165 offset:53248
	ds_read_b128 v[234:237], v165 offset:54272
	ds_read_b128 v[238:241], v165 offset:55296
	ds_read_b128 v[242:245], v165 offset:56320
	s_add_u32 s98, s16, 0xfffc0000
	s_addc_u32 s99, s17, -1
	global_load_lds_dwordx4 v132, s[98:99]
	s_mov_b32 m0, s38
	s_nop 0
	global_load_lds_dwordx4 v128, s[98:99]
	s_mov_b32 m0, s41
	s_nop 0
	global_load_lds_dwordx4 v132, s[16:17]
	s_mov_b32 m0, s42
	s_nop 0
	global_load_lds_dwordx4 v128, s[16:17]
	s_mov_b32 m0, s39
	s_nop 0
	s_add_u32 s100, s18, 0xfffc0080
	s_addc_u32 s101, s19, -1
	global_load_lds_dwordx4 v134, s[100:101]
	s_mov_b32 m0, s40
	s_nop 0
	global_load_lds_dwordx4 v130, s[100:101]
	s_waitcnt vmcnt(8)
	s_waitcnt lgkmcnt(0)
	s_barrier
	s_setprio 1
	v_mfma_f32_16x16x32_bf16 v[60:63], v[140:143], v[214:217], v[60:63]
	v_mfma_f32_16x16x32_bf16 v[36:39], v[172:175], v[222:225], v[36:39]
	v_mfma_f32_16x16x32_bf16 v[28:31], v[140:143], v[230:233], v[28:31]
	v_mfma_f32_16x16x32_bf16 v[4:7], v[172:175], v[238:241], v[4:7]
	v_mfma_f32_16x16x32_bf16 v[52:55], v[172:175], v[214:217], v[52:55]
	v_mfma_f32_16x16x32_bf16 v[44:47], v[140:143], v[222:225], v[44:47]
	v_mfma_f32_16x16x32_bf16 v[20:23], v[172:175], v[230:233], v[20:23]
	v_mfma_f32_16x16x32_bf16 v[12:15], v[140:143], v[238:241], v[12:15]
	v_mfma_f32_16x16x32_bf16 v[60:63], v[168:171], v[218:221], v[60:63]
	v_mfma_f32_16x16x32_bf16 v[36:39], v[176:179], v[226:229], v[36:39]
	v_mfma_f32_16x16x32_bf16 v[28:31], v[168:171], v[234:237], v[28:31]
	v_mfma_f32_16x16x32_bf16 v[4:7], v[176:179], v[242:245], v[4:7]
	v_mfma_f32_16x16x32_bf16 v[52:55], v[176:179], v[218:221], v[52:55]
	v_mfma_f32_16x16x32_bf16 v[44:47], v[168:171], v[226:229], v[44:47]
	v_mfma_f32_16x16x32_bf16 v[20:23], v[176:179], v[234:237], v[20:23]
	v_mfma_f32_16x16x32_bf16 v[12:15], v[168:171], v[242:245], v[12:15]
	v_mfma_f32_16x16x32_bf16 v[56:59], v[180:183], v[214:217], v[56:59]
	v_mfma_f32_16x16x32_bf16 v[32:35], v[188:191], v[222:225], v[32:35]
	v_mfma_f32_16x16x32_bf16 v[24:27], v[180:183], v[230:233], v[24:27]
	v_mfma_f32_16x16x32_bf16 v[0:3], v[188:191], v[238:241], v[0:3]
	v_mfma_f32_16x16x32_bf16 v[48:51], v[188:191], v[214:217], v[48:51]
	v_mfma_f32_16x16x32_bf16 v[40:43], v[180:183], v[222:225], v[40:43]
	v_mfma_f32_16x16x32_bf16 v[16:19], v[188:191], v[230:233], v[16:19]
	v_mfma_f32_16x16x32_bf16 v[8:11], v[180:183], v[238:241], v[8:11]
	v_mfma_f32_16x16x32_bf16 v[56:59], v[184:187], v[218:221], v[56:59]
	v_mfma_f32_16x16x32_bf16 v[32:35], v[210:213], v[226:229], v[32:35]
	v_mfma_f32_16x16x32_bf16 v[24:27], v[184:187], v[234:237], v[24:27]
	v_mfma_f32_16x16x32_bf16 v[0:3], v[210:213], v[242:245], v[0:3]
	v_mfma_f32_16x16x32_bf16 v[48:51], v[210:213], v[218:221], v[48:51]
	v_mfma_f32_16x16x32_bf16 v[40:43], v[184:187], v[226:229], v[40:43]
	v_mfma_f32_16x16x32_bf16 v[16:19], v[210:213], v[234:237], v[16:19]
	v_mfma_f32_16x16x32_bf16 v[8:11], v[184:187], v[242:245], v[8:11]
	s_setprio 0
	s_barrier
	s_add_i32 s53, s53, 2
	s_add_u32 s14, s14, 0x100
	s_addc_u32 s15, s15, 0
	s_add_u32 s51, s51, 0x100
	s_addc_u32 s52, s52, 0
	s_cmp_gt_u32 s53, 13
	s_cbranch_scc0 .LBB0_446
	s_and_b64 vcc, exec, s[2:3]
	s_cbranch_vccz .LBB0_449
	s_barrier

; #define PG8_STAGE(bufoff, gbase, voff) do { _Pragma("unroll") for (int _i = 0; _i < 2; ++_i) \
;         __builtin_amdgcn_global_load_lds((const unsigned*)((const char*)(gbase) + (voff)[_i]), (PG8_LAS unsigned*)(lds + (bufoff) + ldsw + _i * 8192), 16, 0, 0); } while (0)
; #define PG8_LDA(dst, b, h) do { _Pragma("unroll") for (int m = 0; m < 4; ++m) _Pragma("unroll") for (int k = 0; k < 2; ++k) dst[m][k] = *(const PG8_LAS bf16x8*)(lds + PG8_SA(b, h) + aoff + m * 2048 + k * 1024); } while (0)
; #define PG8_LDB(dst, b, h) do { _Pragma("unroll") for (int n = 0; n < 2; ++n) _Pragma("unroll") for (int k = 0; k < 2; ++k) dst[n][k] = *(const PG8_LAS bf16x8*)(lds + PG8_SB(b, h) + boff + n * 2048 + k * 1024); } while (0)
; #define PG8_MMA(ai, bj, At, Bt) do { __builtin_amdgcn_s_setprio(1); _Pragma("unroll") for (int m = 0; m < 4; ++m) _Pragma("unroll") for (int n = 0; n < 2; ++n) _Pragma("unroll") for (int k = 0; k < 2; ++k) \
;         acc[ai][bj][m][n] = __builtin_amdgcn_mfma_f32_16x16x32_bf16(Bt[n][k], At[m][k], acc[ai][bj][m][n], 0, 0, 0); __builtin_amdgcn_s_setprio(0); } while (0)
; #define PG8_WAIT_V(n) asm volatile("s_waitcnt vmcnt(" #n ")" ::: "memory")
; #define PG8_WAIT_L(n) asm volatile("s_waitcnt lgkmcnt(" #n ")" ::: "memory")
; #define PG8_BAR __builtin_amdgcn_s_barrier()
; #define PG8_SCHED __builtin_amdgcn_sched_barrier(0)
; template <class Epi, class Sched, bool ALIGN_EPI = false, bool SP2 = false>
; __device__ __forceinline__ void gemm_phase(PG8_LAS unsigned char* lds, const Gemm g, const Sched& S, const Epi& E) {
;     ...
;             PG8_LDB(B0, 0, 0); PG8_LDB(B1, 0, 1); PG8_SCHED; PG8_LDA(At, 0, 0); PG8_STAGE(PG8_SA(1, 1), a1 + hstep, voffA);
;             PG8_WAIT_V(8); PG8_WAIT_L(0); PG8_BAR; PG8_MMA(0, 0, At, B0); PG8_MMA(0, 1, At, B1); PG8_BAR; PG8_SCHED;
;             PG8_LDA(At, 0, 1); PG8_STAGE(PG8_SB(0, 0), b2, voffB); PG8_STAGE(PG8_SB(0, 1), b2 + hstep, voffB); PG8_STAGE(PG8_SA(0, 0), a2, voffA);
;             PG8_WAIT_V(8); PG8_WAIT_L(0); PG8_BAR; PG8_MMA(1, 0, At, B0); PG8_MMA(1, 1, At, B1); PG8_BAR; PG8_SCHED;
.Ldn_peel:
	ds_read_b128 v[128:131], v254
	ds_read_b128 v[132:135], v254 offset:1024
	ds_read_b128 v[136:139], v254 offset:2048
	ds_read_b128 v[140:143], v254 offset:3072
	ds_read_b128 v[174:177], v254 offset:16384
	ds_read_b128 v[184:187], v254 offset:17408
	ds_read_b128 v[188:191], v254 offset:18432
	ds_read_b128 v[210:213], v254 offset:19456
	s_add_u32 s2, s0, 0x100
	s_addc_u32 s3, s1, 0
	s_cmp_eq_u32 s13, 40
	s_cselect_b32 s7, s27, s3
	s_cselect_b32 s6, s26, s2
	s_cselect_b32 s5, s37, s11
	s_cselect_b32 s4, s36, s10
	s_add_i32 m0, s29, 0xc000
	ds_read_b128 v[214:217], v181
	ds_read_b128 v[218:221], v181 offset:1024
	ds_read_b128 v[222:225], v181 offset:2048
	ds_read_b128 v[226:229], v181 offset:3072
	ds_read_b128 v[230:233], v181 offset:4096
	ds_read_b128 v[234:237], v181 offset:5120
	ds_read_b128 v[238:241], v181 offset:6144
	ds_read_b128 v[242:245], v181 offset:7168
	global_load_lds_dwordx4 v170, s[0:1]
	s_add_i32 m0, s29, 0xe000
	s_nop 0
	global_load_lds_dwordx4 v172, s[0:1]
	s_waitcnt vmcnt(8)
	s_waitcnt lgkmcnt(0)
	s_barrier
	s_setprio 1
	v_mfma_f32_16x16x32_bf16 v[124:127], v[128:131], v[214:217], 0
	v_mfma_f32_16x16x32_bf16 v[104:107], v[136:139], v[222:225], 0
	v_mfma_f32_16x16x32_bf16 v[92:95], v[128:131], v[230:233], 0
	v_mfma_f32_16x16x32_bf16 v[72:75], v[136:139], v[238:241], 0
	v_mfma_f32_16x16x32_bf16 v[120:123], v[136:139], v[214:217], 0
	v_mfma_f32_16x16x32_bf16 v[108:111], v[128:131], v[222:225], 0
	v_mfma_f32_16x16x32_bf16 v[88:91], v[136:139], v[230:233], 0
	v_mfma_f32_16x16x32_bf16 v[76:79], v[128:131], v[238:241], 0
	v_mfma_f32_16x16x32_bf16 v[124:127], v[132:135], v[218:221], v[124:127]
	v_mfma_f32_16x16x32_bf16 v[104:107], v[140:143], v[226:229], v[104:107]
	v_mfma_f32_16x16x32_bf16 v[92:95], v[132:135], v[234:237], v[92:95]
	v_mfma_f32_16x16x32_bf16 v[72:75], v[140:143], v[242:245], v[72:75]
	v_mfma_f32_16x16x32_bf16 v[120:123], v[140:143], v[218:221], v[120:123]
	v_mfma_f32_16x16x32_bf16 v[108:111], v[132:135], v[226:229], v[108:111]
	v_mfma_f32_16x16x32_bf16 v[88:91], v[140:143], v[234:237], v[88:91]
	v_mfma_f32_16x16x32_bf16 v[76:79], v[132:135], v[242:245], v[76:79]
	v_mfma_f32_16x16x32_bf16 v[116:119], v[174:177], v[214:217], 0
	v_mfma_f32_16x16x32_bf16 v[96:99], v[188:191], v[222:225], 0
	v_mfma_f32_16x16x32_bf16 v[84:87], v[174:177], v[230:233], 0
	v_mfma_f32_16x16x32_bf16 v[64:67], v[188:191], v[238:241], 0
	v_mfma_f32_16x16x32_bf16 v[112:115], v[188:191], v[214:217], 0
	v_mfma_f32_16x16x32_bf16 v[100:103], v[174:177], v[222:225], 0
	v_mfma_f32_16x16x32_bf16 v[80:83], v[188:191], v[230:233], 0
	v_mfma_f32_16x16x32_bf16 v[68:71], v[174:177], v[238:241], 0
	v_mfma_f32_16x16x32_bf16 v[116:119], v[184:187], v[218:221], v[116:119]
	v_mfma_f32_16x16x32_bf16 v[96:99], v[210:213], v[226:229], v[96:99]
	v_mfma_f32_16x16x32_bf16 v[84:87], v[184:187], v[234:237], v[84:87]
	v_mfma_f32_16x16x32_bf16 v[64:67], v[210:213], v[242:245], v[64:67]
	v_mfma_f32_16x16x32_bf16 v[112:115], v[210:213], v[218:221], v[112:115]
	v_mfma_f32_16x16x32_bf16 v[100:103], v[184:187], v[226:229], v[100:103]
	v_mfma_f32_16x16x32_bf16 v[80:83], v[210:213], v[234:237], v[80:83]
	v_mfma_f32_16x16x32_bf16 v[68:71], v[184:187], v[242:245], v[68:71]
	s_setprio 0
	s_barrier
	s_mov_b32 m0, s35
	s_add_u32 s0, s4, 0xb0000
	s_addc_u32 s1, s5, 0
	ds_read_b128 v[214:217], v181 offset:16384
	ds_read_b128 v[218:221], v181 offset:17408
	ds_read_b128 v[222:225], v181 offset:18432
	ds_read_b128 v[226:229], v181 offset:19456
	ds_read_b128 v[230:233], v181 offset:20480
	ds_read_b128 v[234:237], v181 offset:21504
	ds_read_b128 v[238:241], v181 offset:22528
	ds_read_b128 v[242:245], v181 offset:23552
	global_load_lds_dwordx4 v166, s[4:5]
	s_mov_b32 m0, s38
	s_nop 0
	global_load_lds_dwordx4 v162, s[4:5]
	s_mov_b32 m0, s39
	s_nop 0
	global_load_lds_dwordx4 v166, s[0:1]
	s_mov_b32 m0, s40
	s_nop 0
	global_load_lds_dwordx4 v162, s[0:1]
	s_mov_b32 m0, s29
	s_nop 0
	global_load_lds_dwordx4 v168, s[6:7]
	s_mov_b32 m0, s41
	s_nop 0
	global_load_lds_dwordx4 v164, s[6:7]
	s_waitcnt vmcnt(8)
	s_waitcnt lgkmcnt(0)
	s_barrier
	s_setprio 1
	v_mfma_f32_16x16x32_bf16 v[60:63], v[128:131], v[214:217], 0
	v_mfma_f32_16x16x32_bf16 v[40:43], v[136:139], v[222:225], 0
	v_mfma_f32_16x16x32_bf16 v[28:31], v[128:131], v[230:233], 0
	v_mfma_f32_16x16x32_bf16 v[8:11], v[136:139], v[238:241], 0
	v_mfma_f32_16x16x32_bf16 v[56:59], v[136:139], v[214:217], 0
	v_mfma_f32_16x16x32_bf16 v[44:47], v[128:131], v[222:225], 0
	v_mfma_f32_16x16x32_bf16 v[24:27], v[136:139], v[230:233], 0
	v_mfma_f32_16x16x32_bf16 v[12:15], v[128:131], v[238:241], 0
	v_mfma_f32_16x16x32_bf16 v[60:63], v[132:135], v[218:221], v[60:63]
	v_mfma_f32_16x16x32_bf16 v[40:43], v[140:143], v[226:229], v[40:43]
	v_mfma_f32_16x16x32_bf16 v[28:31], v[132:135], v[234:237], v[28:31]
	v_mfma_f32_16x16x32_bf16 v[8:11], v[140:143], v[242:245], v[8:11]
	v_mfma_f32_16x16x32_bf16 v[56:59], v[140:143], v[218:221], v[56:59]
	v_mfma_f32_16x16x32_bf16 v[44:47], v[132:135], v[226:229], v[44:47]
	v_mfma_f32_16x16x32_bf16 v[24:27], v[140:143], v[234:237], v[24:27]
	v_mfma_f32_16x16x32_bf16 v[12:15], v[132:135], v[242:245], v[12:15]
	v_mfma_f32_16x16x32_bf16 v[52:55], v[174:177], v[214:217], 0
	v_mfma_f32_16x16x32_bf16 v[32:35], v[188:191], v[222:225], 0
	v_mfma_f32_16x16x32_bf16 v[20:23], v[174:177], v[230:233], 0
	v_mfma_f32_16x16x32_bf16 v[0:3], v[188:191], v[238:241], 0
	v_mfma_f32_16x16x32_bf16 v[48:51], v[188:191], v[214:217], 0
	v_mfma_f32_16x16x32_bf16 v[36:39], v[174:177], v[222:225], 0
	v_mfma_f32_16x16x32_bf16 v[16:19], v[188:191], v[230:233], 0
	v_mfma_f32_16x16x32_bf16 v[4:7], v[174:177], v[238:241], 0
	v_mfma_f32_16x16x32_bf16 v[52:55], v[184:187], v[218:221], v[52:55]
	v_mfma_f32_16x16x32_bf16 v[32:35], v[210:213], v[226:229], v[32:35]
	v_mfma_f32_16x16x32_bf16 v[20:23], v[184:187], v[234:237], v[20:23]
	v_mfma_f32_16x16x32_bf16 v[0:3], v[210:213], v[242:245], v[0:3]
	v_mfma_f32_16x16x32_bf16 v[48:51], v[210:213], v[218:221], v[48:51]
	v_mfma_f32_16x16x32_bf16 v[36:39], v[184:187], v[226:229], v[36:39]
	v_mfma_f32_16x16x32_bf16 v[16:19], v[210:213], v[234:237], v[16:19]
	v_mfma_f32_16x16x32_bf16 v[4:7], v[184:187], v[242:245], v[4:7]
	s_setprio 0
	s_barrier
; #define PG8_STAGE(bufoff, gbase, voff) do { _Pragma("unroll") for (int _i = 0; _i < 2; ++_i) \
;         __builtin_amdgcn_global_load_lds((const unsigned*)((const char*)(gbase) + (voff)[_i]), (PG8_LAS unsigned*)(lds + (bufoff) + ldsw + _i * 8192), 16, 0, 0); } while (0)
; #define PG8_LDA(dst, b, h) do { _Pragma("unroll") for (int m = 0; m < 4; ++m) _Pragma("unroll") for (int k = 0; k < 2; ++k) dst[m][k] = *(const PG8_LAS bf16x8*)(lds + PG8_SA(b, h) + aoff + m * 2048 + k * 1024); } while (0)
; #define PG8_LDB(dst, b, h) do { _Pragma("unroll") for (int n = 0; n < 2; ++n) _Pragma("unroll") for (int k = 0; k < 2; ++k) dst[n][k] = *(const PG8_LAS bf16x8*)(lds + PG8_SB(b, h) + boff + n * 2048 + k * 1024); } while (0)
; #define PG8_MMA(ai, bj, At, Bt) do { __builtin_amdgcn_s_setprio(1); _Pragma("unroll") for (int m = 0; m < 4; ++m) _Pragma("unroll") for (int n = 0; n < 2; ++n) _Pragma("unroll") for (int k = 0; k < 2; ++k) \
;         acc[ai][bj][m][n] = __builtin_amdgcn_mfma_f32_16x16x32_bf16(Bt[n][k], At[m][k], acc[ai][bj][m][n], 0, 0, 0); __builtin_amdgcn_s_setprio(0); } while (0)
; #define PG8_WAIT_V(n) asm volatile("s_waitcnt vmcnt(" #n ")" ::: "memory")
; #define PG8_WAIT_L(n) asm volatile("s_waitcnt lgkmcnt(" #n ")" ::: "memory")
; #define PG8_BAR __builtin_amdgcn_s_barrier()
; #define PG8_SCHED __builtin_amdgcn_sched_barrier(0)
; template <class Epi, class Sched, bool ALIGN_EPI = false, bool SP2 = false>
; __device__ __forceinline__ void gemm_phase(PG8_LAS unsigned char* lds, const Gemm g, const Sched& S, const Epi& E) {
;     ...
;         for (int t = 0; t < nt; t += 2) {
;     ...
;             PG8_LDB(B0, 1, 0); PG8_LDB(B1, 1, 1); PG8_SCHED; PG8_LDA(At, 1, 0); PG8_STAGE(PG8_SA(0, 1), a2 + hstep, voffA);
;             PG8_WAIT_V(8); PG8_WAIT_L(0); PG8_BAR; PG8_MMA(0, 0, At, B0); PG8_MMA(0, 1, At, B1); PG8_BAR; PG8_SCHED;
;             PG8_LDA(At, 1, 1); PG8_STAGE(PG8_SB(1, 0), b3, voffB); PG8_STAGE(PG8_SB(1, 1), b3 + hstep, voffB); PG8_STAGE(PG8_SA(1, 0), a3, voffA);
;             PG8_WAIT_V(8); PG8_WAIT_L(0); PG8_BAR; PG8_MMA(1, 0, At, B0); PG8_MMA(1, 1, At, B1); PG8_BAR; PG8_SCHED;
	ds_read_b128 v[128:131], v254 offset:32768
	ds_read_b128 v[132:135], v254 offset:33792
	ds_read_b128 v[136:139], v254 offset:34816
	ds_read_b128 v[140:143], v254 offset:35840
	ds_read_b128 v[174:177], v254 offset:49152
	ds_read_b128 v[184:187], v254 offset:50176
	ds_read_b128 v[188:191], v254 offset:51200
	ds_read_b128 v[210:213], v254 offset:52224
	s_add_u32 s0, s6, 0xb0000
	s_addc_u32 s1, s7, 0
	s_mov_b32 m0, s42
	ds_read_b128 v[214:217], v181 offset:32768
	ds_read_b128 v[218:221], v181 offset:33792
	ds_read_b128 v[222:225], v181 offset:34816
	ds_read_b128 v[226:229], v181 offset:35840
	ds_read_b128 v[230:233], v181 offset:36864
	ds_read_b128 v[234:237], v181 offset:37888
	ds_read_b128 v[238:241], v181 offset:38912
	ds_read_b128 v[242:245], v181 offset:39936
	global_load_lds_dwordx4 v168, s[0:1]
	s_mov_b32 m0, s43
	s_nop 0
	global_load_lds_dwordx4 v164, s[0:1]
	s_waitcnt vmcnt(8)
	s_waitcnt lgkmcnt(0)
	s_barrier
	s_setprio 1
	v_mfma_f32_16x16x32_bf16 v[124:127], v[128:131], v[214:217], v[124:127]
	v_mfma_f32_16x16x32_bf16 v[104:107], v[136:139], v[222:225], v[104:107]
	v_mfma_f32_16x16x32_bf16 v[92:95], v[128:131], v[230:233], v[92:95]
	v_mfma_f32_16x16x32_bf16 v[72:75], v[136:139], v[238:241], v[72:75]
	v_mfma_f32_16x16x32_bf16 v[120:123], v[136:139], v[214:217], v[120:123]
	v_mfma_f32_16x16x32_bf16 v[108:111], v[128:131], v[222:225], v[108:111]
	v_mfma_f32_16x16x32_bf16 v[88:91], v[136:139], v[230:233], v[88:91]
	v_mfma_f32_16x16x32_bf16 v[76:79], v[128:131], v[238:241], v[76:79]
	v_mfma_f32_16x16x32_bf16 v[124:127], v[132:135], v[218:221], v[124:127]
	v_mfma_f32_16x16x32_bf16 v[104:107], v[140:143], v[226:229], v[104:107]
	v_mfma_f32_16x16x32_bf16 v[92:95], v[132:135], v[234:237], v[92:95]
	v_mfma_f32_16x16x32_bf16 v[72:75], v[140:143], v[242:245], v[72:75]
	v_mfma_f32_16x16x32_bf16 v[120:123], v[140:143], v[218:221], v[120:123]
	v_mfma_f32_16x16x32_bf16 v[108:111], v[132:135], v[226:229], v[108:111]
	v_mfma_f32_16x16x32_bf16 v[88:91], v[140:143], v[234:237], v[88:91]
	v_mfma_f32_16x16x32_bf16 v[76:79], v[132:135], v[242:245], v[76:79]
	v_mfma_f32_16x16x32_bf16 v[116:119], v[174:177], v[214:217], v[116:119]
	v_mfma_f32_16x16x32_bf16 v[96:99], v[188:191], v[222:225], v[96:99]
	v_mfma_f32_16x16x32_bf16 v[84:87], v[174:177], v[230:233], v[84:87]
	v_mfma_f32_16x16x32_bf16 v[64:67], v[188:191], v[238:241], v[64:67]
	v_mfma_f32_16x16x32_bf16 v[112:115], v[188:191], v[214:217], v[112:115]
	v_mfma_f32_16x16x32_bf16 v[100:103], v[174:177], v[222:225], v[100:103]
	v_mfma_f32_16x16x32_bf16 v[80:83], v[188:191], v[230:233], v[80:83]
	v_mfma_f32_16x16x32_bf16 v[68:71], v[174:177], v[238:241], v[68:71]
	v_mfma_f32_16x16x32_bf16 v[116:119], v[184:187], v[218:221], v[116:119]
	v_mfma_f32_16x16x32_bf16 v[96:99], v[210:213], v[226:229], v[96:99]
	v_mfma_f32_16x16x32_bf16 v[84:87], v[184:187], v[234:237], v[84:87]
	v_mfma_f32_16x16x32_bf16 v[64:67], v[210:213], v[242:245], v[64:67]
	v_mfma_f32_16x16x32_bf16 v[112:115], v[210:213], v[218:221], v[112:115]
	v_mfma_f32_16x16x32_bf16 v[100:103], v[184:187], v[226:229], v[100:103]
	v_mfma_f32_16x16x32_bf16 v[80:83], v[210:213], v[234:237], v[80:83]
	v_mfma_f32_16x16x32_bf16 v[68:71], v[184:187], v[242:245], v[68:71]
	s_setprio 0
	s_barrier
	s_mov_b32 m0, s47
	s_add_u32 s0, s4, 0xb0080
	s_addc_u32 s1, s5, 0
	ds_read_b128 v[214:217], v181 offset:49152
	ds_read_b128 v[218:221], v181 offset:50176
	ds_read_b128 v[222:225], v181 offset:51200
	ds_read_b128 v[226:229], v181 offset:52224
	ds_read_b128 v[230:233], v181 offset:53248
	ds_read_b128 v[234:237], v181 offset:54272
	ds_read_b128 v[238:241], v181 offset:55296
	ds_read_b128 v[242:245], v181 offset:56320
	s_add_u32 s98, s4, 0x80
	s_addc_u32 s99, s5, 0
	global_load_lds_dwordx4 v166, s[98:99]
	s_mov_b32 m0, s48
	s_nop 0
	global_load_lds_dwordx4 v162, s[98:99]
	s_mov_b32 m0, s51
	s_nop 0
	global_load_lds_dwordx4 v166, s[0:1]
	s_mov_b32 m0, s52
	s_nop 0
	global_load_lds_dwordx4 v162, s[0:1]
	s_mov_b32 m0, s49
	s_nop 0
	s_add_u32 s100, s6, 0x80
	s_addc_u32 s101, s7, 0
	global_load_lds_dwordx4 v168, s[100:101]
	s_mov_b32 m0, s50
	s_nop 0
	global_load_lds_dwordx4 v164, s[100:101]
	s_waitcnt vmcnt(8)
	s_waitcnt lgkmcnt(0)
	s_barrier
	s_setprio 1
	v_mfma_f32_16x16x32_bf16 v[60:63], v[128:131], v[214:217], v[60:63]
	v_mfma_f32_16x16x32_bf16 v[40:43], v[136:139], v[222:225], v[40:43]
	v_mfma_f32_16x16x32_bf16 v[28:31], v[128:131], v[230:233], v[28:31]
	v_mfma_f32_16x16x32_bf16 v[8:11], v[136:139], v[238:241], v[8:11]
	v_mfma_f32_16x16x32_bf16 v[56:59], v[136:139], v[214:217], v[56:59]
	v_mfma_f32_16x16x32_bf16 v[44:47], v[128:131], v[222:225], v[44:47]
	v_mfma_f32_16x16x32_bf16 v[24:27], v[136:139], v[230:233], v[24:27]
	v_mfma_f32_16x16x32_bf16 v[12:15], v[128:131], v[238:241], v[12:15]
	v_mfma_f32_16x16x32_bf16 v[60:63], v[132:135], v[218:221], v[60:63]
	v_mfma_f32_16x16x32_bf16 v[40:43], v[140:143], v[226:229], v[40:43]
	v_mfma_f32_16x16x32_bf16 v[28:31], v[132:135], v[234:237], v[28:31]
	v_mfma_f32_16x16x32_bf16 v[8:11], v[140:143], v[242:245], v[8:11]
	v_mfma_f32_16x16x32_bf16 v[56:59], v[140:143], v[218:221], v[56:59]
	v_mfma_f32_16x16x32_bf16 v[44:47], v[132:135], v[226:229], v[44:47]
	v_mfma_f32_16x16x32_bf16 v[24:27], v[140:143], v[234:237], v[24:27]
	v_mfma_f32_16x16x32_bf16 v[12:15], v[132:135], v[242:245], v[12:15]
	v_mfma_f32_16x16x32_bf16 v[52:55], v[174:177], v[214:217], v[52:55]
	v_mfma_f32_16x16x32_bf16 v[32:35], v[188:191], v[222:225], v[32:35]
	v_mfma_f32_16x16x32_bf16 v[20:23], v[174:177], v[230:233], v[20:23]
	v_mfma_f32_16x16x32_bf16 v[0:3], v[188:191], v[238:241], v[0:3]
	v_mfma_f32_16x16x32_bf16 v[48:51], v[188:191], v[214:217], v[48:51]
	v_mfma_f32_16x16x32_bf16 v[36:39], v[174:177], v[222:225], v[36:39]
	v_mfma_f32_16x16x32_bf16 v[16:19], v[188:191], v[230:233], v[16:19]
	v_mfma_f32_16x16x32_bf16 v[4:7], v[174:177], v[238:241], v[4:7]
	v_mfma_f32_16x16x32_bf16 v[52:55], v[184:187], v[218:221], v[52:55]
	v_mfma_f32_16x16x32_bf16 v[32:35], v[210:213], v[226:229], v[32:35]
	v_mfma_f32_16x16x32_bf16 v[20:23], v[184:187], v[234:237], v[20:23]
	v_mfma_f32_16x16x32_bf16 v[0:3], v[210:213], v[242:245], v[0:3]
	v_mfma_f32_16x16x32_bf16 v[48:51], v[210:213], v[218:221], v[48:51]
	v_mfma_f32_16x16x32_bf16 v[36:39], v[184:187], v[226:229], v[36:39]
	v_mfma_f32_16x16x32_bf16 v[16:19], v[210:213], v[234:237], v[16:19]
	v_mfma_f32_16x16x32_bf16 v[4:7], v[184:187], v[242:245], v[4:7]
	s_setprio 0
	s_barrier
	s_add_i32 s13, s13, 2
	s_add_u32 s10, s10, 0x100
	s_addc_u32 s11, s11, 0
	s_cmp_gt_u32 s13, 41
	s_mov_b64 s[0:1], s[2:3]
; #define PG8_STAGE(bufoff, gbase, voff) do { _Pragma("unroll") for (int _i = 0; _i < 2; ++_i) \
;         __builtin_amdgcn_global_load_lds((const unsigned*)((const char*)(gbase) + (voff)[_i]), (PG8_LAS unsigned*)(lds + (bufoff) + ldsw + _i * 8192), 16, 0, 0); } while (0)
; #define PG8_LDA(dst, b, h) do { _Pragma("unroll") for (int m = 0; m < 4; ++m) _Pragma("unroll") for (int k = 0; k < 2; ++k) dst[m][k] = *(const PG8_LAS bf16x8*)(lds + PG8_SA(b, h) + aoff + m * 2048 + k * 1024); } while (0)
; #define PG8_LDB(dst, b, h) do { _Pragma("unroll") for (int n = 0; n < 2; ++n) _Pragma("unroll") for (int k = 0; k < 2; ++k) dst[n][k] = *(const PG8_LAS bf16x8*)(lds + PG8_SB(b, h) + boff + n * 2048 + k * 1024); } while (0)
; #define PG8_MMA(ai, bj, At, Bt) do { __builtin_amdgcn_s_setprio(1); _Pragma("unroll") for (int m = 0; m < 4; ++m) _Pragma("unroll") for (int n = 0; n < 2; ++n) _Pragma("unroll") for (int k = 0; k < 2; ++k) \
;         acc[ai][bj][m][n] = __builtin_amdgcn_mfma_f32_16x16x32_bf16(Bt[n][k], At[m][k], acc[ai][bj][m][n], 0, 0, 0); __builtin_amdgcn_s_setprio(0); } while (0)
; #define PG8_WAIT_V(n) asm volatile("s_waitcnt vmcnt(" #n ")" ::: "memory")
; #define PG8_WAIT_L(n) asm volatile("s_waitcnt lgkmcnt(" #n ")" ::: "memory")
; #define PG8_BAR __builtin_amdgcn_s_barrier()
; #define PG8_SCHED __builtin_amdgcn_sched_barrier(0)
; template <class Epi, class Sched, bool ALIGN_EPI = false, bool SP2 = false>
; __device__ __forceinline__ void gemm_phase(PG8_LAS unsigned char* lds, const Gemm g, const Sched& S, const Epi& E) {
;     ...
;             PG8_LDB(B0, 0, 0); PG8_LDB(B1, 0, 1); PG8_SCHED; PG8_LDA(At, 0, 0); PG8_STAGE(PG8_SA(1, 1), a1 + hstep, voffA);
;             PG8_WAIT_V(8); PG8_WAIT_L(0); PG8_BAR; PG8_MMA(0, 0, At, B0); PG8_MMA(0, 1, At, B1); PG8_BAR; PG8_SCHED;
;             PG8_LDA(At, 0, 1); PG8_STAGE(PG8_SB(0, 0), b2, voffB); PG8_STAGE(PG8_SB(0, 1), b2 + hstep, voffB); PG8_STAGE(PG8_SA(0, 0), a2, voffA);
;             PG8_WAIT_V(8); PG8_WAIT_L(0); PG8_BAR; PG8_MMA(1, 0, At, B0); PG8_MMA(1, 1, At, B1); PG8_BAR; PG8_SCHED;
.LBB0_545:
	ds_read_b128 v[128:131], v254
	ds_read_b128 v[132:135], v254 offset:1024
	ds_read_b128 v[136:139], v254 offset:2048
	ds_read_b128 v[140:143], v254 offset:3072
	ds_read_b128 v[174:177], v254 offset:16384
	ds_read_b128 v[184:187], v254 offset:17408
	ds_read_b128 v[188:191], v254 offset:18432
	ds_read_b128 v[210:213], v254 offset:19456
	s_add_u32 s2, s0, 0x100
	s_addc_u32 s3, s1, 0
	s_cmp_eq_u32 s13, 40
	s_cselect_b32 s7, s27, s3
	s_cselect_b32 s6, s26, s2
	s_cselect_b32 s5, s37, s11
	s_cselect_b32 s4, s36, s10
	s_add_i32 m0, s29, 0xc000
	ds_read_b128 v[214:217], v181
	ds_read_b128 v[218:221], v181 offset:1024
	ds_read_b128 v[222:225], v181 offset:2048
	ds_read_b128 v[226:229], v181 offset:3072
	ds_read_b128 v[230:233], v181 offset:4096
	ds_read_b128 v[234:237], v181 offset:5120
	ds_read_b128 v[238:241], v181 offset:6144
	ds_read_b128 v[242:245], v181 offset:7168
	global_load_lds_dwordx4 v170, s[0:1]
	s_add_i32 m0, s29, 0xe000
	s_nop 0
	global_load_lds_dwordx4 v172, s[0:1]
	s_waitcnt vmcnt(8)
	s_waitcnt lgkmcnt(0)
	s_barrier
	s_setprio 1
	v_mfma_f32_16x16x32_bf16 v[124:127], v[128:131], v[214:217], v[124:127]
	v_mfma_f32_16x16x32_bf16 v[104:107], v[136:139], v[222:225], v[104:107]
	v_mfma_f32_16x16x32_bf16 v[92:95], v[128:131], v[230:233], v[92:95]
	v_mfma_f32_16x16x32_bf16 v[72:75], v[136:139], v[238:241], v[72:75]
	v_mfma_f32_16x16x32_bf16 v[120:123], v[136:139], v[214:217], v[120:123]
	v_mfma_f32_16x16x32_bf16 v[108:111], v[128:131], v[222:225], v[108:111]
	v_mfma_f32_16x16x32_bf16 v[88:91], v[136:139], v[230:233], v[88:91]
	v_mfma_f32_16x16x32_bf16 v[76:79], v[128:131], v[238:241], v[76:79]
	v_mfma_f32_16x16x32_bf16 v[124:127], v[132:135], v[218:221], v[124:127]
	v_mfma_f32_16x16x32_bf16 v[104:107], v[140:143], v[226:229], v[104:107]
	v_mfma_f32_16x16x32_bf16 v[92:95], v[132:135], v[234:237], v[92:95]
	v_mfma_f32_16x16x32_bf16 v[72:75], v[140:143], v[242:245], v[72:75]
	v_mfma_f32_16x16x32_bf16 v[120:123], v[140:143], v[218:221], v[120:123]
	v_mfma_f32_16x16x32_bf16 v[108:111], v[132:135], v[226:229], v[108:111]
	v_mfma_f32_16x16x32_bf16 v[88:91], v[140:143], v[234:237], v[88:91]
	v_mfma_f32_16x16x32_bf16 v[76:79], v[132:135], v[242:245], v[76:79]
	v_mfma_f32_16x16x32_bf16 v[116:119], v[174:177], v[214:217], v[116:119]
	v_mfma_f32_16x16x32_bf16 v[96:99], v[188:191], v[222:225], v[96:99]
	v_mfma_f32_16x16x32_bf16 v[84:87], v[174:177], v[230:233], v[84:87]
	v_mfma_f32_16x16x32_bf16 v[64:67], v[188:191], v[238:241], v[64:67]
	v_mfma_f32_16x16x32_bf16 v[112:115], v[188:191], v[214:217], v[112:115]
	v_mfma_f32_16x16x32_bf16 v[100:103], v[174:177], v[222:225], v[100:103]
	v_mfma_f32_16x16x32_bf16 v[80:83], v[188:191], v[230:233], v[80:83]
	v_mfma_f32_16x16x32_bf16 v[68:71], v[174:177], v[238:241], v[68:71]
	v_mfma_f32_16x16x32_bf16 v[116:119], v[184:187], v[218:221], v[116:119]
	v_mfma_f32_16x16x32_bf16 v[96:99], v[210:213], v[226:229], v[96:99]
	v_mfma_f32_16x16x32_bf16 v[84:87], v[184:187], v[234:237], v[84:87]
	v_mfma_f32_16x16x32_bf16 v[64:67], v[210:213], v[242:245], v[64:67]
	v_mfma_f32_16x16x32_bf16 v[112:115], v[210:213], v[218:221], v[112:115]
	v_mfma_f32_16x16x32_bf16 v[100:103], v[184:187], v[226:229], v[100:103]
	v_mfma_f32_16x16x32_bf16 v[80:83], v[210:213], v[234:237], v[80:83]
	v_mfma_f32_16x16x32_bf16 v[68:71], v[184:187], v[242:245], v[68:71]
	s_setprio 0
	s_barrier
	s_mov_b32 m0, s35
	s_add_u32 s0, s4, 0xb0000
	s_addc_u32 s1, s5, 0
	ds_read_b128 v[214:217], v181 offset:16384
	ds_read_b128 v[218:221], v181 offset:17408
	ds_read_b128 v[222:225], v181 offset:18432
	ds_read_b128 v[226:229], v181 offset:19456
	ds_read_b128 v[230:233], v181 offset:20480
	ds_read_b128 v[234:237], v181 offset:21504
	ds_read_b128 v[238:241], v181 offset:22528
	ds_read_b128 v[242:245], v181 offset:23552
	global_load_lds_dwordx4 v166, s[4:5]
	s_mov_b32 m0, s38
	s_nop 0
	global_load_lds_dwordx4 v162, s[4:5]
	s_mov_b32 m0, s39
	s_nop 0
	global_load_lds_dwordx4 v166, s[0:1]
	s_mov_b32 m0, s40
	s_nop 0
	global_load_lds_dwordx4 v162, s[0:1]
	s_mov_b32 m0, s29
	s_nop 0
	global_load_lds_dwordx4 v168, s[6:7]
	s_mov_b32 m0, s41
	s_nop 0
	global_load_lds_dwordx4 v164, s[6:7]
	s_waitcnt vmcnt(8)
	s_waitcnt lgkmcnt(0)
	s_barrier
	s_setprio 1
	v_mfma_f32_16x16x32_bf16 v[60:63], v[128:131], v[214:217], v[60:63]
	v_mfma_f32_16x16x32_bf16 v[40:43], v[136:139], v[222:225], v[40:43]
	v_mfma_f32_16x16x32_bf16 v[28:31], v[128:131], v[230:233], v[28:31]
	v_mfma_f32_16x16x32_bf16 v[8:11], v[136:139], v[238:241], v[8:11]
	v_mfma_f32_16x16x32_bf16 v[56:59], v[136:139], v[214:217], v[56:59]
	v_mfma_f32_16x16x32_bf16 v[44:47], v[128:131], v[222:225], v[44:47]
	v_mfma_f32_16x16x32_bf16 v[24:27], v[136:139], v[230:233], v[24:27]
	v_mfma_f32_16x16x32_bf16 v[12:15], v[128:131], v[238:241], v[12:15]
	v_mfma_f32_16x16x32_bf16 v[60:63], v[132:135], v[218:221], v[60:63]
	v_mfma_f32_16x16x32_bf16 v[40:43], v[140:143], v[226:229], v[40:43]
	v_mfma_f32_16x16x32_bf16 v[28:31], v[132:135], v[234:237], v[28:31]
	v_mfma_f32_16x16x32_bf16 v[8:11], v[140:143], v[242:245], v[8:11]
	v_mfma_f32_16x16x32_bf16 v[56:59], v[140:143], v[218:221], v[56:59]
	v_mfma_f32_16x16x32_bf16 v[44:47], v[132:135], v[226:229], v[44:47]
	v_mfma_f32_16x16x32_bf16 v[24:27], v[140:143], v[234:237], v[24:27]
	v_mfma_f32_16x16x32_bf16 v[12:15], v[132:135], v[242:245], v[12:15]
	v_mfma_f32_16x16x32_bf16 v[52:55], v[174:177], v[214:217], v[52:55]
	v_mfma_f32_16x16x32_bf16 v[32:35], v[188:191], v[222:225], v[32:35]
	v_mfma_f32_16x16x32_bf16 v[20:23], v[174:177], v[230:233], v[20:23]
	v_mfma_f32_16x16x32_bf16 v[0:3], v[188:191], v[238:241], v[0:3]
	v_mfma_f32_16x16x32_bf16 v[48:51], v[188:191], v[214:217], v[48:51]
	v_mfma_f32_16x16x32_bf16 v[36:39], v[174:177], v[222:225], v[36:39]
	v_mfma_f32_16x16x32_bf16 v[16:19], v[188:191], v[230:233], v[16:19]
	v_mfma_f32_16x16x32_bf16 v[4:7], v[174:177], v[238:241], v[4:7]
	v_mfma_f32_16x16x32_bf16 v[52:55], v[184:187], v[218:221], v[52:55]
	v_mfma_f32_16x16x32_bf16 v[32:35], v[210:213], v[226:229], v[32:35]
	v_mfma_f32_16x16x32_bf16 v[20:23], v[184:187], v[234:237], v[20:23]
	v_mfma_f32_16x16x32_bf16 v[0:3], v[210:213], v[242:245], v[0:3]
	v_mfma_f32_16x16x32_bf16 v[48:51], v[210:213], v[218:221], v[48:51]
	v_mfma_f32_16x16x32_bf16 v[36:39], v[184:187], v[226:229], v[36:39]
	v_mfma_f32_16x16x32_bf16 v[16:19], v[210:213], v[234:237], v[16:19]
	v_mfma_f32_16x16x32_bf16 v[4:7], v[184:187], v[242:245], v[4:7]
	s_setprio 0
	s_barrier
; #define PG8_STAGE(bufoff, gbase, voff) do { _Pragma("unroll") for (int _i = 0; _i < 2; ++_i) \
;         __builtin_amdgcn_global_load_lds((const unsigned*)((const char*)(gbase) + (voff)[_i]), (PG8_LAS unsigned*)(lds + (bufoff) + ldsw + _i * 8192), 16, 0, 0); } while (0)
; #define PG8_LDA(dst, b, h) do { _Pragma("unroll") for (int m = 0; m < 4; ++m) _Pragma("unroll") for (int k = 0; k < 2; ++k) dst[m][k] = *(const PG8_LAS bf16x8*)(lds + PG8_SA(b, h) + aoff + m * 2048 + k * 1024); } while (0)
; #define PG8_LDB(dst, b, h) do { _Pragma("unroll") for (int n = 0; n < 2; ++n) _Pragma("unroll") for (int k = 0; k < 2; ++k) dst[n][k] = *(const PG8_LAS bf16x8*)(lds + PG8_SB(b, h) + boff + n * 2048 + k * 1024); } while (0)
; #define PG8_MMA(ai, bj, At, Bt) do { __builtin_amdgcn_s_setprio(1); _Pragma("unroll") for (int m = 0; m < 4; ++m) _Pragma("unroll") for (int n = 0; n < 2; ++n) _Pragma("unroll") for (int k = 0; k < 2; ++k) \
;         acc[ai][bj][m][n] = __builtin_amdgcn_mfma_f32_16x16x32_bf16(Bt[n][k], At[m][k], acc[ai][bj][m][n], 0, 0, 0); __builtin_amdgcn_s_setprio(0); } while (0)
; #define PG8_WAIT_V(n) asm volatile("s_waitcnt vmcnt(" #n ")" ::: "memory")
; #define PG8_WAIT_L(n) asm volatile("s_waitcnt lgkmcnt(" #n ")" ::: "memory")
; #define PG8_BAR __builtin_amdgcn_s_barrier()
; #define PG8_SCHED __builtin_amdgcn_sched_barrier(0)
; template <class Epi, class Sched, bool ALIGN_EPI = false, bool SP2 = false>
; __device__ __forceinline__ void gemm_phase(PG8_LAS unsigned char* lds, const Gemm g, const Sched& S, const Epi& E) {
;     ...
;         for (int t = 0; t < nt; t += 2) {
;     ...
;             PG8_LDB(B0, 1, 0); PG8_LDB(B1, 1, 1); PG8_SCHED; PG8_LDA(At, 1, 0); PG8_STAGE(PG8_SA(0, 1), a2 + hstep, voffA);
;             PG8_WAIT_V(8); PG8_WAIT_L(0); PG8_BAR; PG8_MMA(0, 0, At, B0); PG8_MMA(0, 1, At, B1); PG8_BAR; PG8_SCHED;
;             PG8_LDA(At, 1, 1); PG8_STAGE(PG8_SB(1, 0), b3, voffB); PG8_STAGE(PG8_SB(1, 1), b3 + hstep, voffB); PG8_STAGE(PG8_SA(1, 0), a3, voffA);
;             PG8_WAIT_V(8); PG8_WAIT_L(0); PG8_BAR; PG8_MMA(1, 0, At, B0); PG8_MMA(1, 1, At, B1); PG8_BAR; PG8_SCHED;
;     ...
;         if constexpr (ALIGN_EPI) { if (wr == 0) PG8_BAR; }
	ds_read_b128 v[128:131], v254 offset:32768
	ds_read_b128 v[132:135], v254 offset:33792
	ds_read_b128 v[136:139], v254 offset:34816
	ds_read_b128 v[140:143], v254 offset:35840
	ds_read_b128 v[174:177], v254 offset:49152
	ds_read_b128 v[184:187], v254 offset:50176
	ds_read_b128 v[188:191], v254 offset:51200
	ds_read_b128 v[210:213], v254 offset:52224
	s_add_u32 s0, s6, 0xb0000
	s_addc_u32 s1, s7, 0
	s_mov_b32 m0, s42
	ds_read_b128 v[214:217], v181 offset:32768
	ds_read_b128 v[218:221], v181 offset:33792
	ds_read_b128 v[222:225], v181 offset:34816
	ds_read_b128 v[226:229], v181 offset:35840
	ds_read_b128 v[230:233], v181 offset:36864
	ds_read_b128 v[234:237], v181 offset:37888
	ds_read_b128 v[238:241], v181 offset:38912
	ds_read_b128 v[242:245], v181 offset:39936
	global_load_lds_dwordx4 v168, s[0:1]
	s_mov_b32 m0, s43
	s_nop 0
	global_load_lds_dwordx4 v164, s[0:1]
	s_waitcnt vmcnt(8)
	s_waitcnt lgkmcnt(0)
	s_barrier
	s_setprio 1
	v_mfma_f32_16x16x32_bf16 v[124:127], v[128:131], v[214:217], v[124:127]
	v_mfma_f32_16x16x32_bf16 v[104:107], v[136:139], v[222:225], v[104:107]
	v_mfma_f32_16x16x32_bf16 v[92:95], v[128:131], v[230:233], v[92:95]
	v_mfma_f32_16x16x32_bf16 v[72:75], v[136:139], v[238:241], v[72:75]
	v_mfma_f32_16x16x32_bf16 v[120:123], v[136:139], v[214:217], v[120:123]
	v_mfma_f32_16x16x32_bf16 v[108:111], v[128:131], v[222:225], v[108:111]
	v_mfma_f32_16x16x32_bf16 v[88:91], v[136:139], v[230:233], v[88:91]
	v_mfma_f32_16x16x32_bf16 v[76:79], v[128:131], v[238:241], v[76:79]
	v_mfma_f32_16x16x32_bf16 v[124:127], v[132:135], v[218:221], v[124:127]
	v_mfma_f32_16x16x32_bf16 v[104:107], v[140:143], v[226:229], v[104:107]
	v_mfma_f32_16x16x32_bf16 v[92:95], v[132:135], v[234:237], v[92:95]
	v_mfma_f32_16x16x32_bf16 v[72:75], v[140:143], v[242:245], v[72:75]
	v_mfma_f32_16x16x32_bf16 v[120:123], v[140:143], v[218:221], v[120:123]
	v_mfma_f32_16x16x32_bf16 v[108:111], v[132:135], v[226:229], v[108:111]
	v_mfma_f32_16x16x32_bf16 v[88:91], v[140:143], v[234:237], v[88:91]
	v_mfma_f32_16x16x32_bf16 v[76:79], v[132:135], v[242:245], v[76:79]
	v_mfma_f32_16x16x32_bf16 v[116:119], v[174:177], v[214:217], v[116:119]
	v_mfma_f32_16x16x32_bf16 v[96:99], v[188:191], v[222:225], v[96:99]
	v_mfma_f32_16x16x32_bf16 v[84:87], v[174:177], v[230:233], v[84:87]
	v_mfma_f32_16x16x32_bf16 v[64:67], v[188:191], v[238:241], v[64:67]
	v_mfma_f32_16x16x32_bf16 v[112:115], v[188:191], v[214:217], v[112:115]
	v_mfma_f32_16x16x32_bf16 v[100:103], v[174:177], v[222:225], v[100:103]
	v_mfma_f32_16x16x32_bf16 v[80:83], v[188:191], v[230:233], v[80:83]
	v_mfma_f32_16x16x32_bf16 v[68:71], v[174:177], v[238:241], v[68:71]
	v_mfma_f32_16x16x32_bf16 v[116:119], v[184:187], v[218:221], v[116:119]
	v_mfma_f32_16x16x32_bf16 v[96:99], v[210:213], v[226:229], v[96:99]
	v_mfma_f32_16x16x32_bf16 v[84:87], v[184:187], v[234:237], v[84:87]
	v_mfma_f32_16x16x32_bf16 v[64:67], v[210:213], v[242:245], v[64:67]
	v_mfma_f32_16x16x32_bf16 v[112:115], v[210:213], v[218:221], v[112:115]
	v_mfma_f32_16x16x32_bf16 v[100:103], v[184:187], v[226:229], v[100:103]
	v_mfma_f32_16x16x32_bf16 v[80:83], v[210:213], v[234:237], v[80:83]
	v_mfma_f32_16x16x32_bf16 v[68:71], v[184:187], v[242:245], v[68:71]
	s_setprio 0
	s_barrier
	s_mov_b32 m0, s47
	s_add_u32 s0, s4, 0xb0080
	s_addc_u32 s1, s5, 0
	ds_read_b128 v[214:217], v181 offset:49152
	ds_read_b128 v[218:221], v181 offset:50176
	ds_read_b128 v[222:225], v181 offset:51200
	ds_read_b128 v[226:229], v181 offset:52224
	ds_read_b128 v[230:233], v181 offset:53248
	ds_read_b128 v[234:237], v181 offset:54272
	ds_read_b128 v[238:241], v181 offset:55296
	ds_read_b128 v[242:245], v181 offset:56320
	s_add_u32 s98, s4, 0x80
	s_addc_u32 s99, s5, 0
	global_load_lds_dwordx4 v166, s[98:99]
	s_mov_b32 m0, s48
	s_nop 0
	global_load_lds_dwordx4 v162, s[98:99]
	s_mov_b32 m0, s51
	s_nop 0
	global_load_lds_dwordx4 v166, s[0:1]
	s_mov_b32 m0, s52
	s_nop 0
	global_load_lds_dwordx4 v162, s[0:1]
	s_mov_b32 m0, s49
	s_nop 0
	s_add_u32 s100, s6, 0x80
	s_addc_u32 s101, s7, 0
	global_load_lds_dwordx4 v168, s[100:101]
	s_mov_b32 m0, s50
	s_nop 0
	global_load_lds_dwordx4 v164, s[100:101]
	s_waitcnt vmcnt(8)
	s_waitcnt lgkmcnt(0)
	s_barrier
	s_setprio 1
	v_mfma_f32_16x16x32_bf16 v[60:63], v[128:131], v[214:217], v[60:63]
	v_mfma_f32_16x16x32_bf16 v[40:43], v[136:139], v[222:225], v[40:43]
	v_mfma_f32_16x16x32_bf16 v[28:31], v[128:131], v[230:233], v[28:31]
	v_mfma_f32_16x16x32_bf16 v[8:11], v[136:139], v[238:241], v[8:11]
	v_mfma_f32_16x16x32_bf16 v[56:59], v[136:139], v[214:217], v[56:59]
	v_mfma_f32_16x16x32_bf16 v[44:47], v[128:131], v[222:225], v[44:47]
	v_mfma_f32_16x16x32_bf16 v[24:27], v[136:139], v[230:233], v[24:27]
	v_mfma_f32_16x16x32_bf16 v[12:15], v[128:131], v[238:241], v[12:15]
	v_mfma_f32_16x16x32_bf16 v[60:63], v[132:135], v[218:221], v[60:63]
	v_mfma_f32_16x16x32_bf16 v[40:43], v[140:143], v[226:229], v[40:43]
	v_mfma_f32_16x16x32_bf16 v[28:31], v[132:135], v[234:237], v[28:31]
	v_mfma_f32_16x16x32_bf16 v[8:11], v[140:143], v[242:245], v[8:11]
	v_mfma_f32_16x16x32_bf16 v[56:59], v[140:143], v[218:221], v[56:59]
	v_mfma_f32_16x16x32_bf16 v[44:47], v[132:135], v[226:229], v[44:47]
	v_mfma_f32_16x16x32_bf16 v[24:27], v[140:143], v[234:237], v[24:27]
	v_mfma_f32_16x16x32_bf16 v[12:15], v[132:135], v[242:245], v[12:15]
	v_mfma_f32_16x16x32_bf16 v[52:55], v[174:177], v[214:217], v[52:55]
	v_mfma_f32_16x16x32_bf16 v[32:35], v[188:191], v[222:225], v[32:35]
	v_mfma_f32_16x16x32_bf16 v[20:23], v[174:177], v[230:233], v[20:23]
	v_mfma_f32_16x16x32_bf16 v[0:3], v[188:191], v[238:241], v[0:3]
	v_mfma_f32_16x16x32_bf16 v[48:51], v[188:191], v[214:217], v[48:51]
	v_mfma_f32_16x16x32_bf16 v[36:39], v[174:177], v[222:225], v[36:39]
	v_mfma_f32_16x16x32_bf16 v[16:19], v[188:191], v[230:233], v[16:19]
	v_mfma_f32_16x16x32_bf16 v[4:7], v[174:177], v[238:241], v[4:7]
	v_mfma_f32_16x16x32_bf16 v[52:55], v[184:187], v[218:221], v[52:55]
	v_mfma_f32_16x16x32_bf16 v[32:35], v[210:213], v[226:229], v[32:35]
	v_mfma_f32_16x16x32_bf16 v[20:23], v[184:187], v[234:237], v[20:23]
	v_mfma_f32_16x16x32_bf16 v[0:3], v[210:213], v[242:245], v[0:3]
	v_mfma_f32_16x16x32_bf16 v[48:51], v[210:213], v[218:221], v[48:51]
	v_mfma_f32_16x16x32_bf16 v[36:39], v[184:187], v[226:229], v[36:39]
	v_mfma_f32_16x16x32_bf16 v[16:19], v[210:213], v[234:237], v[16:19]
	v_mfma_f32_16x16x32_bf16 v[4:7], v[184:187], v[242:245], v[4:7]
	s_setprio 0
	s_barrier
	s_add_i32 s13, s13, 2
	s_add_u32 s10, s10, 0x100
	s_addc_u32 s11, s11, 0
	s_cmp_gt_u32 s13, 41
	s_mov_b64 s[0:1], s[2:3]
	s_cbranch_scc0 .LBB0_545
	s_and_b64 vcc, exec, s[22:23]
	s_cbranch_vccz .LBB0_548
	s_barrier

; #define PG8_STAGE(bufoff, gbase, voff) do { _Pragma("unroll") for (int _i = 0; _i < 2; ++_i) \
;         __builtin_amdgcn_global_load_lds((const unsigned*)((const char*)(gbase) + (voff)[_i]), (PG8_LAS unsigned*)(lds + (bufoff) + ldsw + _i * 8192), 16, 0, 0); } while (0)
; #define PG8_LDA(dst, b, h) do { _Pragma("unroll") for (int m = 0; m < 4; ++m) _Pragma("unroll") for (int k = 0; k < 2; ++k) dst[m][k] = *(const PG8_LAS bf16x8*)(lds + PG8_SA(b, h) + aoff + m * 2048 + k * 1024); } while (0)
; #define PG8_LDB(dst, b, h) do { _Pragma("unroll") for (int n = 0; n < 2; ++n) _Pragma("unroll") for (int k = 0; k < 2; ++k) dst[n][k] = *(const PG8_LAS bf16x8*)(lds + PG8_SB(b, h) + boff + n * 2048 + k * 1024); } while (0)
; #define PG8_MMA(ai, bj, At, Bt) do { __builtin_amdgcn_s_setprio(1); _Pragma("unroll") for (int m = 0; m < 4; ++m) _Pragma("unroll") for (int n = 0; n < 2; ++n) _Pragma("unroll") for (int k = 0; k < 2; ++k) \
;         acc[ai][bj][m][n] = __builtin_amdgcn_mfma_f32_16x16x32_bf16(Bt[n][k], At[m][k], acc[ai][bj][m][n], 0, 0, 0); __builtin_amdgcn_s_setprio(0); } while (0)
; #define PG8_WAIT_V(n) asm volatile("s_waitcnt vmcnt(" #n ")" ::: "memory")
; #define PG8_WAIT_L(n) asm volatile("s_waitcnt lgkmcnt(" #n ")" ::: "memory")
; #define PG8_BAR __builtin_amdgcn_s_barrier()
; #define PG8_SCHED __builtin_amdgcn_sched_barrier(0)
; template <class Epi, class Sched, bool ALIGN_EPI = false, bool SP2 = false>
; __device__ __forceinline__ void gemm_phase(PG8_LAS unsigned char* lds, const Gemm g, const Sched& S, const Epi& E) {
;     ...
;             PG8_LDB(B0, 0, 0); PG8_LDB(B1, 0, 1); PG8_SCHED; PG8_LDA(At, 0, 0); PG8_STAGE(PG8_SA(1, 1), a1 + hstep, voffA);
;             PG8_WAIT_V(8); PG8_WAIT_L(0); PG8_BAR; PG8_MMA(0, 0, At, B0); PG8_MMA(0, 1, At, B1); PG8_BAR; PG8_SCHED;
;             PG8_LDA(At, 0, 1); PG8_STAGE(PG8_SB(0, 0), b2, voffB); PG8_STAGE(PG8_SB(0, 1), b2 + hstep, voffB); PG8_STAGE(PG8_SA(0, 0), a2, voffA);
;             PG8_WAIT_V(8); PG8_WAIT_L(0); PG8_BAR; PG8_MMA(1, 0, At, B0); PG8_MMA(1, 1, At, B1); PG8_BAR; PG8_SCHED;
.Lsgi_peel:
	ds_read_b128 v[140:143], v254
	ds_read_b128 v[162:165], v254 offset:1024
	ds_read_b128 v[166:169], v254 offset:2048
	ds_read_b128 v[170:173], v254 offset:3072
	ds_read_b128 v[180:183], v254 offset:16384
	ds_read_b128 v[184:187], v254 offset:17408
	ds_read_b128 v[188:191], v254 offset:18432
	ds_read_b128 v[210:213], v254 offset:19456
	s_add_u32 s2, s0, 0xfffc0080
	s_addc_u32 s3, s1, -1
	s_cmp_eq_u32 s55, 12
	s_cselect_b32 s5, s13, s3
	s_cselect_b32 s4, s25, s2
	s_cselect_b32 s3, s23, s39
	s_cselect_b32 s2, s33, s38
	s_add_i32 m0, s6, 0xc000
	ds_read_b128 v[214:217], v178
	ds_read_b128 v[218:221], v178 offset:1024
	ds_read_b128 v[222:225], v178 offset:2048
	ds_read_b128 v[226:229], v178 offset:3072
	ds_read_b128 v[230:233], v178 offset:4096
	ds_read_b128 v[234:237], v178 offset:5120
	ds_read_b128 v[238:241], v178 offset:6144
	ds_read_b128 v[242:245], v178 offset:7168
	global_load_lds_dwordx4 v136, s[0:1]
	s_add_i32 m0, s6, 0xe000
	s_nop 0
	global_load_lds_dwordx4 v138, s[0:1]
	s_waitcnt vmcnt(8)
	s_waitcnt lgkmcnt(0)
	s_barrier
	s_setprio 1
	v_mfma_f32_16x16x32_bf16 v[124:127], v[140:143], v[214:217], 0
	v_mfma_f32_16x16x32_bf16 v[104:107], v[166:169], v[222:225], 0
	v_mfma_f32_16x16x32_bf16 v[92:95], v[140:143], v[230:233], 0
	v_mfma_f32_16x16x32_bf16 v[72:75], v[166:169], v[238:241], 0
	v_mfma_f32_16x16x32_bf16 v[120:123], v[166:169], v[214:217], 0
	v_mfma_f32_16x16x32_bf16 v[108:111], v[140:143], v[222:225], 0
	v_mfma_f32_16x16x32_bf16 v[88:91], v[166:169], v[230:233], 0
	v_mfma_f32_16x16x32_bf16 v[76:79], v[140:143], v[238:241], 0
	v_mfma_f32_16x16x32_bf16 v[124:127], v[162:165], v[218:221], v[124:127]
	v_mfma_f32_16x16x32_bf16 v[104:107], v[170:173], v[226:229], v[104:107]
	v_mfma_f32_16x16x32_bf16 v[92:95], v[162:165], v[234:237], v[92:95]
	v_mfma_f32_16x16x32_bf16 v[72:75], v[170:173], v[242:245], v[72:75]
	v_mfma_f32_16x16x32_bf16 v[120:123], v[170:173], v[218:221], v[120:123]
	v_mfma_f32_16x16x32_bf16 v[108:111], v[162:165], v[226:229], v[108:111]
	v_mfma_f32_16x16x32_bf16 v[88:91], v[170:173], v[234:237], v[88:91]
	v_mfma_f32_16x16x32_bf16 v[76:79], v[162:165], v[242:245], v[76:79]
	v_mfma_f32_16x16x32_bf16 v[116:119], v[180:183], v[214:217], 0
	v_mfma_f32_16x16x32_bf16 v[96:99], v[188:191], v[222:225], 0
	v_mfma_f32_16x16x32_bf16 v[84:87], v[180:183], v[230:233], 0
	v_mfma_f32_16x16x32_bf16 v[64:67], v[188:191], v[238:241], 0
	v_mfma_f32_16x16x32_bf16 v[112:115], v[188:191], v[214:217], 0
	v_mfma_f32_16x16x32_bf16 v[100:103], v[180:183], v[222:225], 0
	v_mfma_f32_16x16x32_bf16 v[80:83], v[188:191], v[230:233], 0
	v_mfma_f32_16x16x32_bf16 v[68:71], v[180:183], v[238:241], 0
	v_mfma_f32_16x16x32_bf16 v[116:119], v[184:187], v[218:221], v[116:119]
	v_mfma_f32_16x16x32_bf16 v[96:99], v[210:213], v[226:229], v[96:99]
	v_mfma_f32_16x16x32_bf16 v[84:87], v[184:187], v[234:237], v[84:87]
	v_mfma_f32_16x16x32_bf16 v[64:67], v[210:213], v[242:245], v[64:67]
	v_mfma_f32_16x16x32_bf16 v[112:115], v[210:213], v[218:221], v[112:115]
	v_mfma_f32_16x16x32_bf16 v[100:103], v[184:187], v[226:229], v[100:103]
	v_mfma_f32_16x16x32_bf16 v[80:83], v[210:213], v[234:237], v[80:83]
	v_mfma_f32_16x16x32_bf16 v[68:71], v[184:187], v[242:245], v[68:71]
	s_setprio 0
	s_barrier
	s_mov_b32 m0, s31
	s_add_u32 s56, s2, 0x40000
	s_addc_u32 s57, s3, 0
	ds_read_b128 v[214:217], v178 offset:16384
	ds_read_b128 v[218:221], v178 offset:17408
	ds_read_b128 v[222:225], v178 offset:18432
	ds_read_b128 v[226:229], v178 offset:19456
	ds_read_b128 v[230:233], v178 offset:20480
	ds_read_b128 v[234:237], v178 offset:21504
	ds_read_b128 v[238:241], v178 offset:22528
	ds_read_b128 v[242:245], v178 offset:23552
	global_load_lds_dwordx4 v132, s[2:3]
	s_mov_b32 m0, s34
	s_nop 0
	global_load_lds_dwordx4 v128, s[2:3]
	s_mov_b32 m0, s35
	s_nop 0
	global_load_lds_dwordx4 v132, s[56:57]
	s_mov_b32 m0, s40
	s_nop 0
	global_load_lds_dwordx4 v128, s[56:57]
	s_mov_b32 m0, s6
	s_nop 0
	global_load_lds_dwordx4 v134, s[4:5]
	s_mov_b32 m0, s41
	s_nop 0
	global_load_lds_dwordx4 v130, s[4:5]
	s_waitcnt vmcnt(8)
	s_waitcnt lgkmcnt(0)
	s_barrier
	s_setprio 1
	v_mfma_f32_16x16x32_bf16 v[60:63], v[140:143], v[214:217], 0
	v_mfma_f32_16x16x32_bf16 v[40:43], v[166:169], v[222:225], 0
	v_mfma_f32_16x16x32_bf16 v[28:31], v[140:143], v[230:233], 0
	v_mfma_f32_16x16x32_bf16 v[8:11], v[166:169], v[238:241], 0
	v_mfma_f32_16x16x32_bf16 v[56:59], v[166:169], v[214:217], 0
	v_mfma_f32_16x16x32_bf16 v[44:47], v[140:143], v[222:225], 0
	v_mfma_f32_16x16x32_bf16 v[24:27], v[166:169], v[230:233], 0
	v_mfma_f32_16x16x32_bf16 v[12:15], v[140:143], v[238:241], 0
	v_mfma_f32_16x16x32_bf16 v[60:63], v[162:165], v[218:221], v[60:63]
	v_mfma_f32_16x16x32_bf16 v[40:43], v[170:173], v[226:229], v[40:43]
	v_mfma_f32_16x16x32_bf16 v[28:31], v[162:165], v[234:237], v[28:31]
	v_mfma_f32_16x16x32_bf16 v[8:11], v[170:173], v[242:245], v[8:11]
	v_mfma_f32_16x16x32_bf16 v[56:59], v[170:173], v[218:221], v[56:59]
	v_mfma_f32_16x16x32_bf16 v[44:47], v[162:165], v[226:229], v[44:47]
	v_mfma_f32_16x16x32_bf16 v[24:27], v[170:173], v[234:237], v[24:27]
	v_mfma_f32_16x16x32_bf16 v[12:15], v[162:165], v[242:245], v[12:15]
	v_mfma_f32_16x16x32_bf16 v[52:55], v[180:183], v[214:217], 0
	v_mfma_f32_16x16x32_bf16 v[32:35], v[188:191], v[222:225], 0
	v_mfma_f32_16x16x32_bf16 v[20:23], v[180:183], v[230:233], 0
	v_mfma_f32_16x16x32_bf16 v[0:3], v[188:191], v[238:241], 0
	v_mfma_f32_16x16x32_bf16 v[48:51], v[188:191], v[214:217], 0
	v_mfma_f32_16x16x32_bf16 v[36:39], v[180:183], v[222:225], 0
	v_mfma_f32_16x16x32_bf16 v[16:19], v[188:191], v[230:233], 0
	v_mfma_f32_16x16x32_bf16 v[4:7], v[180:183], v[238:241], 0
	v_mfma_f32_16x16x32_bf16 v[52:55], v[184:187], v[218:221], v[52:55]
	v_mfma_f32_16x16x32_bf16 v[32:35], v[210:213], v[226:229], v[32:35]
	v_mfma_f32_16x16x32_bf16 v[20:23], v[184:187], v[234:237], v[20:23]
	v_mfma_f32_16x16x32_bf16 v[0:3], v[210:213], v[242:245], v[0:3]
	v_mfma_f32_16x16x32_bf16 v[48:51], v[210:213], v[218:221], v[48:51]
	v_mfma_f32_16x16x32_bf16 v[36:39], v[184:187], v[226:229], v[36:39]
	v_mfma_f32_16x16x32_bf16 v[16:19], v[210:213], v[234:237], v[16:19]
	v_mfma_f32_16x16x32_bf16 v[4:7], v[184:187], v[242:245], v[4:7]
	s_setprio 0
	s_barrier
; #define PG8_STAGE(bufoff, gbase, voff) do { _Pragma("unroll") for (int _i = 0; _i < 2; ++_i) \
;         __builtin_amdgcn_global_load_lds((const unsigned*)((const char*)(gbase) + (voff)[_i]), (PG8_LAS unsigned*)(lds + (bufoff) + ldsw + _i * 8192), 16, 0, 0); } while (0)
; #define PG8_LDA(dst, b, h) do { _Pragma("unroll") for (int m = 0; m < 4; ++m) _Pragma("unroll") for (int k = 0; k < 2; ++k) dst[m][k] = *(const PG8_LAS bf16x8*)(lds + PG8_SA(b, h) + aoff + m * 2048 + k * 1024); } while (0)
; #define PG8_LDB(dst, b, h) do { _Pragma("unroll") for (int n = 0; n < 2; ++n) _Pragma("unroll") for (int k = 0; k < 2; ++k) dst[n][k] = *(const PG8_LAS bf16x8*)(lds + PG8_SB(b, h) + boff + n * 2048 + k * 1024); } while (0)
; #define PG8_MMA(ai, bj, At, Bt) do { __builtin_amdgcn_s_setprio(1); _Pragma("unroll") for (int m = 0; m < 4; ++m) _Pragma("unroll") for (int n = 0; n < 2; ++n) _Pragma("unroll") for (int k = 0; k < 2; ++k) \
;         acc[ai][bj][m][n] = __builtin_amdgcn_mfma_f32_16x16x32_bf16(Bt[n][k], At[m][k], acc[ai][bj][m][n], 0, 0, 0); __builtin_amdgcn_s_setprio(0); } while (0)
; #define PG8_WAIT_V(n) asm volatile("s_waitcnt vmcnt(" #n ")" ::: "memory")
; #define PG8_WAIT_L(n) asm volatile("s_waitcnt lgkmcnt(" #n ")" ::: "memory")
; #define PG8_BAR __builtin_amdgcn_s_barrier()
; #define PG8_SCHED __builtin_amdgcn_sched_barrier(0)
; template <class Epi, class Sched, bool ALIGN_EPI = false, bool SP2 = false>
; __device__ __forceinline__ void gemm_phase(PG8_LAS unsigned char* lds, const Gemm g, const Sched& S, const Epi& E) {
;     ...
;         for (int t = 0; t < nt; t += 2) {
;     ...
;             PG8_LDB(B0, 1, 0); PG8_LDB(B1, 1, 1); PG8_SCHED; PG8_LDA(At, 1, 0); PG8_STAGE(PG8_SA(0, 1), a2 + hstep, voffA);
;             PG8_WAIT_V(8); PG8_WAIT_L(0); PG8_BAR; PG8_MMA(0, 0, At, B0); PG8_MMA(0, 1, At, B1); PG8_BAR; PG8_SCHED;
;             PG8_LDA(At, 1, 1); PG8_STAGE(PG8_SB(1, 0), b3, voffB); PG8_STAGE(PG8_SB(1, 1), b3 + hstep, voffB); PG8_STAGE(PG8_SA(1, 0), a3, voffA);
;             PG8_WAIT_V(8); PG8_WAIT_L(0); PG8_BAR; PG8_MMA(1, 0, At, B0); PG8_MMA(1, 1, At, B1); PG8_BAR; PG8_SCHED;
	ds_read_b128 v[140:143], v254 offset:32768
	ds_read_b128 v[162:165], v254 offset:33792
	ds_read_b128 v[166:169], v254 offset:34816
	ds_read_b128 v[170:173], v254 offset:35840
	ds_read_b128 v[180:183], v254 offset:49152
	ds_read_b128 v[184:187], v254 offset:50176
	ds_read_b128 v[188:191], v254 offset:51200
	ds_read_b128 v[210:213], v254 offset:52224
	s_add_u32 s4, s4, 0x40000
	s_addc_u32 s5, s5, 0
	s_mov_b32 m0, s42
	ds_read_b128 v[214:217], v178 offset:32768
	ds_read_b128 v[218:221], v178 offset:33792
	ds_read_b128 v[222:225], v178 offset:34816
	ds_read_b128 v[226:229], v178 offset:35840
	ds_read_b128 v[230:233], v178 offset:36864
	ds_read_b128 v[234:237], v178 offset:37888
	ds_read_b128 v[238:241], v178 offset:38912
	ds_read_b128 v[242:245], v178 offset:39936
	global_load_lds_dwordx4 v134, s[4:5]
	s_mov_b32 m0, s43
	s_nop 0
	global_load_lds_dwordx4 v130, s[4:5]
	s_waitcnt vmcnt(8)
	s_waitcnt lgkmcnt(0)
	s_barrier
	s_setprio 1
	v_mfma_f32_16x16x32_bf16 v[124:127], v[140:143], v[214:217], v[124:127]
	v_mfma_f32_16x16x32_bf16 v[104:107], v[166:169], v[222:225], v[104:107]
	v_mfma_f32_16x16x32_bf16 v[92:95], v[140:143], v[230:233], v[92:95]
	v_mfma_f32_16x16x32_bf16 v[72:75], v[166:169], v[238:241], v[72:75]
	v_mfma_f32_16x16x32_bf16 v[120:123], v[166:169], v[214:217], v[120:123]
	v_mfma_f32_16x16x32_bf16 v[108:111], v[140:143], v[222:225], v[108:111]
	v_mfma_f32_16x16x32_bf16 v[88:91], v[166:169], v[230:233], v[88:91]
	v_mfma_f32_16x16x32_bf16 v[76:79], v[140:143], v[238:241], v[76:79]
	v_mfma_f32_16x16x32_bf16 v[124:127], v[162:165], v[218:221], v[124:127]
	v_mfma_f32_16x16x32_bf16 v[104:107], v[170:173], v[226:229], v[104:107]
	v_mfma_f32_16x16x32_bf16 v[92:95], v[162:165], v[234:237], v[92:95]
	v_mfma_f32_16x16x32_bf16 v[72:75], v[170:173], v[242:245], v[72:75]
	v_mfma_f32_16x16x32_bf16 v[120:123], v[170:173], v[218:221], v[120:123]
	v_mfma_f32_16x16x32_bf16 v[108:111], v[162:165], v[226:229], v[108:111]
	v_mfma_f32_16x16x32_bf16 v[88:91], v[170:173], v[234:237], v[88:91]
	v_mfma_f32_16x16x32_bf16 v[76:79], v[162:165], v[242:245], v[76:79]
	v_mfma_f32_16x16x32_bf16 v[116:119], v[180:183], v[214:217], v[116:119]
	v_mfma_f32_16x16x32_bf16 v[96:99], v[188:191], v[222:225], v[96:99]
	v_mfma_f32_16x16x32_bf16 v[84:87], v[180:183], v[230:233], v[84:87]
	v_mfma_f32_16x16x32_bf16 v[64:67], v[188:191], v[238:241], v[64:67]
	v_mfma_f32_16x16x32_bf16 v[112:115], v[188:191], v[214:217], v[112:115]
	v_mfma_f32_16x16x32_bf16 v[100:103], v[180:183], v[222:225], v[100:103]
	v_mfma_f32_16x16x32_bf16 v[80:83], v[188:191], v[230:233], v[80:83]
	v_mfma_f32_16x16x32_bf16 v[68:71], v[180:183], v[238:241], v[68:71]
	v_mfma_f32_16x16x32_bf16 v[116:119], v[184:187], v[218:221], v[116:119]
	v_mfma_f32_16x16x32_bf16 v[96:99], v[210:213], v[226:229], v[96:99]
	v_mfma_f32_16x16x32_bf16 v[84:87], v[184:187], v[234:237], v[84:87]
	v_mfma_f32_16x16x32_bf16 v[64:67], v[210:213], v[242:245], v[64:67]
	v_mfma_f32_16x16x32_bf16 v[112:115], v[210:213], v[218:221], v[112:115]
	v_mfma_f32_16x16x32_bf16 v[100:103], v[184:187], v[226:229], v[100:103]
	v_mfma_f32_16x16x32_bf16 v[80:83], v[210:213], v[234:237], v[80:83]
	v_mfma_f32_16x16x32_bf16 v[68:71], v[184:187], v[242:245], v[68:71]
	s_setprio 0
	s_barrier
	s_mov_b32 m0, s48
	s_add_u32 s2, s2, 0x40080
	s_addc_u32 s3, s3, 0
	ds_read_b128 v[214:217], v178 offset:49152
	ds_read_b128 v[218:221], v178 offset:50176
	ds_read_b128 v[222:225], v178 offset:51200
	ds_read_b128 v[226:229], v178 offset:52224
	ds_read_b128 v[230:233], v178 offset:53248
	ds_read_b128 v[234:237], v178 offset:54272
	ds_read_b128 v[238:241], v178 offset:55296
	ds_read_b128 v[242:245], v178 offset:56320
	s_add_u32 s98, s2, 0xfffc0000
	s_addc_u32 s99, s3, -1
	global_load_lds_dwordx4 v132, s[98:99]
	s_mov_b32 m0, s49
	s_nop 0
	global_load_lds_dwordx4 v128, s[98:99]
	s_mov_b32 m0, s52
	s_nop 0
	global_load_lds_dwordx4 v132, s[2:3]
	s_mov_b32 m0, s53
	s_nop 0
	global_load_lds_dwordx4 v128, s[2:3]
	s_mov_b32 m0, s50
	s_nop 0
	s_add_u32 s100, s4, 0xfffc0080
	s_addc_u32 s101, s5, -1
	global_load_lds_dwordx4 v134, s[100:101]
	s_mov_b32 m0, s51
	s_nop 0
	global_load_lds_dwordx4 v130, s[100:101]
	s_waitcnt vmcnt(8)
	s_waitcnt lgkmcnt(0)
	s_barrier
	s_setprio 1
	v_mfma_f32_16x16x32_bf16 v[60:63], v[140:143], v[214:217], v[60:63]
	v_mfma_f32_16x16x32_bf16 v[40:43], v[166:169], v[222:225], v[40:43]
	v_mfma_f32_16x16x32_bf16 v[28:31], v[140:143], v[230:233], v[28:31]
	v_mfma_f32_16x16x32_bf16 v[8:11], v[166:169], v[238:241], v[8:11]
	v_mfma_f32_16x16x32_bf16 v[56:59], v[166:169], v[214:217], v[56:59]
	v_mfma_f32_16x16x32_bf16 v[44:47], v[140:143], v[222:225], v[44:47]
	v_mfma_f32_16x16x32_bf16 v[24:27], v[166:169], v[230:233], v[24:27]
	v_mfma_f32_16x16x32_bf16 v[12:15], v[140:143], v[238:241], v[12:15]
	v_mfma_f32_16x16x32_bf16 v[60:63], v[162:165], v[218:221], v[60:63]
	v_mfma_f32_16x16x32_bf16 v[40:43], v[170:173], v[226:229], v[40:43]
	v_mfma_f32_16x16x32_bf16 v[28:31], v[162:165], v[234:237], v[28:31]
	v_mfma_f32_16x16x32_bf16 v[8:11], v[170:173], v[242:245], v[8:11]
	v_mfma_f32_16x16x32_bf16 v[56:59], v[170:173], v[218:221], v[56:59]
	v_mfma_f32_16x16x32_bf16 v[44:47], v[162:165], v[226:229], v[44:47]
	v_mfma_f32_16x16x32_bf16 v[24:27], v[170:173], v[234:237], v[24:27]
	v_mfma_f32_16x16x32_bf16 v[12:15], v[162:165], v[242:245], v[12:15]
	v_mfma_f32_16x16x32_bf16 v[52:55], v[180:183], v[214:217], v[52:55]
	v_mfma_f32_16x16x32_bf16 v[32:35], v[188:191], v[222:225], v[32:35]
	v_mfma_f32_16x16x32_bf16 v[20:23], v[180:183], v[230:233], v[20:23]
	v_mfma_f32_16x16x32_bf16 v[0:3], v[188:191], v[238:241], v[0:3]
	v_mfma_f32_16x16x32_bf16 v[48:51], v[188:191], v[214:217], v[48:51]
	v_mfma_f32_16x16x32_bf16 v[36:39], v[180:183], v[222:225], v[36:39]
	v_mfma_f32_16x16x32_bf16 v[16:19], v[188:191], v[230:233], v[16:19]
	v_mfma_f32_16x16x32_bf16 v[4:7], v[180:183], v[238:241], v[4:7]
	v_mfma_f32_16x16x32_bf16 v[52:55], v[184:187], v[218:221], v[52:55]
	v_mfma_f32_16x16x32_bf16 v[32:35], v[210:213], v[226:229], v[32:35]
	v_mfma_f32_16x16x32_bf16 v[20:23], v[184:187], v[234:237], v[20:23]
	v_mfma_f32_16x16x32_bf16 v[0:3], v[210:213], v[242:245], v[0:3]
	v_mfma_f32_16x16x32_bf16 v[48:51], v[210:213], v[218:221], v[48:51]
	v_mfma_f32_16x16x32_bf16 v[36:39], v[184:187], v[226:229], v[36:39]
	v_mfma_f32_16x16x32_bf16 v[16:19], v[210:213], v[234:237], v[16:19]
	v_mfma_f32_16x16x32_bf16 v[4:7], v[184:187], v[242:245], v[4:7]
	s_setprio 0
	s_barrier
	s_add_i32 s55, s55, 2
	s_add_u32 s0, s0, 0x100
	s_addc_u32 s1, s1, 0
	s_add_u32 s38, s38, 0x100
	s_addc_u32 s39, s39, 0
	s_cmp_gt_u32 s55, 13
; #define PG8_STAGE(bufoff, gbase, voff) do { _Pragma("unroll") for (int _i = 0; _i < 2; ++_i) \
;         __builtin_amdgcn_global_load_lds((const unsigned*)((const char*)(gbase) + (voff)[_i]), (PG8_LAS unsigned*)(lds + (bufoff) + ldsw + _i * 8192), 16, 0, 0); } while (0)
; #define PG8_LDA(dst, b, h) do { _Pragma("unroll") for (int m = 0; m < 4; ++m) _Pragma("unroll") for (int k = 0; k < 2; ++k) dst[m][k] = *(const PG8_LAS bf16x8*)(lds + PG8_SA(b, h) + aoff + m * 2048 + k * 1024); } while (0)
; #define PG8_LDB(dst, b, h) do { _Pragma("unroll") for (int n = 0; n < 2; ++n) _Pragma("unroll") for (int k = 0; k < 2; ++k) dst[n][k] = *(const PG8_LAS bf16x8*)(lds + PG8_SB(b, h) + boff + n * 2048 + k * 1024); } while (0)
; #define PG8_MMA(ai, bj, At, Bt) do { __builtin_amdgcn_s_setprio(1); _Pragma("unroll") for (int m = 0; m < 4; ++m) _Pragma("unroll") for (int n = 0; n < 2; ++n) _Pragma("unroll") for (int k = 0; k < 2; ++k) \
;         acc[ai][bj][m][n] = __builtin_amdgcn_mfma_f32_16x16x32_bf16(Bt[n][k], At[m][k], acc[ai][bj][m][n], 0, 0, 0); __builtin_amdgcn_s_setprio(0); } while (0)
; #define PG8_WAIT_V(n) asm volatile("s_waitcnt vmcnt(" #n ")" ::: "memory")
; #define PG8_WAIT_L(n) asm volatile("s_waitcnt lgkmcnt(" #n ")" ::: "memory")
; #define PG8_BAR __builtin_amdgcn_s_barrier()
; #define PG8_SCHED __builtin_amdgcn_sched_barrier(0)
; template <class Epi, class Sched, bool ALIGN_EPI = false, bool SP2 = false>
; __device__ __forceinline__ void gemm_phase(PG8_LAS unsigned char* lds, const Gemm g, const Sched& S, const Epi& E) {
;     ...
;             PG8_LDB(B0, 0, 0); PG8_LDB(B1, 0, 1); PG8_SCHED; PG8_LDA(At, 0, 0); PG8_STAGE(PG8_SA(1, 1), a1 + hstep, voffA);
;             PG8_WAIT_V(8); PG8_WAIT_L(0); PG8_BAR; PG8_MMA(0, 0, At, B0); PG8_MMA(0, 1, At, B1); PG8_BAR; PG8_SCHED;
;             PG8_LDA(At, 0, 1); PG8_STAGE(PG8_SB(0, 0), b2, voffB); PG8_STAGE(PG8_SB(0, 1), b2 + hstep, voffB); PG8_STAGE(PG8_SA(0, 0), a2, voffA);
;             PG8_WAIT_V(8); PG8_WAIT_L(0); PG8_BAR; PG8_MMA(1, 0, At, B0); PG8_MMA(1, 1, At, B1); PG8_BAR; PG8_SCHED;
.LBB0_749:
	ds_read_b128 v[140:143], v254
	ds_read_b128 v[162:165], v254 offset:1024
	ds_read_b128 v[166:169], v254 offset:2048
	ds_read_b128 v[170:173], v254 offset:3072
	ds_read_b128 v[180:183], v254 offset:16384
	ds_read_b128 v[184:187], v254 offset:17408
	ds_read_b128 v[188:191], v254 offset:18432
	ds_read_b128 v[210:213], v254 offset:19456
	s_add_u32 s2, s0, 0xfffc0080
	s_addc_u32 s3, s1, -1
	s_cmp_eq_u32 s55, 12
	s_cselect_b32 s5, s13, s3
	s_cselect_b32 s4, s25, s2
	s_cselect_b32 s3, s23, s39
	s_cselect_b32 s2, s33, s38
	s_add_i32 m0, s6, 0xc000
	ds_read_b128 v[214:217], v178
	ds_read_b128 v[218:221], v178 offset:1024
	ds_read_b128 v[222:225], v178 offset:2048
	ds_read_b128 v[226:229], v178 offset:3072
	ds_read_b128 v[230:233], v178 offset:4096
	ds_read_b128 v[234:237], v178 offset:5120
	ds_read_b128 v[238:241], v178 offset:6144
	ds_read_b128 v[242:245], v178 offset:7168
	global_load_lds_dwordx4 v136, s[0:1]
	s_add_i32 m0, s6, 0xe000
	s_nop 0
	global_load_lds_dwordx4 v138, s[0:1]
	s_waitcnt vmcnt(8)
	s_waitcnt lgkmcnt(0)
	s_barrier
	s_setprio 1
	v_mfma_f32_16x16x32_bf16 v[124:127], v[140:143], v[214:217], v[124:127]
	v_mfma_f32_16x16x32_bf16 v[104:107], v[166:169], v[222:225], v[104:107]
	v_mfma_f32_16x16x32_bf16 v[92:95], v[140:143], v[230:233], v[92:95]
	v_mfma_f32_16x16x32_bf16 v[72:75], v[166:169], v[238:241], v[72:75]
	v_mfma_f32_16x16x32_bf16 v[120:123], v[166:169], v[214:217], v[120:123]
	v_mfma_f32_16x16x32_bf16 v[108:111], v[140:143], v[222:225], v[108:111]
	v_mfma_f32_16x16x32_bf16 v[88:91], v[166:169], v[230:233], v[88:91]
	v_mfma_f32_16x16x32_bf16 v[76:79], v[140:143], v[238:241], v[76:79]
	v_mfma_f32_16x16x32_bf16 v[124:127], v[162:165], v[218:221], v[124:127]
	v_mfma_f32_16x16x32_bf16 v[104:107], v[170:173], v[226:229], v[104:107]
	v_mfma_f32_16x16x32_bf16 v[92:95], v[162:165], v[234:237], v[92:95]
	v_mfma_f32_16x16x32_bf16 v[72:75], v[170:173], v[242:245], v[72:75]
	v_mfma_f32_16x16x32_bf16 v[120:123], v[170:173], v[218:221], v[120:123]
	v_mfma_f32_16x16x32_bf16 v[108:111], v[162:165], v[226:229], v[108:111]
	v_mfma_f32_16x16x32_bf16 v[88:91], v[170:173], v[234:237], v[88:91]
	v_mfma_f32_16x16x32_bf16 v[76:79], v[162:165], v[242:245], v[76:79]
	v_mfma_f32_16x16x32_bf16 v[116:119], v[180:183], v[214:217], v[116:119]
	v_mfma_f32_16x16x32_bf16 v[96:99], v[188:191], v[222:225], v[96:99]
	v_mfma_f32_16x16x32_bf16 v[84:87], v[180:183], v[230:233], v[84:87]
	v_mfma_f32_16x16x32_bf16 v[64:67], v[188:191], v[238:241], v[64:67]
	v_mfma_f32_16x16x32_bf16 v[112:115], v[188:191], v[214:217], v[112:115]
	v_mfma_f32_16x16x32_bf16 v[100:103], v[180:183], v[222:225], v[100:103]
	v_mfma_f32_16x16x32_bf16 v[80:83], v[188:191], v[230:233], v[80:83]
	v_mfma_f32_16x16x32_bf16 v[68:71], v[180:183], v[238:241], v[68:71]
	v_mfma_f32_16x16x32_bf16 v[116:119], v[184:187], v[218:221], v[116:119]
	v_mfma_f32_16x16x32_bf16 v[96:99], v[210:213], v[226:229], v[96:99]
	v_mfma_f32_16x16x32_bf16 v[84:87], v[184:187], v[234:237], v[84:87]
	v_mfma_f32_16x16x32_bf16 v[64:67], v[210:213], v[242:245], v[64:67]
	v_mfma_f32_16x16x32_bf16 v[112:115], v[210:213], v[218:221], v[112:115]
	v_mfma_f32_16x16x32_bf16 v[100:103], v[184:187], v[226:229], v[100:103]
	v_mfma_f32_16x16x32_bf16 v[80:83], v[210:213], v[234:237], v[80:83]
	v_mfma_f32_16x16x32_bf16 v[68:71], v[184:187], v[242:245], v[68:71]
	s_setprio 0
	s_barrier
	s_mov_b32 m0, s31
	s_add_u32 s56, s2, 0x40000
	s_addc_u32 s57, s3, 0
	ds_read_b128 v[214:217], v178 offset:16384
	ds_read_b128 v[218:221], v178 offset:17408
	ds_read_b128 v[222:225], v178 offset:18432
	ds_read_b128 v[226:229], v178 offset:19456
	ds_read_b128 v[230:233], v178 offset:20480
	ds_read_b128 v[234:237], v178 offset:21504
	ds_read_b128 v[238:241], v178 offset:22528
	ds_read_b128 v[242:245], v178 offset:23552
	global_load_lds_dwordx4 v132, s[2:3]
	s_mov_b32 m0, s34
	s_nop 0
	global_load_lds_dwordx4 v128, s[2:3]
	s_mov_b32 m0, s35
	s_nop 0
	global_load_lds_dwordx4 v132, s[56:57]
	s_mov_b32 m0, s40
	s_nop 0
	global_load_lds_dwordx4 v128, s[56:57]
	s_mov_b32 m0, s6
	s_nop 0
	global_load_lds_dwordx4 v134, s[4:5]
	s_mov_b32 m0, s41
	s_nop 0
	global_load_lds_dwordx4 v130, s[4:5]
	s_waitcnt vmcnt(8)
	s_waitcnt lgkmcnt(0)
	s_barrier
	s_setprio 1
	v_mfma_f32_16x16x32_bf16 v[60:63], v[140:143], v[214:217], v[60:63]
	v_mfma_f32_16x16x32_bf16 v[40:43], v[166:169], v[222:225], v[40:43]
	v_mfma_f32_16x16x32_bf16 v[28:31], v[140:143], v[230:233], v[28:31]
	v_mfma_f32_16x16x32_bf16 v[8:11], v[166:169], v[238:241], v[8:11]
	v_mfma_f32_16x16x32_bf16 v[56:59], v[166:169], v[214:217], v[56:59]
	v_mfma_f32_16x16x32_bf16 v[44:47], v[140:143], v[222:225], v[44:47]
	v_mfma_f32_16x16x32_bf16 v[24:27], v[166:169], v[230:233], v[24:27]
	v_mfma_f32_16x16x32_bf16 v[12:15], v[140:143], v[238:241], v[12:15]
	v_mfma_f32_16x16x32_bf16 v[60:63], v[162:165], v[218:221], v[60:63]
	v_mfma_f32_16x16x32_bf16 v[40:43], v[170:173], v[226:229], v[40:43]
	v_mfma_f32_16x16x32_bf16 v[28:31], v[162:165], v[234:237], v[28:31]
	v_mfma_f32_16x16x32_bf16 v[8:11], v[170:173], v[242:245], v[8:11]
	v_mfma_f32_16x16x32_bf16 v[56:59], v[170:173], v[218:221], v[56:59]
	v_mfma_f32_16x16x32_bf16 v[44:47], v[162:165], v[226:229], v[44:47]
	v_mfma_f32_16x16x32_bf16 v[24:27], v[170:173], v[234:237], v[24:27]
	v_mfma_f32_16x16x32_bf16 v[12:15], v[162:165], v[242:245], v[12:15]
	v_mfma_f32_16x16x32_bf16 v[52:55], v[180:183], v[214:217], v[52:55]
	v_mfma_f32_16x16x32_bf16 v[32:35], v[188:191], v[222:225], v[32:35]
	v_mfma_f32_16x16x32_bf16 v[20:23], v[180:183], v[230:233], v[20:23]
	v_mfma_f32_16x16x32_bf16 v[0:3], v[188:191], v[238:241], v[0:3]
	v_mfma_f32_16x16x32_bf16 v[48:51], v[188:191], v[214:217], v[48:51]
	v_mfma_f32_16x16x32_bf16 v[36:39], v[180:183], v[222:225], v[36:39]
	v_mfma_f32_16x16x32_bf16 v[16:19], v[188:191], v[230:233], v[16:19]
	v_mfma_f32_16x16x32_bf16 v[4:7], v[180:183], v[238:241], v[4:7]
	v_mfma_f32_16x16x32_bf16 v[52:55], v[184:187], v[218:221], v[52:55]
	v_mfma_f32_16x16x32_bf16 v[32:35], v[210:213], v[226:229], v[32:35]
	v_mfma_f32_16x16x32_bf16 v[20:23], v[184:187], v[234:237], v[20:23]
	v_mfma_f32_16x16x32_bf16 v[0:3], v[210:213], v[242:245], v[0:3]
	v_mfma_f32_16x16x32_bf16 v[48:51], v[210:213], v[218:221], v[48:51]
	v_mfma_f32_16x16x32_bf16 v[36:39], v[184:187], v[226:229], v[36:39]
	v_mfma_f32_16x16x32_bf16 v[16:19], v[210:213], v[234:237], v[16:19]
	v_mfma_f32_16x16x32_bf16 v[4:7], v[184:187], v[242:245], v[4:7]
	s_setprio 0
	s_barrier
; #define PG8_STAGE(bufoff, gbase, voff) do { _Pragma("unroll") for (int _i = 0; _i < 2; ++_i) \
;         __builtin_amdgcn_global_load_lds((const unsigned*)((const char*)(gbase) + (voff)[_i]), (PG8_LAS unsigned*)(lds + (bufoff) + ldsw + _i * 8192), 16, 0, 0); } while (0)
; #define PG8_LDA(dst, b, h) do { _Pragma("unroll") for (int m = 0; m < 4; ++m) _Pragma("unroll") for (int k = 0; k < 2; ++k) dst[m][k] = *(const PG8_LAS bf16x8*)(lds + PG8_SA(b, h) + aoff + m * 2048 + k * 1024); } while (0)
; #define PG8_LDB(dst, b, h) do { _Pragma("unroll") for (int n = 0; n < 2; ++n) _Pragma("unroll") for (int k = 0; k < 2; ++k) dst[n][k] = *(const PG8_LAS bf16x8*)(lds + PG8_SB(b, h) + boff + n * 2048 + k * 1024); } while (0)
; #define PG8_MMA(ai, bj, At, Bt) do { __builtin_amdgcn_s_setprio(1); _Pragma("unroll") for (int m = 0; m < 4; ++m) _Pragma("unroll") for (int n = 0; n < 2; ++n) _Pragma("unroll") for (int k = 0; k < 2; ++k) \
;         acc[ai][bj][m][n] = __builtin_amdgcn_mfma_f32_16x16x32_bf16(Bt[n][k], At[m][k], acc[ai][bj][m][n], 0, 0, 0); __builtin_amdgcn_s_setprio(0); } while (0)
; #define PG8_WAIT_V(n) asm volatile("s_waitcnt vmcnt(" #n ")" ::: "memory")
; #define PG8_WAIT_L(n) asm volatile("s_waitcnt lgkmcnt(" #n ")" ::: "memory")
; #define PG8_BAR __builtin_amdgcn_s_barrier()
; #define PG8_SCHED __builtin_amdgcn_sched_barrier(0)
; template <class Epi, class Sched, bool ALIGN_EPI = false, bool SP2 = false>
; __device__ __forceinline__ void gemm_phase(PG8_LAS unsigned char* lds, const Gemm g, const Sched& S, const Epi& E) {
;     ...
;         for (int t = 0; t < nt; t += 2) {
;     ...
;             PG8_LDB(B0, 1, 0); PG8_LDB(B1, 1, 1); PG8_SCHED; PG8_LDA(At, 1, 0); PG8_STAGE(PG8_SA(0, 1), a2 + hstep, voffA);
;             PG8_WAIT_V(8); PG8_WAIT_L(0); PG8_BAR; PG8_MMA(0, 0, At, B0); PG8_MMA(0, 1, At, B1); PG8_BAR; PG8_SCHED;
;             PG8_LDA(At, 1, 1); PG8_STAGE(PG8_SB(1, 0), b3, voffB); PG8_STAGE(PG8_SB(1, 1), b3 + hstep, voffB); PG8_STAGE(PG8_SA(1, 0), a3, voffA);
;             PG8_WAIT_V(8); PG8_WAIT_L(0); PG8_BAR; PG8_MMA(1, 0, At, B0); PG8_MMA(1, 1, At, B1); PG8_BAR; PG8_SCHED;
;     ...
;         if constexpr (ALIGN_EPI) { if (wr == 0) PG8_BAR; }
	ds_read_b128 v[140:143], v254 offset:32768
	ds_read_b128 v[162:165], v254 offset:33792
	ds_read_b128 v[166:169], v254 offset:34816
	ds_read_b128 v[170:173], v254 offset:35840
	ds_read_b128 v[180:183], v254 offset:49152
	ds_read_b128 v[184:187], v254 offset:50176
	ds_read_b128 v[188:191], v254 offset:51200
	ds_read_b128 v[210:213], v254 offset:52224
	s_add_u32 s4, s4, 0x40000
	s_addc_u32 s5, s5, 0
	s_mov_b32 m0, s42
	ds_read_b128 v[214:217], v178 offset:32768
	ds_read_b128 v[218:221], v178 offset:33792
	ds_read_b128 v[222:225], v178 offset:34816
	ds_read_b128 v[226:229], v178 offset:35840
	ds_read_b128 v[230:233], v178 offset:36864
	ds_read_b128 v[234:237], v178 offset:37888
	ds_read_b128 v[238:241], v178 offset:38912
	ds_read_b128 v[242:245], v178 offset:39936
	global_load_lds_dwordx4 v134, s[4:5]
	s_mov_b32 m0, s43
	s_nop 0
	global_load_lds_dwordx4 v130, s[4:5]
	s_waitcnt vmcnt(8)
	s_waitcnt lgkmcnt(0)
	s_barrier
	s_setprio 1
	v_mfma_f32_16x16x32_bf16 v[124:127], v[140:143], v[214:217], v[124:127]
	v_mfma_f32_16x16x32_bf16 v[104:107], v[166:169], v[222:225], v[104:107]
	v_mfma_f32_16x16x32_bf16 v[92:95], v[140:143], v[230:233], v[92:95]
	v_mfma_f32_16x16x32_bf16 v[72:75], v[166:169], v[238:241], v[72:75]
	v_mfma_f32_16x16x32_bf16 v[120:123], v[166:169], v[214:217], v[120:123]
	v_mfma_f32_16x16x32_bf16 v[108:111], v[140:143], v[222:225], v[108:111]
	v_mfma_f32_16x16x32_bf16 v[88:91], v[166:169], v[230:233], v[88:91]
	v_mfma_f32_16x16x32_bf16 v[76:79], v[140:143], v[238:241], v[76:79]
	v_mfma_f32_16x16x32_bf16 v[124:127], v[162:165], v[218:221], v[124:127]
	v_mfma_f32_16x16x32_bf16 v[104:107], v[170:173], v[226:229], v[104:107]
	v_mfma_f32_16x16x32_bf16 v[92:95], v[162:165], v[234:237], v[92:95]
	v_mfma_f32_16x16x32_bf16 v[72:75], v[170:173], v[242:245], v[72:75]
	v_mfma_f32_16x16x32_bf16 v[120:123], v[170:173], v[218:221], v[120:123]
	v_mfma_f32_16x16x32_bf16 v[108:111], v[162:165], v[226:229], v[108:111]
	v_mfma_f32_16x16x32_bf16 v[88:91], v[170:173], v[234:237], v[88:91]
	v_mfma_f32_16x16x32_bf16 v[76:79], v[162:165], v[242:245], v[76:79]
	v_mfma_f32_16x16x32_bf16 v[116:119], v[180:183], v[214:217], v[116:119]
	v_mfma_f32_16x16x32_bf16 v[96:99], v[188:191], v[222:225], v[96:99]
	v_mfma_f32_16x16x32_bf16 v[84:87], v[180:183], v[230:233], v[84:87]
	v_mfma_f32_16x16x32_bf16 v[64:67], v[188:191], v[238:241], v[64:67]
	v_mfma_f32_16x16x32_bf16 v[112:115], v[188:191], v[214:217], v[112:115]
	v_mfma_f32_16x16x32_bf16 v[100:103], v[180:183], v[222:225], v[100:103]
	v_mfma_f32_16x16x32_bf16 v[80:83], v[188:191], v[230:233], v[80:83]
	v_mfma_f32_16x16x32_bf16 v[68:71], v[180:183], v[238:241], v[68:71]
	v_mfma_f32_16x16x32_bf16 v[116:119], v[184:187], v[218:221], v[116:119]
	v_mfma_f32_16x16x32_bf16 v[96:99], v[210:213], v[226:229], v[96:99]
	v_mfma_f32_16x16x32_bf16 v[84:87], v[184:187], v[234:237], v[84:87]
	v_mfma_f32_16x16x32_bf16 v[64:67], v[210:213], v[242:245], v[64:67]
	v_mfma_f32_16x16x32_bf16 v[112:115], v[210:213], v[218:221], v[112:115]
	v_mfma_f32_16x16x32_bf16 v[100:103], v[184:187], v[226:229], v[100:103]
	v_mfma_f32_16x16x32_bf16 v[80:83], v[210:213], v[234:237], v[80:83]
	v_mfma_f32_16x16x32_bf16 v[68:71], v[184:187], v[242:245], v[68:71]
	s_setprio 0
	s_barrier
	s_mov_b32 m0, s48
	s_add_u32 s2, s2, 0x40080
	s_addc_u32 s3, s3, 0
	ds_read_b128 v[214:217], v178 offset:49152
	ds_read_b128 v[218:221], v178 offset:50176
	ds_read_b128 v[222:225], v178 offset:51200
	ds_read_b128 v[226:229], v178 offset:52224
	ds_read_b128 v[230:233], v178 offset:53248
	ds_read_b128 v[234:237], v178 offset:54272
	ds_read_b128 v[238:241], v178 offset:55296
	ds_read_b128 v[242:245], v178 offset:56320
	s_add_u32 s98, s2, 0xfffc0000
	s_addc_u32 s99, s3, -1
	global_load_lds_dwordx4 v132, s[98:99]
	s_mov_b32 m0, s49
	s_nop 0
	global_load_lds_dwordx4 v128, s[98:99]
	s_mov_b32 m0, s52
	s_nop 0
	global_load_lds_dwordx4 v132, s[2:3]
	s_mov_b32 m0, s53
	s_nop 0
	global_load_lds_dwordx4 v128, s[2:3]
	s_mov_b32 m0, s50
	s_nop 0
	s_add_u32 s100, s4, 0xfffc0080
	s_addc_u32 s101, s5, -1
	global_load_lds_dwordx4 v134, s[100:101]
	s_mov_b32 m0, s51
	s_nop 0
	global_load_lds_dwordx4 v130, s[100:101]
	s_waitcnt vmcnt(8)
	s_waitcnt lgkmcnt(0)
	s_barrier
	s_setprio 1
	v_mfma_f32_16x16x32_bf16 v[60:63], v[140:143], v[214:217], v[60:63]
	v_mfma_f32_16x16x32_bf16 v[40:43], v[166:169], v[222:225], v[40:43]
	v_mfma_f32_16x16x32_bf16 v[28:31], v[140:143], v[230:233], v[28:31]
	v_mfma_f32_16x16x32_bf16 v[8:11], v[166:169], v[238:241], v[8:11]
	v_mfma_f32_16x16x32_bf16 v[56:59], v[166:169], v[214:217], v[56:59]
	v_mfma_f32_16x16x32_bf16 v[44:47], v[140:143], v[222:225], v[44:47]
	v_mfma_f32_16x16x32_bf16 v[24:27], v[166:169], v[230:233], v[24:27]
	v_mfma_f32_16x16x32_bf16 v[12:15], v[140:143], v[238:241], v[12:15]
	v_mfma_f32_16x16x32_bf16 v[60:63], v[162:165], v[218:221], v[60:63]
	v_mfma_f32_16x16x32_bf16 v[40:43], v[170:173], v[226:229], v[40:43]
	v_mfma_f32_16x16x32_bf16 v[28:31], v[162:165], v[234:237], v[28:31]
	v_mfma_f32_16x16x32_bf16 v[8:11], v[170:173], v[242:245], v[8:11]
	v_mfma_f32_16x16x32_bf16 v[56:59], v[170:173], v[218:221], v[56:59]
	v_mfma_f32_16x16x32_bf16 v[44:47], v[162:165], v[226:229], v[44:47]
	v_mfma_f32_16x16x32_bf16 v[24:27], v[170:173], v[234:237], v[24:27]
	v_mfma_f32_16x16x32_bf16 v[12:15], v[162:165], v[242:245], v[12:15]
	v_mfma_f32_16x16x32_bf16 v[52:55], v[180:183], v[214:217], v[52:55]
	v_mfma_f32_16x16x32_bf16 v[32:35], v[188:191], v[222:225], v[32:35]
	v_mfma_f32_16x16x32_bf16 v[20:23], v[180:183], v[230:233], v[20:23]
	v_mfma_f32_16x16x32_bf16 v[0:3], v[188:191], v[238:241], v[0:3]
	v_mfma_f32_16x16x32_bf16 v[48:51], v[188:191], v[214:217], v[48:51]
	v_mfma_f32_16x16x32_bf16 v[36:39], v[180:183], v[222:225], v[36:39]
	v_mfma_f32_16x16x32_bf16 v[16:19], v[188:191], v[230:233], v[16:19]
	v_mfma_f32_16x16x32_bf16 v[4:7], v[180:183], v[238:241], v[4:7]
	v_mfma_f32_16x16x32_bf16 v[52:55], v[184:187], v[218:221], v[52:55]
	v_mfma_f32_16x16x32_bf16 v[32:35], v[210:213], v[226:229], v[32:35]
	v_mfma_f32_16x16x32_bf16 v[20:23], v[184:187], v[234:237], v[20:23]
	v_mfma_f32_16x16x32_bf16 v[0:3], v[210:213], v[242:245], v[0:3]
	v_mfma_f32_16x16x32_bf16 v[48:51], v[210:213], v[218:221], v[48:51]
	v_mfma_f32_16x16x32_bf16 v[36:39], v[184:187], v[226:229], v[36:39]
	v_mfma_f32_16x16x32_bf16 v[16:19], v[210:213], v[234:237], v[16:19]
	v_mfma_f32_16x16x32_bf16 v[4:7], v[184:187], v[242:245], v[4:7]
	s_setprio 0
	s_barrier
	s_add_i32 s55, s55, 2
	s_add_u32 s0, s0, 0x100
	s_addc_u32 s1, s1, 0
	s_add_u32 s38, s38, 0x100
	s_addc_u32 s39, s39, 0
	s_cmp_gt_u32 s55, 13
	s_cbranch_scc0 .LBB0_749
	s_and_b64 vcc, exec, s[18:19]
	s_cbranch_vccz .LBB0_752
	s_barrier

; #define PG8_STAGE(bufoff, gbase, voff) do { _Pragma("unroll") for (int _i = 0; _i < 2; ++_i) \
;         __builtin_amdgcn_global_load_lds((const unsigned*)((const char*)(gbase) + (voff)[_i]), (PG8_LAS unsigned*)(lds + (bufoff) + ldsw + _i * 8192), 16, 0, 0); } while (0)
; #define PG8_LDA(dst, b, h) do { _Pragma("unroll") for (int m = 0; m < 4; ++m) _Pragma("unroll") for (int k = 0; k < 2; ++k) dst[m][k] = *(const PG8_LAS bf16x8*)(lds + PG8_SA(b, h) + aoff + m * 2048 + k * 1024); } while (0)
; #define PG8_LDB(dst, b, h) do { _Pragma("unroll") for (int n = 0; n < 2; ++n) _Pragma("unroll") for (int k = 0; k < 2; ++k) dst[n][k] = *(const PG8_LAS bf16x8*)(lds + PG8_SB(b, h) + boff + n * 2048 + k * 1024); } while (0)
; #define PG8_MMA(ai, bj, At, Bt) do { __builtin_amdgcn_s_setprio(1); _Pragma("unroll") for (int m = 0; m < 4; ++m) _Pragma("unroll") for (int n = 0; n < 2; ++n) _Pragma("unroll") for (int k = 0; k < 2; ++k) \
;         acc[ai][bj][m][n] = __builtin_amdgcn_mfma_f32_16x16x32_bf16(Bt[n][k], At[m][k], acc[ai][bj][m][n], 0, 0, 0); __builtin_amdgcn_s_setprio(0); } while (0)
; #define PG8_WAIT_V(n) asm volatile("s_waitcnt vmcnt(" #n ")" ::: "memory")
; #define PG8_WAIT_L(n) asm volatile("s_waitcnt lgkmcnt(" #n ")" ::: "memory")
; #define PG8_BAR __builtin_amdgcn_s_barrier()
; #define PG8_SCHED __builtin_amdgcn_sched_barrier(0)
; template <class Epi, class Sched, bool ALIGN_EPI = false, bool SP2 = false>
; __device__ __forceinline__ void gemm_phase(PG8_LAS unsigned char* lds, const Gemm g, const Sched& S, const Epi& E) {
;     ...
;             PG8_LDB(B0, 0, 0); PG8_LDB(B1, 0, 1); PG8_SCHED; PG8_LDA(At, 0, 0); PG8_STAGE(PG8_SA(1, 1), a1 + hstep, voffA);
;             PG8_WAIT_V(8); PG8_WAIT_L(0); PG8_BAR; PG8_MMA(0, 0, At, B0); PG8_MMA(0, 1, At, B1); PG8_BAR; PG8_SCHED;
;             PG8_LDA(At, 0, 1); PG8_STAGE(PG8_SB(0, 0), b2, voffB); PG8_STAGE(PG8_SB(0, 1), b2 + hstep, voffB); PG8_STAGE(PG8_SA(0, 0), a2, voffA);
;             PG8_WAIT_V(8); PG8_WAIT_L(0); PG8_BAR; PG8_MMA(1, 0, At, B0); PG8_MMA(1, 1, At, B1); PG8_BAR; PG8_SCHED;
.Labi_peel:
	s_waitcnt lgkmcnt(0)
	ds_read_b128 v[140:143], v254
	ds_read_b128 v[162:165], v254 offset:1024
	ds_read_b128 v[166:169], v254 offset:2048
	ds_read_b128 v[176:179], v254 offset:3072
	ds_read_b128 v[180:183], v254 offset:16384
	ds_read_b128 v[184:187], v254 offset:17408
	ds_read_b128 v[188:191], v254 offset:18432
	ds_read_b128 v[210:213], v254 offset:19456
	s_add_u32 s2, s0, 0xfffc0080
	s_addc_u32 s3, s1, -1
	s_cmp_eq_u32 s52, 12
	s_cselect_b32 s5, s17, s3
	s_cselect_b32 s4, s48, s2
	s_cselect_b32 s3, s15, s51
	s_cselect_b32 s2, s49, s50
	s_add_i32 m0, s6, 0xc000
	ds_read_b128 v[214:217], v173
	ds_read_b128 v[218:221], v173 offset:1024
	ds_read_b128 v[222:225], v173 offset:2048
	ds_read_b128 v[226:229], v173 offset:3072
	ds_read_b128 v[230:233], v173 offset:4096
	ds_read_b128 v[234:237], v173 offset:5120
	ds_read_b128 v[238:241], v173 offset:6144
	ds_read_b128 v[242:245], v173 offset:7168
	global_load_lds_dwordx4 v136, s[0:1]
	s_add_i32 m0, s6, 0xe000
	s_nop 0
	global_load_lds_dwordx4 v138, s[0:1]
	s_waitcnt vmcnt(8)
	s_waitcnt lgkmcnt(0)
	s_barrier
	s_setprio 1
	v_mfma_f32_16x16x32_bf16 v[124:127], v[140:143], v[214:217], 0
	v_mfma_f32_16x16x32_bf16 v[104:107], v[166:169], v[222:225], 0
	v_mfma_f32_16x16x32_bf16 v[96:99], v[140:143], v[230:233], 0
	v_mfma_f32_16x16x32_bf16 v[72:75], v[166:169], v[238:241], 0
	v_mfma_f32_16x16x32_bf16 v[120:123], v[166:169], v[214:217], 0
	v_mfma_f32_16x16x32_bf16 v[112:115], v[140:143], v[222:225], 0
	v_mfma_f32_16x16x32_bf16 v[88:91], v[166:169], v[230:233], 0
	v_mfma_f32_16x16x32_bf16 v[80:83], v[140:143], v[238:241], 0
	v_mfma_f32_16x16x32_bf16 v[124:127], v[162:165], v[218:221], v[124:127]
	v_mfma_f32_16x16x32_bf16 v[104:107], v[176:179], v[226:229], v[104:107]
	v_mfma_f32_16x16x32_bf16 v[96:99], v[162:165], v[234:237], v[96:99]
	v_mfma_f32_16x16x32_bf16 v[72:75], v[176:179], v[242:245], v[72:75]
	v_mfma_f32_16x16x32_bf16 v[120:123], v[176:179], v[218:221], v[120:123]
	v_mfma_f32_16x16x32_bf16 v[112:115], v[162:165], v[226:229], v[112:115]
	v_mfma_f32_16x16x32_bf16 v[88:91], v[176:179], v[234:237], v[88:91]
	v_mfma_f32_16x16x32_bf16 v[80:83], v[162:165], v[242:245], v[80:83]
	v_mfma_f32_16x16x32_bf16 v[116:119], v[180:183], v[214:217], 0
	v_mfma_f32_16x16x32_bf16 v[92:95], v[188:191], v[222:225], 0
	v_mfma_f32_16x16x32_bf16 v[84:87], v[180:183], v[230:233], 0
	v_mfma_f32_16x16x32_bf16 v[64:67], v[188:191], v[238:241], 0
	v_mfma_f32_16x16x32_bf16 v[108:111], v[188:191], v[214:217], 0
	v_mfma_f32_16x16x32_bf16 v[100:103], v[180:183], v[222:225], 0
	v_mfma_f32_16x16x32_bf16 v[76:79], v[188:191], v[230:233], 0
	v_mfma_f32_16x16x32_bf16 v[68:71], v[180:183], v[238:241], 0
	v_mfma_f32_16x16x32_bf16 v[116:119], v[184:187], v[218:221], v[116:119]
	v_mfma_f32_16x16x32_bf16 v[92:95], v[210:213], v[226:229], v[92:95]
	v_mfma_f32_16x16x32_bf16 v[84:87], v[184:187], v[234:237], v[84:87]
	v_mfma_f32_16x16x32_bf16 v[64:67], v[210:213], v[242:245], v[64:67]
	v_mfma_f32_16x16x32_bf16 v[108:111], v[210:213], v[218:221], v[108:111]
	v_mfma_f32_16x16x32_bf16 v[100:103], v[184:187], v[226:229], v[100:103]
	v_mfma_f32_16x16x32_bf16 v[76:79], v[210:213], v[234:237], v[76:79]
	v_mfma_f32_16x16x32_bf16 v[68:71], v[184:187], v[242:245], v[68:71]
	s_setprio 0
	s_barrier
	s_mov_b32 m0, s27
	s_add_u32 s54, s2, 0x40000
	s_addc_u32 s55, s3, 0
	ds_read_b128 v[214:217], v173 offset:16384
	ds_read_b128 v[218:221], v173 offset:17408
	ds_read_b128 v[222:225], v173 offset:18432
	ds_read_b128 v[226:229], v173 offset:19456
	ds_read_b128 v[230:233], v173 offset:20480
	ds_read_b128 v[234:237], v173 offset:21504
	ds_read_b128 v[238:241], v173 offset:22528
	ds_read_b128 v[242:245], v173 offset:23552
	global_load_lds_dwordx4 v132, s[2:3]
	s_mov_b32 m0, s28
	s_nop 0
	global_load_lds_dwordx4 v128, s[2:3]
	s_mov_b32 m0, s29
	s_nop 0
	global_load_lds_dwordx4 v132, s[54:55]
	s_mov_b32 m0, s30
	s_nop 0
	global_load_lds_dwordx4 v128, s[54:55]
	s_mov_b32 m0, s6
	s_nop 0
	global_load_lds_dwordx4 v134, s[4:5]
	s_mov_b32 m0, s31
	s_nop 0
	global_load_lds_dwordx4 v130, s[4:5]
	s_waitcnt vmcnt(8)
	s_waitcnt lgkmcnt(0)
	s_barrier
	s_setprio 1
	v_mfma_f32_16x16x32_bf16 v[60:63], v[140:143], v[214:217], 0
	v_mfma_f32_16x16x32_bf16 v[40:43], v[166:169], v[222:225], 0
	v_mfma_f32_16x16x32_bf16 v[32:35], v[140:143], v[230:233], 0
	v_mfma_f32_16x16x32_bf16 v[8:11], v[166:169], v[238:241], 0
	v_mfma_f32_16x16x32_bf16 v[56:59], v[166:169], v[214:217], 0
	v_mfma_f32_16x16x32_bf16 v[48:51], v[140:143], v[222:225], 0
	v_mfma_f32_16x16x32_bf16 v[24:27], v[166:169], v[230:233], 0
	v_mfma_f32_16x16x32_bf16 v[16:19], v[140:143], v[238:241], 0
	v_mfma_f32_16x16x32_bf16 v[60:63], v[162:165], v[218:221], v[60:63]
	v_mfma_f32_16x16x32_bf16 v[40:43], v[176:179], v[226:229], v[40:43]
	v_mfma_f32_16x16x32_bf16 v[32:35], v[162:165], v[234:237], v[32:35]
	v_mfma_f32_16x16x32_bf16 v[8:11], v[176:179], v[242:245], v[8:11]
	v_mfma_f32_16x16x32_bf16 v[56:59], v[176:179], v[218:221], v[56:59]
	v_mfma_f32_16x16x32_bf16 v[48:51], v[162:165], v[226:229], v[48:51]
	v_mfma_f32_16x16x32_bf16 v[24:27], v[176:179], v[234:237], v[24:27]
	v_mfma_f32_16x16x32_bf16 v[16:19], v[162:165], v[242:245], v[16:19]
	v_mfma_f32_16x16x32_bf16 v[52:55], v[180:183], v[214:217], 0
	v_mfma_f32_16x16x32_bf16 v[28:31], v[188:191], v[222:225], 0
	v_mfma_f32_16x16x32_bf16 v[20:23], v[180:183], v[230:233], 0
	v_mfma_f32_16x16x32_bf16 v[0:3], v[188:191], v[238:241], 0
	v_mfma_f32_16x16x32_bf16 v[44:47], v[188:191], v[214:217], 0
	v_mfma_f32_16x16x32_bf16 v[36:39], v[180:183], v[222:225], 0
	v_mfma_f32_16x16x32_bf16 v[12:15], v[188:191], v[230:233], 0
	v_mfma_f32_16x16x32_bf16 v[4:7], v[180:183], v[238:241], 0
	v_mfma_f32_16x16x32_bf16 v[52:55], v[184:187], v[218:221], v[52:55]
	v_mfma_f32_16x16x32_bf16 v[28:31], v[210:213], v[226:229], v[28:31]
	v_mfma_f32_16x16x32_bf16 v[20:23], v[184:187], v[234:237], v[20:23]
	v_mfma_f32_16x16x32_bf16 v[0:3], v[210:213], v[242:245], v[0:3]
	v_mfma_f32_16x16x32_bf16 v[44:47], v[210:213], v[218:221], v[44:47]
	v_mfma_f32_16x16x32_bf16 v[36:39], v[184:187], v[226:229], v[36:39]
	v_mfma_f32_16x16x32_bf16 v[12:15], v[210:213], v[234:237], v[12:15]
	v_mfma_f32_16x16x32_bf16 v[4:7], v[184:187], v[242:245], v[4:7]
	s_setprio 0
	s_barrier
; #define PG8_STAGE(bufoff, gbase, voff) do { _Pragma("unroll") for (int _i = 0; _i < 2; ++_i) \
;         __builtin_amdgcn_global_load_lds((const unsigned*)((const char*)(gbase) + (voff)[_i]), (PG8_LAS unsigned*)(lds + (bufoff) + ldsw + _i * 8192), 16, 0, 0); } while (0)
; #define PG8_LDA(dst, b, h) do { _Pragma("unroll") for (int m = 0; m < 4; ++m) _Pragma("unroll") for (int k = 0; k < 2; ++k) dst[m][k] = *(const PG8_LAS bf16x8*)(lds + PG8_SA(b, h) + aoff + m * 2048 + k * 1024); } while (0)
; #define PG8_LDB(dst, b, h) do { _Pragma("unroll") for (int n = 0; n < 2; ++n) _Pragma("unroll") for (int k = 0; k < 2; ++k) dst[n][k] = *(const PG8_LAS bf16x8*)(lds + PG8_SB(b, h) + boff + n * 2048 + k * 1024); } while (0)
; #define PG8_MMA(ai, bj, At, Bt) do { __builtin_amdgcn_s_setprio(1); _Pragma("unroll") for (int m = 0; m < 4; ++m) _Pragma("unroll") for (int n = 0; n < 2; ++n) _Pragma("unroll") for (int k = 0; k < 2; ++k) \
;         acc[ai][bj][m][n] = __builtin_amdgcn_mfma_f32_16x16x32_bf16(Bt[n][k], At[m][k], acc[ai][bj][m][n], 0, 0, 0); __builtin_amdgcn_s_setprio(0); } while (0)
; #define PG8_WAIT_V(n) asm volatile("s_waitcnt vmcnt(" #n ")" ::: "memory")
; #define PG8_WAIT_L(n) asm volatile("s_waitcnt lgkmcnt(" #n ")" ::: "memory")
; #define PG8_BAR __builtin_amdgcn_s_barrier()
; #define PG8_SCHED __builtin_amdgcn_sched_barrier(0)
; template <class Epi, class Sched, bool ALIGN_EPI = false, bool SP2 = false>
; __device__ __forceinline__ void gemm_phase(PG8_LAS unsigned char* lds, const Gemm g, const Sched& S, const Epi& E) {
;     ...
;             PG8_LDB(B0, 1, 0); PG8_LDB(B1, 1, 1); PG8_SCHED; PG8_LDA(At, 1, 0); PG8_STAGE(PG8_SA(0, 1), a2 + hstep, voffA);
;             PG8_WAIT_V(8); PG8_WAIT_L(0); PG8_BAR; PG8_MMA(0, 0, At, B0); PG8_MMA(0, 1, At, B1); PG8_BAR; PG8_SCHED;
;             PG8_LDA(At, 1, 1); PG8_STAGE(PG8_SB(1, 0), b3, voffB); PG8_STAGE(PG8_SB(1, 1), b3 + hstep, voffB); PG8_STAGE(PG8_SA(1, 0), a3, voffA);
;             PG8_WAIT_V(8); PG8_WAIT_L(0); PG8_BAR; PG8_MMA(1, 0, At, B0); PG8_MMA(1, 1, At, B1); PG8_BAR; PG8_SCHED;
	ds_read_b128 v[140:143], v254 offset:32768
	ds_read_b128 v[162:165], v254 offset:33792
	ds_read_b128 v[166:169], v254 offset:34816
	ds_read_b128 v[176:179], v254 offset:35840
	ds_read_b128 v[180:183], v254 offset:49152
	ds_read_b128 v[184:187], v254 offset:50176
	ds_read_b128 v[188:191], v254 offset:51200
	ds_read_b128 v[210:213], v254 offset:52224
	s_add_u32 s4, s4, 0x40000
	s_addc_u32 s5, s5, 0
	s_mov_b32 m0, s33
	ds_read_b128 v[214:217], v173 offset:32768
	ds_read_b128 v[218:221], v173 offset:33792
	ds_read_b128 v[222:225], v173 offset:34816
	ds_read_b128 v[226:229], v173 offset:35840
	ds_read_b128 v[230:233], v173 offset:36864
	ds_read_b128 v[234:237], v173 offset:37888
	ds_read_b128 v[238:241], v173 offset:38912
	ds_read_b128 v[242:245], v173 offset:39936
	global_load_lds_dwordx4 v134, s[4:5]
	s_mov_b32 m0, s34
	s_nop 0
	global_load_lds_dwordx4 v130, s[4:5]
	s_waitcnt vmcnt(8)
	s_waitcnt lgkmcnt(0)
	s_barrier
	s_setprio 1
	v_mfma_f32_16x16x32_bf16 v[124:127], v[140:143], v[214:217], v[124:127]
	v_mfma_f32_16x16x32_bf16 v[104:107], v[166:169], v[222:225], v[104:107]
	v_mfma_f32_16x16x32_bf16 v[96:99], v[140:143], v[230:233], v[96:99]
	v_mfma_f32_16x16x32_bf16 v[72:75], v[166:169], v[238:241], v[72:75]
	v_mfma_f32_16x16x32_bf16 v[120:123], v[166:169], v[214:217], v[120:123]
	v_mfma_f32_16x16x32_bf16 v[112:115], v[140:143], v[222:225], v[112:115]
	v_mfma_f32_16x16x32_bf16 v[88:91], v[166:169], v[230:233], v[88:91]
	v_mfma_f32_16x16x32_bf16 v[80:83], v[140:143], v[238:241], v[80:83]
	v_mfma_f32_16x16x32_bf16 v[124:127], v[162:165], v[218:221], v[124:127]
	v_mfma_f32_16x16x32_bf16 v[104:107], v[176:179], v[226:229], v[104:107]
	v_mfma_f32_16x16x32_bf16 v[96:99], v[162:165], v[234:237], v[96:99]
	v_mfma_f32_16x16x32_bf16 v[72:75], v[176:179], v[242:245], v[72:75]
	v_mfma_f32_16x16x32_bf16 v[120:123], v[176:179], v[218:221], v[120:123]
	v_mfma_f32_16x16x32_bf16 v[112:115], v[162:165], v[226:229], v[112:115]
	v_mfma_f32_16x16x32_bf16 v[88:91], v[176:179], v[234:237], v[88:91]
	v_mfma_f32_16x16x32_bf16 v[80:83], v[162:165], v[242:245], v[80:83]
	v_mfma_f32_16x16x32_bf16 v[116:119], v[180:183], v[214:217], v[116:119]
	v_mfma_f32_16x16x32_bf16 v[92:95], v[188:191], v[222:225], v[92:95]
	v_mfma_f32_16x16x32_bf16 v[84:87], v[180:183], v[230:233], v[84:87]
	v_mfma_f32_16x16x32_bf16 v[64:67], v[188:191], v[238:241], v[64:67]
	v_mfma_f32_16x16x32_bf16 v[108:111], v[188:191], v[214:217], v[108:111]
	v_mfma_f32_16x16x32_bf16 v[100:103], v[180:183], v[222:225], v[100:103]
	v_mfma_f32_16x16x32_bf16 v[76:79], v[188:191], v[230:233], v[76:79]
	v_mfma_f32_16x16x32_bf16 v[68:71], v[180:183], v[238:241], v[68:71]
	v_mfma_f32_16x16x32_bf16 v[116:119], v[184:187], v[218:221], v[116:119]
	v_mfma_f32_16x16x32_bf16 v[92:95], v[210:213], v[226:229], v[92:95]
	v_mfma_f32_16x16x32_bf16 v[84:87], v[184:187], v[234:237], v[84:87]
	v_mfma_f32_16x16x32_bf16 v[64:67], v[210:213], v[242:245], v[64:67]
	v_mfma_f32_16x16x32_bf16 v[108:111], v[210:213], v[218:221], v[108:111]
	v_mfma_f32_16x16x32_bf16 v[100:103], v[184:187], v[226:229], v[100:103]
	v_mfma_f32_16x16x32_bf16 v[76:79], v[210:213], v[234:237], v[76:79]
	v_mfma_f32_16x16x32_bf16 v[68:71], v[184:187], v[242:245], v[68:71]
	s_setprio 0
	s_barrier
	s_mov_b32 m0, s37
	s_add_u32 s2, s2, 0x40080
	s_addc_u32 s3, s3, 0
	ds_read_b128 v[214:217], v173 offset:49152
	ds_read_b128 v[218:221], v173 offset:50176
	ds_read_b128 v[222:225], v173 offset:51200
	ds_read_b128 v[226:229], v173 offset:52224
	ds_read_b128 v[230:233], v173 offset:53248
	ds_read_b128 v[234:237], v173 offset:54272
	ds_read_b128 v[238:241], v173 offset:55296
	ds_read_b128 v[242:245], v173 offset:56320
	s_add_u32 s98, s2, 0xfffc0000
	s_addc_u32 s99, s3, -1
	global_load_lds_dwordx4 v132, s[98:99]
	s_mov_b32 m0, s38
	s_nop 0
	global_load_lds_dwordx4 v128, s[98:99]
	s_mov_b32 m0, s41
	s_nop 0
	global_load_lds_dwordx4 v132, s[2:3]
	s_mov_b32 m0, s42
	s_nop 0
	global_load_lds_dwordx4 v128, s[2:3]
	s_mov_b32 m0, s39
	s_nop 0
	s_add_u32 s100, s4, 0xfffc0080
	s_addc_u32 s101, s5, -1
	global_load_lds_dwordx4 v134, s[100:101]
	s_mov_b32 m0, s40
	s_nop 0
	global_load_lds_dwordx4 v130, s[100:101]
	s_waitcnt vmcnt(8)
	s_waitcnt lgkmcnt(0)
	s_barrier
	s_setprio 1
	v_mfma_f32_16x16x32_bf16 v[60:63], v[140:143], v[214:217], v[60:63]
	v_mfma_f32_16x16x32_bf16 v[40:43], v[166:169], v[222:225], v[40:43]
	v_mfma_f32_16x16x32_bf16 v[32:35], v[140:143], v[230:233], v[32:35]
	v_mfma_f32_16x16x32_bf16 v[8:11], v[166:169], v[238:241], v[8:11]
	v_mfma_f32_16x16x32_bf16 v[56:59], v[166:169], v[214:217], v[56:59]
	v_mfma_f32_16x16x32_bf16 v[48:51], v[140:143], v[222:225], v[48:51]
	v_mfma_f32_16x16x32_bf16 v[24:27], v[166:169], v[230:233], v[24:27]
	v_mfma_f32_16x16x32_bf16 v[16:19], v[140:143], v[238:241], v[16:19]
	v_mfma_f32_16x16x32_bf16 v[60:63], v[162:165], v[218:221], v[60:63]
	v_mfma_f32_16x16x32_bf16 v[40:43], v[176:179], v[226:229], v[40:43]
	v_mfma_f32_16x16x32_bf16 v[32:35], v[162:165], v[234:237], v[32:35]
	v_mfma_f32_16x16x32_bf16 v[8:11], v[176:179], v[242:245], v[8:11]
	v_mfma_f32_16x16x32_bf16 v[56:59], v[176:179], v[218:221], v[56:59]
	v_mfma_f32_16x16x32_bf16 v[48:51], v[162:165], v[226:229], v[48:51]
	v_mfma_f32_16x16x32_bf16 v[24:27], v[176:179], v[234:237], v[24:27]
	v_mfma_f32_16x16x32_bf16 v[16:19], v[162:165], v[242:245], v[16:19]
	v_mfma_f32_16x16x32_bf16 v[52:55], v[180:183], v[214:217], v[52:55]
	v_mfma_f32_16x16x32_bf16 v[28:31], v[188:191], v[222:225], v[28:31]
	v_mfma_f32_16x16x32_bf16 v[20:23], v[180:183], v[230:233], v[20:23]
	v_mfma_f32_16x16x32_bf16 v[0:3], v[188:191], v[238:241], v[0:3]
	v_mfma_f32_16x16x32_bf16 v[44:47], v[188:191], v[214:217], v[44:47]
	v_mfma_f32_16x16x32_bf16 v[36:39], v[180:183], v[222:225], v[36:39]
	v_mfma_f32_16x16x32_bf16 v[12:15], v[188:191], v[230:233], v[12:15]
	v_mfma_f32_16x16x32_bf16 v[4:7], v[180:183], v[238:241], v[4:7]
	v_mfma_f32_16x16x32_bf16 v[52:55], v[184:187], v[218:221], v[52:55]
	v_mfma_f32_16x16x32_bf16 v[28:31], v[210:213], v[226:229], v[28:31]
	v_mfma_f32_16x16x32_bf16 v[20:23], v[184:187], v[234:237], v[20:23]
	v_mfma_f32_16x16x32_bf16 v[0:3], v[210:213], v[242:245], v[0:3]
	v_mfma_f32_16x16x32_bf16 v[44:47], v[210:213], v[218:221], v[44:47]
	v_mfma_f32_16x16x32_bf16 v[36:39], v[184:187], v[226:229], v[36:39]
	v_mfma_f32_16x16x32_bf16 v[12:15], v[210:213], v[234:237], v[12:15]
	v_mfma_f32_16x16x32_bf16 v[4:7], v[184:187], v[242:245], v[4:7]
	s_setprio 0
	s_barrier
	s_add_i32 s52, s52, 2
	s_add_u32 s0, s0, 0x100
	s_addc_u32 s1, s1, 0
	s_add_u32 s50, s50, 0x100
	s_addc_u32 s51, s51, 0
	s_cmp_gt_u32 s52, 13
; #define PG8_STAGE(bufoff, gbase, voff) do { _Pragma("unroll") for (int _i = 0; _i < 2; ++_i) \
;         __builtin_amdgcn_global_load_lds((const unsigned*)((const char*)(gbase) + (voff)[_i]), (PG8_LAS unsigned*)(lds + (bufoff) + ldsw + _i * 8192), 16, 0, 0); } while (0)
; #define PG8_LDA(dst, b, h) do { _Pragma("unroll") for (int m = 0; m < 4; ++m) _Pragma("unroll") for (int k = 0; k < 2; ++k) dst[m][k] = *(const PG8_LAS bf16x8*)(lds + PG8_SA(b, h) + aoff + m * 2048 + k * 1024); } while (0)
; #define PG8_LDB(dst, b, h) do { _Pragma("unroll") for (int n = 0; n < 2; ++n) _Pragma("unroll") for (int k = 0; k < 2; ++k) dst[n][k] = *(const PG8_LAS bf16x8*)(lds + PG8_SB(b, h) + boff + n * 2048 + k * 1024); } while (0)
; #define PG8_MMA(ai, bj, At, Bt) do { __builtin_amdgcn_s_setprio(1); _Pragma("unroll") for (int m = 0; m < 4; ++m) _Pragma("unroll") for (int n = 0; n < 2; ++n) _Pragma("unroll") for (int k = 0; k < 2; ++k) \
;         acc[ai][bj][m][n] = __builtin_amdgcn_mfma_f32_16x16x32_bf16(Bt[n][k], At[m][k], acc[ai][bj][m][n], 0, 0, 0); __builtin_amdgcn_s_setprio(0); } while (0)
; #define PG8_WAIT_V(n) asm volatile("s_waitcnt vmcnt(" #n ")" ::: "memory")
; #define PG8_BAR __builtin_amdgcn_s_barrier()
; template <class Epi, class Sched, bool ALIGN_EPI = false, bool SP2 = false>
; __device__ __forceinline__ void gemm_phase(PG8_LAS unsigned char* lds, const Gemm g, const Sched& S, const Epi& E) {
;     ...
;         for (int t = 0; t < nt; t += 2) {
;             const bool last = (t == nt - 2);
;             const char* a1 = cA + (size_t)(t + 1) * kstep;
;             const char* a2 = last ? nA : cA + (size_t)(t + 2) * kstep; const char* b2 = last ? nB : cB + (size_t)(t + 2) * kstep;
;             const char* a3 = a2 + kstep; const char* b3 = b2 + kstep;
;             if (last && has_next) S.a_ready(nxt);
;             if constexpr (SP2) {
;             PG8_LDB(B0, 0, 0); PG8_LDB(B1, 0, 1); PG8_SCHED; PG8_LDA(At, 0, 0); PG8_STAGE(PG8_SA(1, 1), a1 + hstep, voffA);
;             PG8_WAIT_V(8); PG8_WAIT_L(0); PG8_BAR; PG8_MMA(0, 0, At, B0); PG8_MMA(0, 1, At, B1); PG8_BAR; PG8_SCHED;
;             PG8_LDA(At, 0, 1); PG8_STAGE(PG8_SB(0, 0), b2, voffB); PG8_STAGE(PG8_SB(0, 1), b2 + hstep, voffB); PG8_STAGE(PG8_SA(0, 0), a2, voffA);
;             PG8_WAIT_V(8); PG8_WAIT_L(0); PG8_BAR; PG8_MMA(1, 0, At, B0); PG8_MMA(1, 1, At, B1); PG8_BAR; PG8_SCHED;
.LBB0_792:
	s_waitcnt lgkmcnt(0)
	ds_read_b128 v[140:143], v254
	ds_read_b128 v[162:165], v254 offset:1024
	ds_read_b128 v[166:169], v254 offset:2048
	ds_read_b128 v[176:179], v254 offset:3072
	ds_read_b128 v[180:183], v254 offset:16384
	ds_read_b128 v[184:187], v254 offset:17408
	ds_read_b128 v[188:191], v254 offset:18432
	ds_read_b128 v[210:213], v254 offset:19456
	s_add_u32 s2, s0, 0xfffc0080
	s_addc_u32 s3, s1, -1
	s_cmp_eq_u32 s52, 12
	s_cselect_b32 s5, s17, s3
	s_cselect_b32 s4, s48, s2
	s_cselect_b32 s3, s15, s51
	s_cselect_b32 s2, s49, s50
	s_add_i32 m0, s6, 0xc000
	ds_read_b128 v[214:217], v173
	ds_read_b128 v[218:221], v173 offset:1024
	ds_read_b128 v[222:225], v173 offset:2048
	ds_read_b128 v[226:229], v173 offset:3072
	ds_read_b128 v[230:233], v173 offset:4096
	ds_read_b128 v[234:237], v173 offset:5120
	ds_read_b128 v[238:241], v173 offset:6144
	ds_read_b128 v[242:245], v173 offset:7168
	global_load_lds_dwordx4 v136, s[0:1]
	s_add_i32 m0, s6, 0xe000
	s_nop 0
	global_load_lds_dwordx4 v138, s[0:1]
	s_waitcnt vmcnt(8)
	s_waitcnt lgkmcnt(0)
	s_barrier
	s_setprio 1
	v_mfma_f32_16x16x32_bf16 v[124:127], v[140:143], v[214:217], v[124:127]
	v_mfma_f32_16x16x32_bf16 v[104:107], v[166:169], v[222:225], v[104:107]
	v_mfma_f32_16x16x32_bf16 v[96:99], v[140:143], v[230:233], v[96:99]
	v_mfma_f32_16x16x32_bf16 v[72:75], v[166:169], v[238:241], v[72:75]
	v_mfma_f32_16x16x32_bf16 v[120:123], v[166:169], v[214:217], v[120:123]
	v_mfma_f32_16x16x32_bf16 v[112:115], v[140:143], v[222:225], v[112:115]
	v_mfma_f32_16x16x32_bf16 v[88:91], v[166:169], v[230:233], v[88:91]
	v_mfma_f32_16x16x32_bf16 v[80:83], v[140:143], v[238:241], v[80:83]
	v_mfma_f32_16x16x32_bf16 v[124:127], v[162:165], v[218:221], v[124:127]
	v_mfma_f32_16x16x32_bf16 v[104:107], v[176:179], v[226:229], v[104:107]
	v_mfma_f32_16x16x32_bf16 v[96:99], v[162:165], v[234:237], v[96:99]
	v_mfma_f32_16x16x32_bf16 v[72:75], v[176:179], v[242:245], v[72:75]
	v_mfma_f32_16x16x32_bf16 v[120:123], v[176:179], v[218:221], v[120:123]
	v_mfma_f32_16x16x32_bf16 v[112:115], v[162:165], v[226:229], v[112:115]
	v_mfma_f32_16x16x32_bf16 v[88:91], v[176:179], v[234:237], v[88:91]
	v_mfma_f32_16x16x32_bf16 v[80:83], v[162:165], v[242:245], v[80:83]
	v_mfma_f32_16x16x32_bf16 v[116:119], v[180:183], v[214:217], v[116:119]
	v_mfma_f32_16x16x32_bf16 v[92:95], v[188:191], v[222:225], v[92:95]
	v_mfma_f32_16x16x32_bf16 v[84:87], v[180:183], v[230:233], v[84:87]
	v_mfma_f32_16x16x32_bf16 v[64:67], v[188:191], v[238:241], v[64:67]
	v_mfma_f32_16x16x32_bf16 v[108:111], v[188:191], v[214:217], v[108:111]
	v_mfma_f32_16x16x32_bf16 v[100:103], v[180:183], v[222:225], v[100:103]
	v_mfma_f32_16x16x32_bf16 v[76:79], v[188:191], v[230:233], v[76:79]
	v_mfma_f32_16x16x32_bf16 v[68:71], v[180:183], v[238:241], v[68:71]
	v_mfma_f32_16x16x32_bf16 v[116:119], v[184:187], v[218:221], v[116:119]
	v_mfma_f32_16x16x32_bf16 v[92:95], v[210:213], v[226:229], v[92:95]
	v_mfma_f32_16x16x32_bf16 v[84:87], v[184:187], v[234:237], v[84:87]
	v_mfma_f32_16x16x32_bf16 v[64:67], v[210:213], v[242:245], v[64:67]
	v_mfma_f32_16x16x32_bf16 v[108:111], v[210:213], v[218:221], v[108:111]
	v_mfma_f32_16x16x32_bf16 v[100:103], v[184:187], v[226:229], v[100:103]
	v_mfma_f32_16x16x32_bf16 v[76:79], v[210:213], v[234:237], v[76:79]
	v_mfma_f32_16x16x32_bf16 v[68:71], v[184:187], v[242:245], v[68:71]
	s_setprio 0
	s_barrier
	s_mov_b32 m0, s27
	s_add_u32 s54, s2, 0x40000
	s_addc_u32 s55, s3, 0
	ds_read_b128 v[214:217], v173 offset:16384
	ds_read_b128 v[218:221], v173 offset:17408
	ds_read_b128 v[222:225], v173 offset:18432
	ds_read_b128 v[226:229], v173 offset:19456
	ds_read_b128 v[230:233], v173 offset:20480
	ds_read_b128 v[234:237], v173 offset:21504
	ds_read_b128 v[238:241], v173 offset:22528
	ds_read_b128 v[242:245], v173 offset:23552
	global_load_lds_dwordx4 v132, s[2:3]
	s_mov_b32 m0, s28
	s_nop 0
	global_load_lds_dwordx4 v128, s[2:3]
	s_mov_b32 m0, s29
	s_nop 0
	global_load_lds_dwordx4 v132, s[54:55]
	s_mov_b32 m0, s30
	s_nop 0
	global_load_lds_dwordx4 v128, s[54:55]
	s_mov_b32 m0, s6
	s_nop 0
	global_load_lds_dwordx4 v134, s[4:5]
	s_mov_b32 m0, s31
	s_nop 0
	global_load_lds_dwordx4 v130, s[4:5]
	s_waitcnt vmcnt(8)
	s_waitcnt lgkmcnt(0)
	s_barrier
	s_setprio 1
	v_mfma_f32_16x16x32_bf16 v[60:63], v[140:143], v[214:217], v[60:63]
	v_mfma_f32_16x16x32_bf16 v[40:43], v[166:169], v[222:225], v[40:43]
	v_mfma_f32_16x16x32_bf16 v[32:35], v[140:143], v[230:233], v[32:35]
	v_mfma_f32_16x16x32_bf16 v[8:11], v[166:169], v[238:241], v[8:11]
	v_mfma_f32_16x16x32_bf16 v[56:59], v[166:169], v[214:217], v[56:59]
	v_mfma_f32_16x16x32_bf16 v[48:51], v[140:143], v[222:225], v[48:51]
	v_mfma_f32_16x16x32_bf16 v[24:27], v[166:169], v[230:233], v[24:27]
	v_mfma_f32_16x16x32_bf16 v[16:19], v[140:143], v[238:241], v[16:19]
	v_mfma_f32_16x16x32_bf16 v[60:63], v[162:165], v[218:221], v[60:63]
	v_mfma_f32_16x16x32_bf16 v[40:43], v[176:179], v[226:229], v[40:43]
	v_mfma_f32_16x16x32_bf16 v[32:35], v[162:165], v[234:237], v[32:35]
	v_mfma_f32_16x16x32_bf16 v[8:11], v[176:179], v[242:245], v[8:11]
	v_mfma_f32_16x16x32_bf16 v[56:59], v[176:179], v[218:221], v[56:59]
	v_mfma_f32_16x16x32_bf16 v[48:51], v[162:165], v[226:229], v[48:51]
	v_mfma_f32_16x16x32_bf16 v[24:27], v[176:179], v[234:237], v[24:27]
	v_mfma_f32_16x16x32_bf16 v[16:19], v[162:165], v[242:245], v[16:19]
	v_mfma_f32_16x16x32_bf16 v[52:55], v[180:183], v[214:217], v[52:55]
	v_mfma_f32_16x16x32_bf16 v[28:31], v[188:191], v[222:225], v[28:31]
	v_mfma_f32_16x16x32_bf16 v[20:23], v[180:183], v[230:233], v[20:23]
	v_mfma_f32_16x16x32_bf16 v[0:3], v[188:191], v[238:241], v[0:3]
	v_mfma_f32_16x16x32_bf16 v[44:47], v[188:191], v[214:217], v[44:47]
	v_mfma_f32_16x16x32_bf16 v[36:39], v[180:183], v[222:225], v[36:39]
	v_mfma_f32_16x16x32_bf16 v[12:15], v[188:191], v[230:233], v[12:15]
	v_mfma_f32_16x16x32_bf16 v[4:7], v[180:183], v[238:241], v[4:7]
	v_mfma_f32_16x16x32_bf16 v[52:55], v[184:187], v[218:221], v[52:55]
	v_mfma_f32_16x16x32_bf16 v[28:31], v[210:213], v[226:229], v[28:31]
	v_mfma_f32_16x16x32_bf16 v[20:23], v[184:187], v[234:237], v[20:23]
	v_mfma_f32_16x16x32_bf16 v[0:3], v[210:213], v[242:245], v[0:3]
	v_mfma_f32_16x16x32_bf16 v[44:47], v[210:213], v[218:221], v[44:47]
	v_mfma_f32_16x16x32_bf16 v[36:39], v[184:187], v[226:229], v[36:39]
	v_mfma_f32_16x16x32_bf16 v[12:15], v[210:213], v[234:237], v[12:15]
	v_mfma_f32_16x16x32_bf16 v[4:7], v[184:187], v[242:245], v[4:7]
	s_setprio 0
	s_barrier
; #define PG8_STAGE(bufoff, gbase, voff) do { _Pragma("unroll") for (int _i = 0; _i < 2; ++_i) \
;         __builtin_amdgcn_global_load_lds((const unsigned*)((const char*)(gbase) + (voff)[_i]), (PG8_LAS unsigned*)(lds + (bufoff) + ldsw + _i * 8192), 16, 0, 0); } while (0)
; #define PG8_LDA(dst, b, h) do { _Pragma("unroll") for (int m = 0; m < 4; ++m) _Pragma("unroll") for (int k = 0; k < 2; ++k) dst[m][k] = *(const PG8_LAS bf16x8*)(lds + PG8_SA(b, h) + aoff + m * 2048 + k * 1024); } while (0)
; #define PG8_LDB(dst, b, h) do { _Pragma("unroll") for (int n = 0; n < 2; ++n) _Pragma("unroll") for (int k = 0; k < 2; ++k) dst[n][k] = *(const PG8_LAS bf16x8*)(lds + PG8_SB(b, h) + boff + n * 2048 + k * 1024); } while (0)
; #define PG8_MMA(ai, bj, At, Bt) do { __builtin_amdgcn_s_setprio(1); _Pragma("unroll") for (int m = 0; m < 4; ++m) _Pragma("unroll") for (int n = 0; n < 2; ++n) _Pragma("unroll") for (int k = 0; k < 2; ++k) \
;         acc[ai][bj][m][n] = __builtin_amdgcn_mfma_f32_16x16x32_bf16(Bt[n][k], At[m][k], acc[ai][bj][m][n], 0, 0, 0); __builtin_amdgcn_s_setprio(0); } while (0)
; #define PG8_WAIT_V(n) asm volatile("s_waitcnt vmcnt(" #n ")" ::: "memory")
; #define PG8_WAIT_L(n) asm volatile("s_waitcnt lgkmcnt(" #n ")" ::: "memory")
; #define PG8_BAR __builtin_amdgcn_s_barrier()
; #define PG8_SCHED __builtin_amdgcn_sched_barrier(0)
; template <class Epi, class Sched, bool ALIGN_EPI = false, bool SP2 = false>
; __device__ __forceinline__ void gemm_phase(PG8_LAS unsigned char* lds, const Gemm g, const Sched& S, const Epi& E) {
;     ...
;             PG8_LDB(B0, 1, 0); PG8_LDB(B1, 1, 1); PG8_SCHED; PG8_LDA(At, 1, 0); PG8_STAGE(PG8_SA(0, 1), a2 + hstep, voffA);
;             PG8_WAIT_V(8); PG8_WAIT_L(0); PG8_BAR; PG8_MMA(0, 0, At, B0); PG8_MMA(0, 1, At, B1); PG8_BAR; PG8_SCHED;
;             PG8_LDA(At, 1, 1); PG8_STAGE(PG8_SB(1, 0), b3, voffB); PG8_STAGE(PG8_SB(1, 1), b3 + hstep, voffB); PG8_STAGE(PG8_SA(1, 0), a3, voffA);
;             PG8_WAIT_V(8); PG8_WAIT_L(0); PG8_BAR; PG8_MMA(1, 0, At, B0); PG8_MMA(1, 1, At, B1); PG8_BAR; PG8_SCHED;
	ds_read_b128 v[140:143], v254 offset:32768
	ds_read_b128 v[162:165], v254 offset:33792
	ds_read_b128 v[166:169], v254 offset:34816
	ds_read_b128 v[176:179], v254 offset:35840
	ds_read_b128 v[180:183], v254 offset:49152
	ds_read_b128 v[184:187], v254 offset:50176
	ds_read_b128 v[188:191], v254 offset:51200
	ds_read_b128 v[210:213], v254 offset:52224
	s_add_u32 s4, s4, 0x40000
	s_addc_u32 s5, s5, 0
	s_mov_b32 m0, s33
	ds_read_b128 v[214:217], v173 offset:32768
	ds_read_b128 v[218:221], v173 offset:33792
	ds_read_b128 v[222:225], v173 offset:34816
	ds_read_b128 v[226:229], v173 offset:35840
	ds_read_b128 v[230:233], v173 offset:36864
	ds_read_b128 v[234:237], v173 offset:37888
	ds_read_b128 v[238:241], v173 offset:38912
	ds_read_b128 v[242:245], v173 offset:39936
	global_load_lds_dwordx4 v134, s[4:5]
	s_mov_b32 m0, s34
	s_nop 0
	global_load_lds_dwordx4 v130, s[4:5]
	s_waitcnt vmcnt(8)
	s_waitcnt lgkmcnt(0)
	s_barrier
	s_setprio 1
	v_mfma_f32_16x16x32_bf16 v[124:127], v[140:143], v[214:217], v[124:127]
	v_mfma_f32_16x16x32_bf16 v[104:107], v[166:169], v[222:225], v[104:107]
	v_mfma_f32_16x16x32_bf16 v[96:99], v[140:143], v[230:233], v[96:99]
	v_mfma_f32_16x16x32_bf16 v[72:75], v[166:169], v[238:241], v[72:75]
	v_mfma_f32_16x16x32_bf16 v[120:123], v[166:169], v[214:217], v[120:123]
	v_mfma_f32_16x16x32_bf16 v[112:115], v[140:143], v[222:225], v[112:115]
	v_mfma_f32_16x16x32_bf16 v[88:91], v[166:169], v[230:233], v[88:91]
	v_mfma_f32_16x16x32_bf16 v[80:83], v[140:143], v[238:241], v[80:83]
	v_mfma_f32_16x16x32_bf16 v[124:127], v[162:165], v[218:221], v[124:127]
	v_mfma_f32_16x16x32_bf16 v[104:107], v[176:179], v[226:229], v[104:107]
	v_mfma_f32_16x16x32_bf16 v[96:99], v[162:165], v[234:237], v[96:99]
	v_mfma_f32_16x16x32_bf16 v[72:75], v[176:179], v[242:245], v[72:75]
	v_mfma_f32_16x16x32_bf16 v[120:123], v[176:179], v[218:221], v[120:123]
	v_mfma_f32_16x16x32_bf16 v[112:115], v[162:165], v[226:229], v[112:115]
	v_mfma_f32_16x16x32_bf16 v[88:91], v[176:179], v[234:237], v[88:91]
	v_mfma_f32_16x16x32_bf16 v[80:83], v[162:165], v[242:245], v[80:83]
	v_mfma_f32_16x16x32_bf16 v[116:119], v[180:183], v[214:217], v[116:119]
	v_mfma_f32_16x16x32_bf16 v[92:95], v[188:191], v[222:225], v[92:95]
	v_mfma_f32_16x16x32_bf16 v[84:87], v[180:183], v[230:233], v[84:87]
	v_mfma_f32_16x16x32_bf16 v[64:67], v[188:191], v[238:241], v[64:67]
	v_mfma_f32_16x16x32_bf16 v[108:111], v[188:191], v[214:217], v[108:111]
	v_mfma_f32_16x16x32_bf16 v[100:103], v[180:183], v[222:225], v[100:103]
	v_mfma_f32_16x16x32_bf16 v[76:79], v[188:191], v[230:233], v[76:79]
	v_mfma_f32_16x16x32_bf16 v[68:71], v[180:183], v[238:241], v[68:71]
	v_mfma_f32_16x16x32_bf16 v[116:119], v[184:187], v[218:221], v[116:119]
	v_mfma_f32_16x16x32_bf16 v[92:95], v[210:213], v[226:229], v[92:95]
	v_mfma_f32_16x16x32_bf16 v[84:87], v[184:187], v[234:237], v[84:87]
	v_mfma_f32_16x16x32_bf16 v[64:67], v[210:213], v[242:245], v[64:67]
	v_mfma_f32_16x16x32_bf16 v[108:111], v[210:213], v[218:221], v[108:111]
	v_mfma_f32_16x16x32_bf16 v[100:103], v[184:187], v[226:229], v[100:103]
	v_mfma_f32_16x16x32_bf16 v[76:79], v[210:213], v[234:237], v[76:79]
	v_mfma_f32_16x16x32_bf16 v[68:71], v[184:187], v[242:245], v[68:71]
	s_setprio 0
	s_barrier
	s_mov_b32 m0, s37
	s_add_u32 s2, s2, 0x40080
	s_addc_u32 s3, s3, 0
	ds_read_b128 v[214:217], v173 offset:49152
	ds_read_b128 v[218:221], v173 offset:50176
	ds_read_b128 v[222:225], v173 offset:51200
	ds_read_b128 v[226:229], v173 offset:52224
	ds_read_b128 v[230:233], v173 offset:53248
	ds_read_b128 v[234:237], v173 offset:54272
	ds_read_b128 v[238:241], v173 offset:55296
	ds_read_b128 v[242:245], v173 offset:56320
	s_add_u32 s98, s2, 0xfffc0000
	s_addc_u32 s99, s3, -1
	global_load_lds_dwordx4 v132, s[98:99]
	s_mov_b32 m0, s38
	s_nop 0
	global_load_lds_dwordx4 v128, s[98:99]
	s_mov_b32 m0, s41
	s_nop 0
	global_load_lds_dwordx4 v132, s[2:3]
	s_mov_b32 m0, s42
	s_nop 0
	global_load_lds_dwordx4 v128, s[2:3]
	s_mov_b32 m0, s39
	s_nop 0
	s_add_u32 s100, s4, 0xfffc0080
	s_addc_u32 s101, s5, -1
	global_load_lds_dwordx4 v134, s[100:101]
	s_mov_b32 m0, s40
	s_nop 0
	global_load_lds_dwordx4 v130, s[100:101]
	s_waitcnt vmcnt(8)
	s_waitcnt lgkmcnt(0)
	s_barrier
	s_setprio 1
	v_mfma_f32_16x16x32_bf16 v[60:63], v[140:143], v[214:217], v[60:63]
	v_mfma_f32_16x16x32_bf16 v[40:43], v[166:169], v[222:225], v[40:43]
	v_mfma_f32_16x16x32_bf16 v[32:35], v[140:143], v[230:233], v[32:35]
	v_mfma_f32_16x16x32_bf16 v[8:11], v[166:169], v[238:241], v[8:11]
	v_mfma_f32_16x16x32_bf16 v[56:59], v[166:169], v[214:217], v[56:59]
	v_mfma_f32_16x16x32_bf16 v[48:51], v[140:143], v[222:225], v[48:51]
	v_mfma_f32_16x16x32_bf16 v[24:27], v[166:169], v[230:233], v[24:27]
	v_mfma_f32_16x16x32_bf16 v[16:19], v[140:143], v[238:241], v[16:19]
	v_mfma_f32_16x16x32_bf16 v[60:63], v[162:165], v[218:221], v[60:63]
	v_mfma_f32_16x16x32_bf16 v[40:43], v[176:179], v[226:229], v[40:43]
	v_mfma_f32_16x16x32_bf16 v[32:35], v[162:165], v[234:237], v[32:35]
	v_mfma_f32_16x16x32_bf16 v[8:11], v[176:179], v[242:245], v[8:11]
	v_mfma_f32_16x16x32_bf16 v[56:59], v[176:179], v[218:221], v[56:59]
	v_mfma_f32_16x16x32_bf16 v[48:51], v[162:165], v[226:229], v[48:51]
	v_mfma_f32_16x16x32_bf16 v[24:27], v[176:179], v[234:237], v[24:27]
	v_mfma_f32_16x16x32_bf16 v[16:19], v[162:165], v[242:245], v[16:19]
	v_mfma_f32_16x16x32_bf16 v[52:55], v[180:183], v[214:217], v[52:55]
	v_mfma_f32_16x16x32_bf16 v[28:31], v[188:191], v[222:225], v[28:31]
	v_mfma_f32_16x16x32_bf16 v[20:23], v[180:183], v[230:233], v[20:23]
	v_mfma_f32_16x16x32_bf16 v[0:3], v[188:191], v[238:241], v[0:3]
	v_mfma_f32_16x16x32_bf16 v[44:47], v[188:191], v[214:217], v[44:47]
	v_mfma_f32_16x16x32_bf16 v[36:39], v[180:183], v[222:225], v[36:39]
	v_mfma_f32_16x16x32_bf16 v[12:15], v[188:191], v[230:233], v[12:15]
	v_mfma_f32_16x16x32_bf16 v[4:7], v[180:183], v[238:241], v[4:7]
	v_mfma_f32_16x16x32_bf16 v[52:55], v[184:187], v[218:221], v[52:55]
	v_mfma_f32_16x16x32_bf16 v[28:31], v[210:213], v[226:229], v[28:31]
	v_mfma_f32_16x16x32_bf16 v[20:23], v[184:187], v[234:237], v[20:23]
	v_mfma_f32_16x16x32_bf16 v[0:3], v[210:213], v[242:245], v[0:3]
	v_mfma_f32_16x16x32_bf16 v[44:47], v[210:213], v[218:221], v[44:47]
	v_mfma_f32_16x16x32_bf16 v[36:39], v[184:187], v[226:229], v[36:39]
	v_mfma_f32_16x16x32_bf16 v[12:15], v[210:213], v[234:237], v[12:15]
	v_mfma_f32_16x16x32_bf16 v[4:7], v[184:187], v[242:245], v[4:7]
	s_setprio 0
	s_barrier
	s_add_i32 s52, s52, 2
	s_add_u32 s0, s0, 0x100
	s_addc_u32 s1, s1, 0
	s_add_u32 s50, s50, 0x100
	s_addc_u32 s51, s51, 0
	s_cmp_gt_u32 s52, 13
	s_cbranch_scc0 .LBB0_792
	s_and_b64 vcc, exec, s[12:13]
	s_cbranch_vccz .LBB0_795
	s_barrier

; #define PG8_STAGE(bufoff, gbase, voff) do { _Pragma("unroll") for (int _i = 0; _i < 2; ++_i) \
;         __builtin_amdgcn_global_load_lds((const unsigned*)((const char*)(gbase) + (voff)[_i]), (PG8_LAS unsigned*)(lds + (bufoff) + ldsw + _i * 8192), 16, 0, 0); } while (0)
; #define PG8_LDA(dst, b, h) do { _Pragma("unroll") for (int m = 0; m < 4; ++m) _Pragma("unroll") for (int k = 0; k < 2; ++k) dst[m][k] = *(const PG8_LAS bf16x8*)(lds + PG8_SA(b, h) + aoff + m * 2048 + k * 1024); } while (0)
; #define PG8_LDB(dst, b, h) do { _Pragma("unroll") for (int n = 0; n < 2; ++n) _Pragma("unroll") for (int k = 0; k < 2; ++k) dst[n][k] = *(const PG8_LAS bf16x8*)(lds + PG8_SB(b, h) + boff + n * 2048 + k * 1024); } while (0)
; #define PG8_MMA(ai, bj, At, Bt) do { __builtin_amdgcn_s_setprio(1); _Pragma("unroll") for (int m = 0; m < 4; ++m) _Pragma("unroll") for (int n = 0; n < 2; ++n) _Pragma("unroll") for (int k = 0; k < 2; ++k) \
;         acc[ai][bj][m][n] = __builtin_amdgcn_mfma_f32_16x16x32_bf16(Bt[n][k], At[m][k], acc[ai][bj][m][n], 0, 0, 0); __builtin_amdgcn_s_setprio(0); } while (0)
; #define PG8_WAIT_V(n) asm volatile("s_waitcnt vmcnt(" #n ")" ::: "memory")
; #define PG8_WAIT_L(n) asm volatile("s_waitcnt lgkmcnt(" #n ")" ::: "memory")
; #define PG8_BAR __builtin_amdgcn_s_barrier()
; template <class Epi, class Sched, bool ALIGN_EPI = false, bool SP2 = false>
; __device__ __forceinline__ void gemm_phase(PG8_LAS unsigned char* lds, const Gemm g, const Sched& S, const Epi& E) {
;     ...
;             const char* a1 = cA + (size_t)(t + 1) * kstep;
;             const char* a2 = last ? nA : cA + (size_t)(t + 2) * kstep; const char* b2 = last ? nB : cB + (size_t)(t + 2) * kstep;
;             const char* a3 = a2 + kstep; const char* b3 = b2 + kstep;
;             if (last && has_next) S.a_ready(nxt);
;             if constexpr (SP2) {
;             PG8_LDB(B0, 0, 0); PG8_LDB(B1, 0, 1); PG8_SCHED; PG8_LDA(At, 0, 0); PG8_STAGE(PG8_SA(1, 1), a1 + hstep, voffA);
;             PG8_WAIT_V(8); PG8_WAIT_L(0); PG8_BAR; PG8_MMA(0, 0, At, B0); PG8_MMA(0, 1, At, B1); PG8_BAR; PG8_SCHED;
;             PG8_LDA(At, 0, 1); PG8_STAGE(PG8_SB(0, 0), b2, voffB); PG8_STAGE(PG8_SB(0, 1), b2 + hstep, voffB); PG8_STAGE(PG8_SA(0, 0), a2, voffA);
;             PG8_WAIT_V(8); PG8_WAIT_L(0); PG8_BAR; PG8_MMA(1, 0, At, B0); PG8_MMA(1, 1, At, B1); PG8_BAR; PG8_SCHED;
.Lsgo_peel:
	ds_read_b128 v[140:143], v254
	ds_read_b128 v[166:169], v254 offset:1024
	ds_read_b128 v[170:173], v254 offset:2048
	ds_read_b128 v[174:177], v254 offset:3072
	ds_read_b128 v[178:181], v254 offset:16384
	ds_read_b128 v[182:185], v254 offset:17408
	ds_read_b128 v[186:189], v254 offset:18432
	ds_read_b128 v[210:213], v254 offset:19456
	s_add_u32 s2, s0, 0xfffc0080
	s_addc_u32 s3, s1, -1
	s_cmp_eq_u32 s55, 12
	s_cselect_b32 s5, s23, s3
	s_cselect_b32 s4, s51, s2
	s_cselect_b32 s3, s21, s54
	s_cselect_b32 s2, s52, s53
	s_add_i32 m0, s31, 0xc000
	ds_read_b128 v[214:217], v163
	ds_read_b128 v[218:221], v163 offset:1024
	ds_read_b128 v[222:225], v163 offset:2048
	ds_read_b128 v[226:229], v163 offset:3072
	ds_read_b128 v[230:233], v163 offset:4096
	ds_read_b128 v[234:237], v163 offset:5120
	ds_read_b128 v[238:241], v163 offset:6144
	ds_read_b128 v[242:245], v163 offset:7168
	global_load_lds_dwordx4 v136, s[0:1]
	s_add_i32 m0, s31, 0xe000
	s_nop 0
	global_load_lds_dwordx4 v138, s[0:1]
	s_waitcnt vmcnt(8)
	s_waitcnt lgkmcnt(0)
	s_barrier
	s_setprio 1
	v_mfma_f32_16x16x32_bf16 v[124:127], v[140:143], v[214:217], 0
	v_mfma_f32_16x16x32_bf16 v[104:107], v[170:173], v[222:225], 0
	v_mfma_f32_16x16x32_bf16 v[92:95], v[140:143], v[230:233], 0
	v_mfma_f32_16x16x32_bf16 v[72:75], v[170:173], v[238:241], 0
	v_mfma_f32_16x16x32_bf16 v[120:123], v[170:173], v[214:217], 0
	v_mfma_f32_16x16x32_bf16 v[108:111], v[140:143], v[222:225], 0
	v_mfma_f32_16x16x32_bf16 v[88:91], v[170:173], v[230:233], 0
	v_mfma_f32_16x16x32_bf16 v[76:79], v[140:143], v[238:241], 0
	v_mfma_f32_16x16x32_bf16 v[124:127], v[166:169], v[218:221], v[124:127]
	v_mfma_f32_16x16x32_bf16 v[104:107], v[174:177], v[226:229], v[104:107]
	v_mfma_f32_16x16x32_bf16 v[92:95], v[166:169], v[234:237], v[92:95]
	v_mfma_f32_16x16x32_bf16 v[72:75], v[174:177], v[242:245], v[72:75]
	v_mfma_f32_16x16x32_bf16 v[120:123], v[174:177], v[218:221], v[120:123]
	v_mfma_f32_16x16x32_bf16 v[108:111], v[166:169], v[226:229], v[108:111]
	v_mfma_f32_16x16x32_bf16 v[88:91], v[174:177], v[234:237], v[88:91]
	v_mfma_f32_16x16x32_bf16 v[76:79], v[166:169], v[242:245], v[76:79]
	v_mfma_f32_16x16x32_bf16 v[116:119], v[178:181], v[214:217], 0
	v_mfma_f32_16x16x32_bf16 v[96:99], v[186:189], v[222:225], 0
	v_mfma_f32_16x16x32_bf16 v[84:87], v[178:181], v[230:233], 0
	v_mfma_f32_16x16x32_bf16 v[64:67], v[186:189], v[238:241], 0
	v_mfma_f32_16x16x32_bf16 v[112:115], v[186:189], v[214:217], 0
	v_mfma_f32_16x16x32_bf16 v[100:103], v[178:181], v[222:225], 0
	v_mfma_f32_16x16x32_bf16 v[80:83], v[186:189], v[230:233], 0
	v_mfma_f32_16x16x32_bf16 v[68:71], v[178:181], v[238:241], 0
	v_mfma_f32_16x16x32_bf16 v[116:119], v[182:185], v[218:221], v[116:119]
	v_mfma_f32_16x16x32_bf16 v[96:99], v[210:213], v[226:229], v[96:99]
	v_mfma_f32_16x16x32_bf16 v[84:87], v[182:185], v[234:237], v[84:87]
	v_mfma_f32_16x16x32_bf16 v[64:67], v[210:213], v[242:245], v[64:67]
	v_mfma_f32_16x16x32_bf16 v[112:115], v[210:213], v[218:221], v[112:115]
	v_mfma_f32_16x16x32_bf16 v[100:103], v[182:185], v[226:229], v[100:103]
	v_mfma_f32_16x16x32_bf16 v[80:83], v[210:213], v[234:237], v[80:83]
	v_mfma_f32_16x16x32_bf16 v[68:71], v[182:185], v[242:245], v[68:71]
	s_setprio 0
	s_barrier
	s_mov_b32 m0, s33
	s_add_u32 s56, s2, 0x40000
	s_addc_u32 s57, s3, 0
	ds_read_b128 v[214:217], v163 offset:16384
	ds_read_b128 v[218:221], v163 offset:17408
	ds_read_b128 v[222:225], v163 offset:18432
	ds_read_b128 v[226:229], v163 offset:19456
	ds_read_b128 v[230:233], v163 offset:20480
	ds_read_b128 v[234:237], v163 offset:21504
	ds_read_b128 v[238:241], v163 offset:22528
	ds_read_b128 v[242:245], v163 offset:23552
	global_load_lds_dwordx4 v132, s[2:3]
	s_mov_b32 m0, s34
	s_nop 0
	global_load_lds_dwordx4 v128, s[2:3]
	s_mov_b32 m0, s35
	s_nop 0
	global_load_lds_dwordx4 v132, s[56:57]
	s_mov_b32 m0, s36
	s_nop 0
	global_load_lds_dwordx4 v128, s[56:57]
	s_mov_b32 m0, s31
	s_nop 0
	global_load_lds_dwordx4 v134, s[4:5]
	s_mov_b32 m0, s37
	s_nop 0
	global_load_lds_dwordx4 v130, s[4:5]
	s_waitcnt vmcnt(8)
	s_waitcnt lgkmcnt(0)
	s_barrier
	s_setprio 1
	v_mfma_f32_16x16x32_bf16 v[60:63], v[140:143], v[214:217], 0
	v_mfma_f32_16x16x32_bf16 v[40:43], v[170:173], v[222:225], 0
	v_mfma_f32_16x16x32_bf16 v[28:31], v[140:143], v[230:233], 0
	v_mfma_f32_16x16x32_bf16 v[8:11], v[170:173], v[238:241], 0
	v_mfma_f32_16x16x32_bf16 v[56:59], v[170:173], v[214:217], 0
	v_mfma_f32_16x16x32_bf16 v[44:47], v[140:143], v[222:225], 0
	v_mfma_f32_16x16x32_bf16 v[24:27], v[170:173], v[230:233], 0
	v_mfma_f32_16x16x32_bf16 v[12:15], v[140:143], v[238:241], 0
	v_mfma_f32_16x16x32_bf16 v[60:63], v[166:169], v[218:221], v[60:63]
	v_mfma_f32_16x16x32_bf16 v[40:43], v[174:177], v[226:229], v[40:43]
	v_mfma_f32_16x16x32_bf16 v[28:31], v[166:169], v[234:237], v[28:31]
	v_mfma_f32_16x16x32_bf16 v[8:11], v[174:177], v[242:245], v[8:11]
	v_mfma_f32_16x16x32_bf16 v[56:59], v[174:177], v[218:221], v[56:59]
	v_mfma_f32_16x16x32_bf16 v[44:47], v[166:169], v[226:229], v[44:47]
	v_mfma_f32_16x16x32_bf16 v[24:27], v[174:177], v[234:237], v[24:27]
	v_mfma_f32_16x16x32_bf16 v[12:15], v[166:169], v[242:245], v[12:15]
	v_mfma_f32_16x16x32_bf16 v[52:55], v[178:181], v[214:217], 0
	v_mfma_f32_16x16x32_bf16 v[32:35], v[186:189], v[222:225], 0
	v_mfma_f32_16x16x32_bf16 v[20:23], v[178:181], v[230:233], 0
	v_mfma_f32_16x16x32_bf16 v[0:3], v[186:189], v[238:241], 0
	v_mfma_f32_16x16x32_bf16 v[48:51], v[186:189], v[214:217], 0
	v_mfma_f32_16x16x32_bf16 v[36:39], v[178:181], v[222:225], 0
	v_mfma_f32_16x16x32_bf16 v[16:19], v[186:189], v[230:233], 0
	v_mfma_f32_16x16x32_bf16 v[4:7], v[178:181], v[238:241], 0
	v_mfma_f32_16x16x32_bf16 v[52:55], v[182:185], v[218:221], v[52:55]
	v_mfma_f32_16x16x32_bf16 v[32:35], v[210:213], v[226:229], v[32:35]
	v_mfma_f32_16x16x32_bf16 v[20:23], v[182:185], v[234:237], v[20:23]
	v_mfma_f32_16x16x32_bf16 v[0:3], v[210:213], v[242:245], v[0:3]
	v_mfma_f32_16x16x32_bf16 v[48:51], v[210:213], v[218:221], v[48:51]
	v_mfma_f32_16x16x32_bf16 v[36:39], v[182:185], v[226:229], v[36:39]
	v_mfma_f32_16x16x32_bf16 v[16:19], v[210:213], v[234:237], v[16:19]
	v_mfma_f32_16x16x32_bf16 v[4:7], v[182:185], v[242:245], v[4:7]
	s_setprio 0
	s_barrier
; #define PG8_STAGE(bufoff, gbase, voff) do { _Pragma("unroll") for (int _i = 0; _i < 2; ++_i) \
;         __builtin_amdgcn_global_load_lds((const unsigned*)((const char*)(gbase) + (voff)[_i]), (PG8_LAS unsigned*)(lds + (bufoff) + ldsw + _i * 8192), 16, 0, 0); } while (0)
; #define PG8_LDA(dst, b, h) do { _Pragma("unroll") for (int m = 0; m < 4; ++m) _Pragma("unroll") for (int k = 0; k < 2; ++k) dst[m][k] = *(const PG8_LAS bf16x8*)(lds + PG8_SA(b, h) + aoff + m * 2048 + k * 1024); } while (0)
; #define PG8_LDB(dst, b, h) do { _Pragma("unroll") for (int n = 0; n < 2; ++n) _Pragma("unroll") for (int k = 0; k < 2; ++k) dst[n][k] = *(const PG8_LAS bf16x8*)(lds + PG8_SB(b, h) + boff + n * 2048 + k * 1024); } while (0)
; #define PG8_MMA(ai, bj, At, Bt) do { __builtin_amdgcn_s_setprio(1); _Pragma("unroll") for (int m = 0; m < 4; ++m) _Pragma("unroll") for (int n = 0; n < 2; ++n) _Pragma("unroll") for (int k = 0; k < 2; ++k) \
;         acc[ai][bj][m][n] = __builtin_amdgcn_mfma_f32_16x16x32_bf16(Bt[n][k], At[m][k], acc[ai][bj][m][n], 0, 0, 0); __builtin_amdgcn_s_setprio(0); } while (0)
; #define PG8_WAIT_V(n) asm volatile("s_waitcnt vmcnt(" #n ")" ::: "memory")
; #define PG8_WAIT_L(n) asm volatile("s_waitcnt lgkmcnt(" #n ")" ::: "memory")
; #define PG8_BAR __builtin_amdgcn_s_barrier()
; #define PG8_SCHED __builtin_amdgcn_sched_barrier(0)
; template <class Epi, class Sched, bool ALIGN_EPI = false, bool SP2 = false>
; __device__ __forceinline__ void gemm_phase(PG8_LAS unsigned char* lds, const Gemm g, const Sched& S, const Epi& E) {
;     ...
;             PG8_LDB(B0, 1, 0); PG8_LDB(B1, 1, 1); PG8_SCHED; PG8_LDA(At, 1, 0); PG8_STAGE(PG8_SA(0, 1), a2 + hstep, voffA);
;             PG8_WAIT_V(8); PG8_WAIT_L(0); PG8_BAR; PG8_MMA(0, 0, At, B0); PG8_MMA(0, 1, At, B1); PG8_BAR; PG8_SCHED;
;             PG8_LDA(At, 1, 1); PG8_STAGE(PG8_SB(1, 0), b3, voffB); PG8_STAGE(PG8_SB(1, 1), b3 + hstep, voffB); PG8_STAGE(PG8_SA(1, 0), a3, voffA);
;             PG8_WAIT_V(8); PG8_WAIT_L(0); PG8_BAR; PG8_MMA(1, 0, At, B0); PG8_MMA(1, 1, At, B1); PG8_BAR; PG8_SCHED;
	ds_read_b128 v[140:143], v254 offset:32768
	ds_read_b128 v[166:169], v254 offset:33792
	ds_read_b128 v[170:173], v254 offset:34816
	ds_read_b128 v[174:177], v254 offset:35840
	ds_read_b128 v[178:181], v254 offset:49152
	ds_read_b128 v[182:185], v254 offset:50176
	ds_read_b128 v[186:189], v254 offset:51200
	ds_read_b128 v[210:213], v254 offset:52224
	s_add_u32 s4, s4, 0x40000
	s_addc_u32 s5, s5, 0
	s_mov_b32 m0, s38
	ds_read_b128 v[214:217], v163 offset:32768
	ds_read_b128 v[218:221], v163 offset:33792
	ds_read_b128 v[222:225], v163 offset:34816
	ds_read_b128 v[226:229], v163 offset:35840
	ds_read_b128 v[230:233], v163 offset:36864
	ds_read_b128 v[234:237], v163 offset:37888
	ds_read_b128 v[238:241], v163 offset:38912
	ds_read_b128 v[242:245], v163 offset:39936
	global_load_lds_dwordx4 v134, s[4:5]
	s_mov_b32 m0, s39
	s_nop 0
	global_load_lds_dwordx4 v130, s[4:5]
	s_waitcnt vmcnt(8)
	s_waitcnt lgkmcnt(0)
	s_barrier
	s_setprio 1
	v_mfma_f32_16x16x32_bf16 v[124:127], v[140:143], v[214:217], v[124:127]
	v_mfma_f32_16x16x32_bf16 v[104:107], v[170:173], v[222:225], v[104:107]
	v_mfma_f32_16x16x32_bf16 v[92:95], v[140:143], v[230:233], v[92:95]
	v_mfma_f32_16x16x32_bf16 v[72:75], v[170:173], v[238:241], v[72:75]
	v_mfma_f32_16x16x32_bf16 v[120:123], v[170:173], v[214:217], v[120:123]
	v_mfma_f32_16x16x32_bf16 v[108:111], v[140:143], v[222:225], v[108:111]
	v_mfma_f32_16x16x32_bf16 v[88:91], v[170:173], v[230:233], v[88:91]
	v_mfma_f32_16x16x32_bf16 v[76:79], v[140:143], v[238:241], v[76:79]
	v_mfma_f32_16x16x32_bf16 v[124:127], v[166:169], v[218:221], v[124:127]
	v_mfma_f32_16x16x32_bf16 v[104:107], v[174:177], v[226:229], v[104:107]
	v_mfma_f32_16x16x32_bf16 v[92:95], v[166:169], v[234:237], v[92:95]
	v_mfma_f32_16x16x32_bf16 v[72:75], v[174:177], v[242:245], v[72:75]
	v_mfma_f32_16x16x32_bf16 v[120:123], v[174:177], v[218:221], v[120:123]
	v_mfma_f32_16x16x32_bf16 v[108:111], v[166:169], v[226:229], v[108:111]
	v_mfma_f32_16x16x32_bf16 v[88:91], v[174:177], v[234:237], v[88:91]
	v_mfma_f32_16x16x32_bf16 v[76:79], v[166:169], v[242:245], v[76:79]
	v_mfma_f32_16x16x32_bf16 v[116:119], v[178:181], v[214:217], v[116:119]
	v_mfma_f32_16x16x32_bf16 v[96:99], v[186:189], v[222:225], v[96:99]
	v_mfma_f32_16x16x32_bf16 v[84:87], v[178:181], v[230:233], v[84:87]
	v_mfma_f32_16x16x32_bf16 v[64:67], v[186:189], v[238:241], v[64:67]
	v_mfma_f32_16x16x32_bf16 v[112:115], v[186:189], v[214:217], v[112:115]
	v_mfma_f32_16x16x32_bf16 v[100:103], v[178:181], v[222:225], v[100:103]
	v_mfma_f32_16x16x32_bf16 v[80:83], v[186:189], v[230:233], v[80:83]
	v_mfma_f32_16x16x32_bf16 v[68:71], v[178:181], v[238:241], v[68:71]
	v_mfma_f32_16x16x32_bf16 v[116:119], v[182:185], v[218:221], v[116:119]
	v_mfma_f32_16x16x32_bf16 v[96:99], v[210:213], v[226:229], v[96:99]
	v_mfma_f32_16x16x32_bf16 v[84:87], v[182:185], v[234:237], v[84:87]
	v_mfma_f32_16x16x32_bf16 v[64:67], v[210:213], v[242:245], v[64:67]
	v_mfma_f32_16x16x32_bf16 v[112:115], v[210:213], v[218:221], v[112:115]
	v_mfma_f32_16x16x32_bf16 v[100:103], v[182:185], v[226:229], v[100:103]
	v_mfma_f32_16x16x32_bf16 v[80:83], v[210:213], v[234:237], v[80:83]
	v_mfma_f32_16x16x32_bf16 v[68:71], v[182:185], v[242:245], v[68:71]
	s_setprio 0
	s_barrier
	s_mov_b32 m0, s43
	s_add_u32 s2, s2, 0x40080
	s_addc_u32 s3, s3, 0
	ds_read_b128 v[214:217], v163 offset:49152
	ds_read_b128 v[218:221], v163 offset:50176
	ds_read_b128 v[222:225], v163 offset:51200
	ds_read_b128 v[226:229], v163 offset:52224
	ds_read_b128 v[230:233], v163 offset:53248
	ds_read_b128 v[234:237], v163 offset:54272
	ds_read_b128 v[238:241], v163 offset:55296
	ds_read_b128 v[242:245], v163 offset:56320
	s_add_u32 s98, s2, 0xfffc0000
	s_addc_u32 s99, s3, -1
	global_load_lds_dwordx4 v132, s[98:99]
	s_mov_b32 m0, s44
	s_nop 0
	global_load_lds_dwordx4 v128, s[98:99]
	s_mov_b32 m0, s48
	s_nop 0
	global_load_lds_dwordx4 v132, s[2:3]
	s_mov_b32 m0, s49
	s_nop 0
	global_load_lds_dwordx4 v128, s[2:3]
	s_mov_b32 m0, s45
	s_nop 0
	s_add_u32 s100, s4, 0xfffc0080
	s_addc_u32 s101, s5, -1
	global_load_lds_dwordx4 v134, s[100:101]
	s_mov_b32 m0, s47
	s_nop 0
	global_load_lds_dwordx4 v130, s[100:101]
	s_waitcnt vmcnt(8)
	s_waitcnt lgkmcnt(0)
	s_barrier
	s_setprio 1
	v_mfma_f32_16x16x32_bf16 v[60:63], v[140:143], v[214:217], v[60:63]
	v_mfma_f32_16x16x32_bf16 v[40:43], v[170:173], v[222:225], v[40:43]
	v_mfma_f32_16x16x32_bf16 v[28:31], v[140:143], v[230:233], v[28:31]
	v_mfma_f32_16x16x32_bf16 v[8:11], v[170:173], v[238:241], v[8:11]
	v_mfma_f32_16x16x32_bf16 v[56:59], v[170:173], v[214:217], v[56:59]
	v_mfma_f32_16x16x32_bf16 v[44:47], v[140:143], v[222:225], v[44:47]
	v_mfma_f32_16x16x32_bf16 v[24:27], v[170:173], v[230:233], v[24:27]
	v_mfma_f32_16x16x32_bf16 v[12:15], v[140:143], v[238:241], v[12:15]
	v_mfma_f32_16x16x32_bf16 v[60:63], v[166:169], v[218:221], v[60:63]
	v_mfma_f32_16x16x32_bf16 v[40:43], v[174:177], v[226:229], v[40:43]
	v_mfma_f32_16x16x32_bf16 v[28:31], v[166:169], v[234:237], v[28:31]
	v_mfma_f32_16x16x32_bf16 v[8:11], v[174:177], v[242:245], v[8:11]
	v_mfma_f32_16x16x32_bf16 v[56:59], v[174:177], v[218:221], v[56:59]
	v_mfma_f32_16x16x32_bf16 v[44:47], v[166:169], v[226:229], v[44:47]
	v_mfma_f32_16x16x32_bf16 v[24:27], v[174:177], v[234:237], v[24:27]
	v_mfma_f32_16x16x32_bf16 v[12:15], v[166:169], v[242:245], v[12:15]
	v_mfma_f32_16x16x32_bf16 v[52:55], v[178:181], v[214:217], v[52:55]
	v_mfma_f32_16x16x32_bf16 v[32:35], v[186:189], v[222:225], v[32:35]
	v_mfma_f32_16x16x32_bf16 v[20:23], v[178:181], v[230:233], v[20:23]
	v_mfma_f32_16x16x32_bf16 v[0:3], v[186:189], v[238:241], v[0:3]
	v_mfma_f32_16x16x32_bf16 v[48:51], v[186:189], v[214:217], v[48:51]
	v_mfma_f32_16x16x32_bf16 v[36:39], v[178:181], v[222:225], v[36:39]
	v_mfma_f32_16x16x32_bf16 v[16:19], v[186:189], v[230:233], v[16:19]
	v_mfma_f32_16x16x32_bf16 v[4:7], v[178:181], v[238:241], v[4:7]
	v_mfma_f32_16x16x32_bf16 v[52:55], v[182:185], v[218:221], v[52:55]
	v_mfma_f32_16x16x32_bf16 v[32:35], v[210:213], v[226:229], v[32:35]
	v_mfma_f32_16x16x32_bf16 v[20:23], v[182:185], v[234:237], v[20:23]
	v_mfma_f32_16x16x32_bf16 v[0:3], v[210:213], v[242:245], v[0:3]
	v_mfma_f32_16x16x32_bf16 v[48:51], v[210:213], v[218:221], v[48:51]
	v_mfma_f32_16x16x32_bf16 v[36:39], v[182:185], v[226:229], v[36:39]
	v_mfma_f32_16x16x32_bf16 v[16:19], v[210:213], v[234:237], v[16:19]
	v_mfma_f32_16x16x32_bf16 v[4:7], v[182:185], v[242:245], v[4:7]
	s_setprio 0
	s_barrier
	s_add_i32 s55, s55, 2
	s_add_u32 s0, s0, 0x100
	s_addc_u32 s1, s1, 0
	s_add_u32 s53, s53, 0x100
	s_addc_u32 s54, s54, 0
	s_cmp_gt_u32 s55, 13
; #define PG8_STAGE(bufoff, gbase, voff) do { _Pragma("unroll") for (int _i = 0; _i < 2; ++_i) \
;         __builtin_amdgcn_global_load_lds((const unsigned*)((const char*)(gbase) + (voff)[_i]), (PG8_LAS unsigned*)(lds + (bufoff) + ldsw + _i * 8192), 16, 0, 0); } while (0)
; #define PG8_LDA(dst, b, h) do { _Pragma("unroll") for (int m = 0; m < 4; ++m) _Pragma("unroll") for (int k = 0; k < 2; ++k) dst[m][k] = *(const PG8_LAS bf16x8*)(lds + PG8_SA(b, h) + aoff + m * 2048 + k * 1024); } while (0)
; #define PG8_LDB(dst, b, h) do { _Pragma("unroll") for (int n = 0; n < 2; ++n) _Pragma("unroll") for (int k = 0; k < 2; ++k) dst[n][k] = *(const PG8_LAS bf16x8*)(lds + PG8_SB(b, h) + boff + n * 2048 + k * 1024); } while (0)
; #define PG8_MMA(ai, bj, At, Bt) do { __builtin_amdgcn_s_setprio(1); _Pragma("unroll") for (int m = 0; m < 4; ++m) _Pragma("unroll") for (int n = 0; n < 2; ++n) _Pragma("unroll") for (int k = 0; k < 2; ++k) \
;         acc[ai][bj][m][n] = __builtin_amdgcn_mfma_f32_16x16x32_bf16(Bt[n][k], At[m][k], acc[ai][bj][m][n], 0, 0, 0); __builtin_amdgcn_s_setprio(0); } while (0)
; #define PG8_WAIT_V(n) asm volatile("s_waitcnt vmcnt(" #n ")" ::: "memory")
; #define PG8_BAR __builtin_amdgcn_s_barrier()
; template <class Epi, class Sched, bool ALIGN_EPI = false, bool SP2 = false>
; __device__ __forceinline__ void gemm_phase(PG8_LAS unsigned char* lds, const Gemm g, const Sched& S, const Epi& E) {
;     ...
;         for (int t = 0; t < nt; t += 2) {
;             const bool last = (t == nt - 2);
;             const char* a1 = cA + (size_t)(t + 1) * kstep;
;             const char* a2 = last ? nA : cA + (size_t)(t + 2) * kstep; const char* b2 = last ? nB : cB + (size_t)(t + 2) * kstep;
;             const char* a3 = a2 + kstep; const char* b3 = b2 + kstep;
;             if (last && has_next) S.a_ready(nxt);
;             if constexpr (SP2) {
;             PG8_LDB(B0, 0, 0); PG8_LDB(B1, 0, 1); PG8_SCHED; PG8_LDA(At, 0, 0); PG8_STAGE(PG8_SA(1, 1), a1 + hstep, voffA);
;             PG8_WAIT_V(8); PG8_WAIT_L(0); PG8_BAR; PG8_MMA(0, 0, At, B0); PG8_MMA(0, 1, At, B1); PG8_BAR; PG8_SCHED;
;             PG8_LDA(At, 0, 1); PG8_STAGE(PG8_SB(0, 0), b2, voffB); PG8_STAGE(PG8_SB(0, 1), b2 + hstep, voffB); PG8_STAGE(PG8_SA(0, 0), a2, voffA);
;             PG8_WAIT_V(8); PG8_WAIT_L(0); PG8_BAR; PG8_MMA(1, 0, At, B0); PG8_MMA(1, 1, At, B1); PG8_BAR; PG8_SCHED;
.LBB0_1042:
	ds_read_b128 v[140:143], v254
	ds_read_b128 v[166:169], v254 offset:1024
	ds_read_b128 v[170:173], v254 offset:2048
	ds_read_b128 v[174:177], v254 offset:3072
	ds_read_b128 v[178:181], v254 offset:16384
	ds_read_b128 v[182:185], v254 offset:17408
	ds_read_b128 v[186:189], v254 offset:18432
	ds_read_b128 v[210:213], v254 offset:19456
	s_add_u32 s2, s0, 0xfffc0080
	s_addc_u32 s3, s1, -1
	s_cmp_eq_u32 s55, 12
	s_cselect_b32 s5, s23, s3
	s_cselect_b32 s4, s51, s2
	s_cselect_b32 s3, s21, s54
	s_cselect_b32 s2, s52, s53
	s_add_i32 m0, s31, 0xc000
	ds_read_b128 v[214:217], v163
	ds_read_b128 v[218:221], v163 offset:1024
	ds_read_b128 v[222:225], v163 offset:2048
	ds_read_b128 v[226:229], v163 offset:3072
	ds_read_b128 v[230:233], v163 offset:4096
	ds_read_b128 v[234:237], v163 offset:5120
	ds_read_b128 v[238:241], v163 offset:6144
	ds_read_b128 v[242:245], v163 offset:7168
	global_load_lds_dwordx4 v136, s[0:1]
	s_add_i32 m0, s31, 0xe000
	s_nop 0
	global_load_lds_dwordx4 v138, s[0:1]
	s_waitcnt vmcnt(8)
	s_waitcnt lgkmcnt(0)
	s_barrier
	s_setprio 1
	v_mfma_f32_16x16x32_bf16 v[124:127], v[140:143], v[214:217], v[124:127]
	v_mfma_f32_16x16x32_bf16 v[104:107], v[170:173], v[222:225], v[104:107]
	v_mfma_f32_16x16x32_bf16 v[92:95], v[140:143], v[230:233], v[92:95]
	v_mfma_f32_16x16x32_bf16 v[72:75], v[170:173], v[238:241], v[72:75]
	v_mfma_f32_16x16x32_bf16 v[120:123], v[170:173], v[214:217], v[120:123]
	v_mfma_f32_16x16x32_bf16 v[108:111], v[140:143], v[222:225], v[108:111]
	v_mfma_f32_16x16x32_bf16 v[88:91], v[170:173], v[230:233], v[88:91]
	v_mfma_f32_16x16x32_bf16 v[76:79], v[140:143], v[238:241], v[76:79]
	v_mfma_f32_16x16x32_bf16 v[124:127], v[166:169], v[218:221], v[124:127]
	v_mfma_f32_16x16x32_bf16 v[104:107], v[174:177], v[226:229], v[104:107]
	v_mfma_f32_16x16x32_bf16 v[92:95], v[166:169], v[234:237], v[92:95]
	v_mfma_f32_16x16x32_bf16 v[72:75], v[174:177], v[242:245], v[72:75]
	v_mfma_f32_16x16x32_bf16 v[120:123], v[174:177], v[218:221], v[120:123]
	v_mfma_f32_16x16x32_bf16 v[108:111], v[166:169], v[226:229], v[108:111]
	v_mfma_f32_16x16x32_bf16 v[88:91], v[174:177], v[234:237], v[88:91]
	v_mfma_f32_16x16x32_bf16 v[76:79], v[166:169], v[242:245], v[76:79]
	v_mfma_f32_16x16x32_bf16 v[116:119], v[178:181], v[214:217], v[116:119]
	v_mfma_f32_16x16x32_bf16 v[96:99], v[186:189], v[222:225], v[96:99]
	v_mfma_f32_16x16x32_bf16 v[84:87], v[178:181], v[230:233], v[84:87]
	v_mfma_f32_16x16x32_bf16 v[64:67], v[186:189], v[238:241], v[64:67]
	v_mfma_f32_16x16x32_bf16 v[112:115], v[186:189], v[214:217], v[112:115]
	v_mfma_f32_16x16x32_bf16 v[100:103], v[178:181], v[222:225], v[100:103]
	v_mfma_f32_16x16x32_bf16 v[80:83], v[186:189], v[230:233], v[80:83]
	v_mfma_f32_16x16x32_bf16 v[68:71], v[178:181], v[238:241], v[68:71]
	v_mfma_f32_16x16x32_bf16 v[116:119], v[182:185], v[218:221], v[116:119]
	v_mfma_f32_16x16x32_bf16 v[96:99], v[210:213], v[226:229], v[96:99]
	v_mfma_f32_16x16x32_bf16 v[84:87], v[182:185], v[234:237], v[84:87]
	v_mfma_f32_16x16x32_bf16 v[64:67], v[210:213], v[242:245], v[64:67]
	v_mfma_f32_16x16x32_bf16 v[112:115], v[210:213], v[218:221], v[112:115]
	v_mfma_f32_16x16x32_bf16 v[100:103], v[182:185], v[226:229], v[100:103]
	v_mfma_f32_16x16x32_bf16 v[80:83], v[210:213], v[234:237], v[80:83]
	v_mfma_f32_16x16x32_bf16 v[68:71], v[182:185], v[242:245], v[68:71]
	s_setprio 0
	s_barrier
	s_mov_b32 m0, s33
	s_add_u32 s56, s2, 0x40000
	s_addc_u32 s57, s3, 0
	ds_read_b128 v[214:217], v163 offset:16384
	ds_read_b128 v[218:221], v163 offset:17408
	ds_read_b128 v[222:225], v163 offset:18432
	ds_read_b128 v[226:229], v163 offset:19456
	ds_read_b128 v[230:233], v163 offset:20480
	ds_read_b128 v[234:237], v163 offset:21504
	ds_read_b128 v[238:241], v163 offset:22528
	ds_read_b128 v[242:245], v163 offset:23552
	global_load_lds_dwordx4 v132, s[2:3]
	s_mov_b32 m0, s34
	s_nop 0
	global_load_lds_dwordx4 v128, s[2:3]
	s_mov_b32 m0, s35
	s_nop 0
	global_load_lds_dwordx4 v132, s[56:57]
	s_mov_b32 m0, s36
	s_nop 0
	global_load_lds_dwordx4 v128, s[56:57]
	s_mov_b32 m0, s31
	s_nop 0
	global_load_lds_dwordx4 v134, s[4:5]
	s_mov_b32 m0, s37
	s_nop 0
	global_load_lds_dwordx4 v130, s[4:5]
	s_waitcnt vmcnt(8)
	s_waitcnt lgkmcnt(0)
	s_barrier
	s_setprio 1
	v_mfma_f32_16x16x32_bf16 v[60:63], v[140:143], v[214:217], v[60:63]
	v_mfma_f32_16x16x32_bf16 v[40:43], v[170:173], v[222:225], v[40:43]
	v_mfma_f32_16x16x32_bf16 v[28:31], v[140:143], v[230:233], v[28:31]
	v_mfma_f32_16x16x32_bf16 v[8:11], v[170:173], v[238:241], v[8:11]
	v_mfma_f32_16x16x32_bf16 v[56:59], v[170:173], v[214:217], v[56:59]
	v_mfma_f32_16x16x32_bf16 v[44:47], v[140:143], v[222:225], v[44:47]
	v_mfma_f32_16x16x32_bf16 v[24:27], v[170:173], v[230:233], v[24:27]
	v_mfma_f32_16x16x32_bf16 v[12:15], v[140:143], v[238:241], v[12:15]
	v_mfma_f32_16x16x32_bf16 v[60:63], v[166:169], v[218:221], v[60:63]
	v_mfma_f32_16x16x32_bf16 v[40:43], v[174:177], v[226:229], v[40:43]
	v_mfma_f32_16x16x32_bf16 v[28:31], v[166:169], v[234:237], v[28:31]
	v_mfma_f32_16x16x32_bf16 v[8:11], v[174:177], v[242:245], v[8:11]
	v_mfma_f32_16x16x32_bf16 v[56:59], v[174:177], v[218:221], v[56:59]
	v_mfma_f32_16x16x32_bf16 v[44:47], v[166:169], v[226:229], v[44:47]
	v_mfma_f32_16x16x32_bf16 v[24:27], v[174:177], v[234:237], v[24:27]
	v_mfma_f32_16x16x32_bf16 v[12:15], v[166:169], v[242:245], v[12:15]
	v_mfma_f32_16x16x32_bf16 v[52:55], v[178:181], v[214:217], v[52:55]
	v_mfma_f32_16x16x32_bf16 v[32:35], v[186:189], v[222:225], v[32:35]
	v_mfma_f32_16x16x32_bf16 v[20:23], v[178:181], v[230:233], v[20:23]
	v_mfma_f32_16x16x32_bf16 v[0:3], v[186:189], v[238:241], v[0:3]
	v_mfma_f32_16x16x32_bf16 v[48:51], v[186:189], v[214:217], v[48:51]
	v_mfma_f32_16x16x32_bf16 v[36:39], v[178:181], v[222:225], v[36:39]
	v_mfma_f32_16x16x32_bf16 v[16:19], v[186:189], v[230:233], v[16:19]
	v_mfma_f32_16x16x32_bf16 v[4:7], v[178:181], v[238:241], v[4:7]
	v_mfma_f32_16x16x32_bf16 v[52:55], v[182:185], v[218:221], v[52:55]
	v_mfma_f32_16x16x32_bf16 v[32:35], v[210:213], v[226:229], v[32:35]
	v_mfma_f32_16x16x32_bf16 v[20:23], v[182:185], v[234:237], v[20:23]
	v_mfma_f32_16x16x32_bf16 v[0:3], v[210:213], v[242:245], v[0:3]
	v_mfma_f32_16x16x32_bf16 v[48:51], v[210:213], v[218:221], v[48:51]
	v_mfma_f32_16x16x32_bf16 v[36:39], v[182:185], v[226:229], v[36:39]
	v_mfma_f32_16x16x32_bf16 v[16:19], v[210:213], v[234:237], v[16:19]
	v_mfma_f32_16x16x32_bf16 v[4:7], v[182:185], v[242:245], v[4:7]
	s_setprio 0
	s_barrier
; #define PG8_STAGE(bufoff, gbase, voff) do { _Pragma("unroll") for (int _i = 0; _i < 2; ++_i) \
;         __builtin_amdgcn_global_load_lds((const unsigned*)((const char*)(gbase) + (voff)[_i]), (PG8_LAS unsigned*)(lds + (bufoff) + ldsw + _i * 8192), 16, 0, 0); } while (0)
; #define PG8_LDA(dst, b, h) do { _Pragma("unroll") for (int m = 0; m < 4; ++m) _Pragma("unroll") for (int k = 0; k < 2; ++k) dst[m][k] = *(const PG8_LAS bf16x8*)(lds + PG8_SA(b, h) + aoff + m * 2048 + k * 1024); } while (0)
; #define PG8_LDB(dst, b, h) do { _Pragma("unroll") for (int n = 0; n < 2; ++n) _Pragma("unroll") for (int k = 0; k < 2; ++k) dst[n][k] = *(const PG8_LAS bf16x8*)(lds + PG8_SB(b, h) + boff + n * 2048 + k * 1024); } while (0)
; #define PG8_MMA(ai, bj, At, Bt) do { __builtin_amdgcn_s_setprio(1); _Pragma("unroll") for (int m = 0; m < 4; ++m) _Pragma("unroll") for (int n = 0; n < 2; ++n) _Pragma("unroll") for (int k = 0; k < 2; ++k) \
;         acc[ai][bj][m][n] = __builtin_amdgcn_mfma_f32_16x16x32_bf16(Bt[n][k], At[m][k], acc[ai][bj][m][n], 0, 0, 0); __builtin_amdgcn_s_setprio(0); } while (0)
; #define PG8_WAIT_V(n) asm volatile("s_waitcnt vmcnt(" #n ")" ::: "memory")
; #define PG8_WAIT_L(n) asm volatile("s_waitcnt lgkmcnt(" #n ")" ::: "memory")
; #define PG8_BAR __builtin_amdgcn_s_barrier()
; #define PG8_SCHED __builtin_amdgcn_sched_barrier(0)
; template <class Epi, class Sched, bool ALIGN_EPI = false, bool SP2 = false>
; __device__ __forceinline__ void gemm_phase(PG8_LAS unsigned char* lds, const Gemm g, const Sched& S, const Epi& E) {
;     ...
;             PG8_LDB(B0, 1, 0); PG8_LDB(B1, 1, 1); PG8_SCHED; PG8_LDA(At, 1, 0); PG8_STAGE(PG8_SA(0, 1), a2 + hstep, voffA);
;             PG8_WAIT_V(8); PG8_WAIT_L(0); PG8_BAR; PG8_MMA(0, 0, At, B0); PG8_MMA(0, 1, At, B1); PG8_BAR; PG8_SCHED;
;             PG8_LDA(At, 1, 1); PG8_STAGE(PG8_SB(1, 0), b3, voffB); PG8_STAGE(PG8_SB(1, 1), b3 + hstep, voffB); PG8_STAGE(PG8_SA(1, 0), a3, voffA);
;             PG8_WAIT_V(8); PG8_WAIT_L(0); PG8_BAR; PG8_MMA(1, 0, At, B0); PG8_MMA(1, 1, At, B1); PG8_BAR; PG8_SCHED;
	ds_read_b128 v[140:143], v254 offset:32768
	ds_read_b128 v[166:169], v254 offset:33792
	ds_read_b128 v[170:173], v254 offset:34816
	ds_read_b128 v[174:177], v254 offset:35840
	ds_read_b128 v[178:181], v254 offset:49152
	ds_read_b128 v[182:185], v254 offset:50176
	ds_read_b128 v[186:189], v254 offset:51200
	ds_read_b128 v[210:213], v254 offset:52224
	s_add_u32 s4, s4, 0x40000
	s_addc_u32 s5, s5, 0
	s_mov_b32 m0, s38
	ds_read_b128 v[214:217], v163 offset:32768
	ds_read_b128 v[218:221], v163 offset:33792
	ds_read_b128 v[222:225], v163 offset:34816
	ds_read_b128 v[226:229], v163 offset:35840
	ds_read_b128 v[230:233], v163 offset:36864
	ds_read_b128 v[234:237], v163 offset:37888
	ds_read_b128 v[238:241], v163 offset:38912
	ds_read_b128 v[242:245], v163 offset:39936
	global_load_lds_dwordx4 v134, s[4:5]
	s_mov_b32 m0, s39
	s_nop 0
	global_load_lds_dwordx4 v130, s[4:5]
	s_waitcnt vmcnt(8)
	s_waitcnt lgkmcnt(0)
	s_barrier
	s_setprio 1
	v_mfma_f32_16x16x32_bf16 v[124:127], v[140:143], v[214:217], v[124:127]
	v_mfma_f32_16x16x32_bf16 v[104:107], v[170:173], v[222:225], v[104:107]
	v_mfma_f32_16x16x32_bf16 v[92:95], v[140:143], v[230:233], v[92:95]
	v_mfma_f32_16x16x32_bf16 v[72:75], v[170:173], v[238:241], v[72:75]
	v_mfma_f32_16x16x32_bf16 v[120:123], v[170:173], v[214:217], v[120:123]
	v_mfma_f32_16x16x32_bf16 v[108:111], v[140:143], v[222:225], v[108:111]
	v_mfma_f32_16x16x32_bf16 v[88:91], v[170:173], v[230:233], v[88:91]
	v_mfma_f32_16x16x32_bf16 v[76:79], v[140:143], v[238:241], v[76:79]
	v_mfma_f32_16x16x32_bf16 v[124:127], v[166:169], v[218:221], v[124:127]
	v_mfma_f32_16x16x32_bf16 v[104:107], v[174:177], v[226:229], v[104:107]
	v_mfma_f32_16x16x32_bf16 v[92:95], v[166:169], v[234:237], v[92:95]
	v_mfma_f32_16x16x32_bf16 v[72:75], v[174:177], v[242:245], v[72:75]
	v_mfma_f32_16x16x32_bf16 v[120:123], v[174:177], v[218:221], v[120:123]
	v_mfma_f32_16x16x32_bf16 v[108:111], v[166:169], v[226:229], v[108:111]
	v_mfma_f32_16x16x32_bf16 v[88:91], v[174:177], v[234:237], v[88:91]
	v_mfma_f32_16x16x32_bf16 v[76:79], v[166:169], v[242:245], v[76:79]
	v_mfma_f32_16x16x32_bf16 v[116:119], v[178:181], v[214:217], v[116:119]
	v_mfma_f32_16x16x32_bf16 v[96:99], v[186:189], v[222:225], v[96:99]
	v_mfma_f32_16x16x32_bf16 v[84:87], v[178:181], v[230:233], v[84:87]
	v_mfma_f32_16x16x32_bf16 v[64:67], v[186:189], v[238:241], v[64:67]
	v_mfma_f32_16x16x32_bf16 v[112:115], v[186:189], v[214:217], v[112:115]
	v_mfma_f32_16x16x32_bf16 v[100:103], v[178:181], v[222:225], v[100:103]
	v_mfma_f32_16x16x32_bf16 v[80:83], v[186:189], v[230:233], v[80:83]
	v_mfma_f32_16x16x32_bf16 v[68:71], v[178:181], v[238:241], v[68:71]
	v_mfma_f32_16x16x32_bf16 v[116:119], v[182:185], v[218:221], v[116:119]
	v_mfma_f32_16x16x32_bf16 v[96:99], v[210:213], v[226:229], v[96:99]
	v_mfma_f32_16x16x32_bf16 v[84:87], v[182:185], v[234:237], v[84:87]
	v_mfma_f32_16x16x32_bf16 v[64:67], v[210:213], v[242:245], v[64:67]
	v_mfma_f32_16x16x32_bf16 v[112:115], v[210:213], v[218:221], v[112:115]
	v_mfma_f32_16x16x32_bf16 v[100:103], v[182:185], v[226:229], v[100:103]
	v_mfma_f32_16x16x32_bf16 v[80:83], v[210:213], v[234:237], v[80:83]
	v_mfma_f32_16x16x32_bf16 v[68:71], v[182:185], v[242:245], v[68:71]
	s_setprio 0
	s_barrier
	s_mov_b32 m0, s43
	s_add_u32 s2, s2, 0x40080
	s_addc_u32 s3, s3, 0
	ds_read_b128 v[214:217], v163 offset:49152
	ds_read_b128 v[218:221], v163 offset:50176
	ds_read_b128 v[222:225], v163 offset:51200
	ds_read_b128 v[226:229], v163 offset:52224
	ds_read_b128 v[230:233], v163 offset:53248
	ds_read_b128 v[234:237], v163 offset:54272
	ds_read_b128 v[238:241], v163 offset:55296
	ds_read_b128 v[242:245], v163 offset:56320
	s_add_u32 s98, s2, 0xfffc0000
	s_addc_u32 s99, s3, -1
	global_load_lds_dwordx4 v132, s[98:99]
	s_mov_b32 m0, s44
	s_nop 0
	global_load_lds_dwordx4 v128, s[98:99]
	s_mov_b32 m0, s48
	s_nop 0
	global_load_lds_dwordx4 v132, s[2:3]
	s_mov_b32 m0, s49
	s_nop 0
	global_load_lds_dwordx4 v128, s[2:3]
	s_mov_b32 m0, s45
	s_nop 0
	s_add_u32 s100, s4, 0xfffc0080
	s_addc_u32 s101, s5, -1
	global_load_lds_dwordx4 v134, s[100:101]
	s_mov_b32 m0, s47
	s_nop 0
	global_load_lds_dwordx4 v130, s[100:101]
	s_waitcnt vmcnt(8)
	s_waitcnt lgkmcnt(0)
	s_barrier
	s_setprio 1
	v_mfma_f32_16x16x32_bf16 v[60:63], v[140:143], v[214:217], v[60:63]
	v_mfma_f32_16x16x32_bf16 v[40:43], v[170:173], v[222:225], v[40:43]
	v_mfma_f32_16x16x32_bf16 v[28:31], v[140:143], v[230:233], v[28:31]
	v_mfma_f32_16x16x32_bf16 v[8:11], v[170:173], v[238:241], v[8:11]
	v_mfma_f32_16x16x32_bf16 v[56:59], v[170:173], v[214:217], v[56:59]
	v_mfma_f32_16x16x32_bf16 v[44:47], v[140:143], v[222:225], v[44:47]
	v_mfma_f32_16x16x32_bf16 v[24:27], v[170:173], v[230:233], v[24:27]
	v_mfma_f32_16x16x32_bf16 v[12:15], v[140:143], v[238:241], v[12:15]
	v_mfma_f32_16x16x32_bf16 v[60:63], v[166:169], v[218:221], v[60:63]
	v_mfma_f32_16x16x32_bf16 v[40:43], v[174:177], v[226:229], v[40:43]
	v_mfma_f32_16x16x32_bf16 v[28:31], v[166:169], v[234:237], v[28:31]
	v_mfma_f32_16x16x32_bf16 v[8:11], v[174:177], v[242:245], v[8:11]
	v_mfma_f32_16x16x32_bf16 v[56:59], v[174:177], v[218:221], v[56:59]
	v_mfma_f32_16x16x32_bf16 v[44:47], v[166:169], v[226:229], v[44:47]
	v_mfma_f32_16x16x32_bf16 v[24:27], v[174:177], v[234:237], v[24:27]
	v_mfma_f32_16x16x32_bf16 v[12:15], v[166:169], v[242:245], v[12:15]
	v_mfma_f32_16x16x32_bf16 v[52:55], v[178:181], v[214:217], v[52:55]
	v_mfma_f32_16x16x32_bf16 v[32:35], v[186:189], v[222:225], v[32:35]
	v_mfma_f32_16x16x32_bf16 v[20:23], v[178:181], v[230:233], v[20:23]
	v_mfma_f32_16x16x32_bf16 v[0:3], v[186:189], v[238:241], v[0:3]
	v_mfma_f32_16x16x32_bf16 v[48:51], v[186:189], v[214:217], v[48:51]
	v_mfma_f32_16x16x32_bf16 v[36:39], v[178:181], v[222:225], v[36:39]
	v_mfma_f32_16x16x32_bf16 v[16:19], v[186:189], v[230:233], v[16:19]
	v_mfma_f32_16x16x32_bf16 v[4:7], v[178:181], v[238:241], v[4:7]
	v_mfma_f32_16x16x32_bf16 v[52:55], v[182:185], v[218:221], v[52:55]
	v_mfma_f32_16x16x32_bf16 v[32:35], v[210:213], v[226:229], v[32:35]
	v_mfma_f32_16x16x32_bf16 v[20:23], v[182:185], v[234:237], v[20:23]
	v_mfma_f32_16x16x32_bf16 v[0:3], v[210:213], v[242:245], v[0:3]
	v_mfma_f32_16x16x32_bf16 v[48:51], v[210:213], v[218:221], v[48:51]
	v_mfma_f32_16x16x32_bf16 v[36:39], v[182:185], v[226:229], v[36:39]
	v_mfma_f32_16x16x32_bf16 v[16:19], v[210:213], v[234:237], v[16:19]
	v_mfma_f32_16x16x32_bf16 v[4:7], v[182:185], v[242:245], v[4:7]
	s_setprio 0
	s_barrier
	s_add_i32 s55, s55, 2
	s_add_u32 s0, s0, 0x100
	s_addc_u32 s1, s1, 0
	s_add_u32 s53, s53, 0x100
	s_addc_u32 s54, s54, 0
	s_cmp_gt_u32 s55, 13
	s_cbranch_scc0 .LBB0_1042
	s_and_b64 vcc, exec, s[18:19]
	s_cbranch_vccz .LBB0_1045
	s_barrier
